# GEMM compute segments: the two MFMAs of each accumulator (k-halves) issued back to back instead of 8 apart (same instructions, reordered)
# speedup vs baseline: 1.0005x; 1.0005x over previous
; #define PG8_STAGE(bufoff, gbase, voff) do { _Pragma("unroll") for (int _i = 0; _i < 2; ++_i) \
;         __builtin_amdgcn_global_load_lds((const unsigned*)((const char*)(gbase) + (voff)[_i]), (LAS unsigned*)(lds + (bufoff) + ldsw + _i * 8192), 16, 0, 0); } while (0)
; #define PG8_LDA(dst, b, h) do { _Pragma("unroll") for (int m = 0; m < 4; ++m) _Pragma("unroll") for (int k = 0; k < 2; ++k) dst[m][k] = *(const LAS bf16x8*)(lds + PG8_SA(b, h) + aoff + m * 2048 + k * 1024); } while (0)
; #define PG8_LDB(dst, b, h) do { _Pragma("unroll") for (int n = 0; n < 2; ++n) _Pragma("unroll") for (int k = 0; k < 2; ++k) dst[n][k] = *(const LAS bf16x8*)(lds + PG8_SB(b, h) + boff + n * 2048 + k * 1024); } while (0)
; #define PG8_MMA(ai, bj, At, Bt) do { __builtin_amdgcn_s_setprio(1); _Pragma("unroll") for (int m = 0; m < 4; ++m) _Pragma("unroll") for (int n = 0; n < 2; ++n) _Pragma("unroll") for (int k = 0; k < 2; ++k) \
;         acc[ai][bj][m][n] = __builtin_amdgcn_mfma_f32_16x16x32_bf16(Bt[n][k], At[m][k], acc[ai][bj][m][n], 0, 0, 0); __builtin_amdgcn_s_setprio(0); } while (0)
; #define PG8_WAIT_V(n) asm volatile("s_waitcnt vmcnt(" #n ")" ::: "memory")
; #define PG8_WAIT_L(n) asm volatile("s_waitcnt lgkmcnt(" #n ")" ::: "memory")
; #define PG8_BAR __builtin_amdgcn_s_barrier()
; #define PG8_SCHED __builtin_amdgcn_sched_barrier(0)
; template <class Epi, bool ALIGN_EPI>
; __device__ __forceinline__ void gemm_phase(LAS unsigned char* lds, const Gemm g, const StaticOrder& S, const Epi& E) {
;     ...
;         for (int t = 0; t < nt; t += 2) {
;             const bool last = (t == nt - 2);
;             const char* a1 = cA + (size_t)(t + 1) * kstep;
;             const char* a2 = last ? nA : cA + (size_t)(t + 2) * kstep; const char* b2 = last ? nB : cB + (size_t)(t + 2) * kstep;
;             const char* a3 = a2 + kstep; const char* b3 = b2 + kstep;
;             PG8_LDB(B0, 0, 0); PG8_LDB(B1, 0, 1); PG8_SCHED; PG8_LDA(At, 0, 0); PG8_STAGE(PG8_SA(1, 1), a1 + hstepA, voffA);
;             PG8_WAIT_V(8); PG8_WAIT_L(0); PG8_BAR; PG8_MMA(0, 0, At, B0); PG8_MMA(0, 1, At, B1); PG8_BAR; PG8_SCHED;
;             PG8_LDA(At, 0, 1); PG8_STAGE(PG8_SB(0, 0), b2, voffB); PG8_STAGE(PG8_SB(0, 1), b2 + hstepB, voffB); PG8_STAGE(PG8_SA(0, 0), a2, voffA);
;             PG8_WAIT_V(8); PG8_WAIT_L(0); PG8_BAR; PG8_MMA(1, 0, At, B0); PG8_MMA(1, 1, At, B1); PG8_BAR; PG8_SCHED;
.LBB0_102:
	s_add_u32 s6, s2, 0xfffc0080
	s_addc_u32 s7, s3, -1
	s_add_i32 s49, 0, 0x10000
	s_cmp_eq_u32 s37, 12
	s_cselect_b32 s9, s4, s7
	s_cselect_b32 s8, s10, s6
	v_add_u32_e32 v152, s49, v148
	s_cselect_b32 s7, s11, s36
	s_cselect_b32 s6, s13, s27
	s_add_i32 s52, 0, 0x14000
	ds_read_b128 v[140:143], v152
	ds_read_b128 v[144:147], v152 offset:1024
	ds_read_b128 v[156:159], v152 offset:2048
	ds_read_b128 v[160:163], v152 offset:3072
	v_add_u32_e32 v152, s52, v148
	ds_read_b128 v[170:173], v152
	ds_read_b128 v[180:183], v152 offset:1024
	ds_read_b128 v[184:187], v152 offset:2048
	ds_read_b128 v[188:191], v152 offset:3072
	v_lshl_add_u64 v[152:153], s[2:3], 0, v[136:137]
	s_add_i32 m0, s41, 0xc000
	ds_read_b128 v[192:195], v150
	ds_read_b128 v[196:199], v150 offset:1024
	ds_read_b128 v[200:203], v150 offset:2048
	ds_read_b128 v[204:207], v150 offset:3072
	ds_read_b128 v[208:211], v150 offset:4096
	ds_read_b128 v[212:215], v150 offset:5120
	ds_read_b128 v[216:219], v150 offset:6144
	ds_read_b128 v[220:223], v150 offset:7168
	global_load_lds_dwordx4 v[152:153], off
	v_lshl_add_u64 v[152:153], s[2:3], 0, v[138:139]
	s_add_i32 m0, s41, 0xe000
	s_nop 0
	global_load_lds_dwordx4 v[152:153], off
	s_waitcnt vmcnt(8)
	s_waitcnt lgkmcnt(0)
	s_barrier
	s_waitcnt lgkmcnt(0)
	v_mfma_f32_16x16x32_bf16 v[122:125], v[140:143], v[192:195], v[122:125]
	v_mfma_f32_16x16x32_bf16 v[122:125], v[144:147], v[196:199], v[122:125]
	v_mfma_f32_16x16x32_bf16 v[126:129], v[156:159], v[192:195], v[126:129]
	v_mfma_f32_16x16x32_bf16 v[126:129], v[160:163], v[196:199], v[126:129]
	v_mfma_f32_16x16x32_bf16 v[110:113], v[140:143], v[200:203], v[110:113]
	v_mfma_f32_16x16x32_bf16 v[110:113], v[144:147], v[204:207], v[110:113]
	v_mfma_f32_16x16x32_bf16 v[106:109], v[156:159], v[200:203], v[106:109]
	v_mfma_f32_16x16x32_bf16 v[106:109], v[160:163], v[204:207], v[106:109]
	v_mfma_f32_16x16x32_bf16 v[94:97], v[140:143], v[208:211], v[94:97]
	v_mfma_f32_16x16x32_bf16 v[94:97], v[144:147], v[212:215], v[94:97]
	v_mfma_f32_16x16x32_bf16 v[90:93], v[156:159], v[208:211], v[90:93]
	v_mfma_f32_16x16x32_bf16 v[90:93], v[160:163], v[212:215], v[90:93]
	v_mfma_f32_16x16x32_bf16 v[78:81], v[140:143], v[216:219], v[78:81]
	v_mfma_f32_16x16x32_bf16 v[78:81], v[144:147], v[220:223], v[78:81]
	v_mfma_f32_16x16x32_bf16 v[74:77], v[156:159], v[216:219], v[74:77]
	v_mfma_f32_16x16x32_bf16 v[74:77], v[160:163], v[220:223], v[74:77]
	v_mfma_f32_16x16x32_bf16 v[118:121], v[170:173], v[192:195], v[118:121]
	v_mfma_f32_16x16x32_bf16 v[118:121], v[180:183], v[196:199], v[118:121]
	v_mfma_f32_16x16x32_bf16 v[114:117], v[184:187], v[192:195], v[114:117]
	v_mfma_f32_16x16x32_bf16 v[114:117], v[188:191], v[196:199], v[114:117]
	v_mfma_f32_16x16x32_bf16 v[102:105], v[170:173], v[200:203], v[102:105]
	v_mfma_f32_16x16x32_bf16 v[102:105], v[180:183], v[204:207], v[102:105]
	v_mfma_f32_16x16x32_bf16 v[98:101], v[184:187], v[200:203], v[98:101]
	v_mfma_f32_16x16x32_bf16 v[98:101], v[188:191], v[204:207], v[98:101]
	v_mfma_f32_16x16x32_bf16 v[86:89], v[170:173], v[208:211], v[86:89]
	v_mfma_f32_16x16x32_bf16 v[86:89], v[180:183], v[212:215], v[86:89]
	v_mfma_f32_16x16x32_bf16 v[82:85], v[184:187], v[208:211], v[82:85]
	v_mfma_f32_16x16x32_bf16 v[82:85], v[188:191], v[212:215], v[82:85]
	v_mfma_f32_16x16x32_bf16 v[70:73], v[170:173], v[216:219], v[70:73]
	v_mfma_f32_16x16x32_bf16 v[70:73], v[180:183], v[220:223], v[70:73]
	v_mfma_f32_16x16x32_bf16 v[66:69], v[184:187], v[216:219], v[66:69]
	v_mfma_f32_16x16x32_bf16 v[66:69], v[188:191], v[220:223], v[66:69]
	s_barrier
	s_add_i32 s49, s49, s40
	v_lshl_add_u64 v[152:153], s[6:7], 0, v[0:1]
	s_mov_b32 m0, s49
	ds_read_b128 v[192:195], v150 offset:16384
	ds_read_b128 v[196:199], v150 offset:17408
	ds_read_b128 v[200:203], v150 offset:18432
	ds_read_b128 v[204:207], v150 offset:19456
	ds_read_b128 v[208:211], v150 offset:20480
	ds_read_b128 v[212:215], v150 offset:21504
	ds_read_b128 v[216:219], v150 offset:22528
	ds_read_b128 v[220:223], v150 offset:23552
	global_load_lds_dwordx4 v[152:153], off
	s_add_i32 m0, s49, 0x2000
	s_add_u32 s50, s6, 0x40000
	v_lshl_add_u64 v[164:165], s[6:7], 0, v[134:135]
	s_addc_u32 s51, s7, 0
	s_add_i32 s49, s52, s40
	global_load_lds_dwordx4 v[164:165], off
	v_lshl_add_u64 v[168:169], s[50:51], 0, v[0:1]
	s_mov_b32 m0, s49
	v_lshl_add_u64 v[174:175], s[8:9], 0, v[132:133]
	global_load_lds_dwordx4 v[168:169], off
	v_lshl_add_u64 v[168:169], s[50:51], 0, v[134:135]
	s_add_i32 m0, s49, 0x2000
	s_nop 0
	global_load_lds_dwordx4 v[168:169], off
	v_lshl_add_u64 v[168:169], s[8:9], 0, v[130:131]
	s_mov_b32 m0, s41
	s_nop 0
	global_load_lds_dwordx4 v[168:169], off
	s_mov_b32 m0, s42
	s_nop 0
	global_load_lds_dwordx4 v[174:175], off
	s_waitcnt vmcnt(8)
	s_waitcnt lgkmcnt(0)
	s_barrier
; #define PG8_STAGE(bufoff, gbase, voff) do { _Pragma("unroll") for (int _i = 0; _i < 2; ++_i) \
;         __builtin_amdgcn_global_load_lds((const unsigned*)((const char*)(gbase) + (voff)[_i]), (LAS unsigned*)(lds + (bufoff) + ldsw + _i * 8192), 16, 0, 0); } while (0)
; #define PG8_LDA(dst, b, h) do { _Pragma("unroll") for (int m = 0; m < 4; ++m) _Pragma("unroll") for (int k = 0; k < 2; ++k) dst[m][k] = *(const LAS bf16x8*)(lds + PG8_SA(b, h) + aoff + m * 2048 + k * 1024); } while (0)
; #define PG8_LDB(dst, b, h) do { _Pragma("unroll") for (int n = 0; n < 2; ++n) _Pragma("unroll") for (int k = 0; k < 2; ++k) dst[n][k] = *(const LAS bf16x8*)(lds + PG8_SB(b, h) + boff + n * 2048 + k * 1024); } while (0)
; #define PG8_MMA(ai, bj, At, Bt) do { __builtin_amdgcn_s_setprio(1); _Pragma("unroll") for (int m = 0; m < 4; ++m) _Pragma("unroll") for (int n = 0; n < 2; ++n) _Pragma("unroll") for (int k = 0; k < 2; ++k) \
;         acc[ai][bj][m][n] = __builtin_amdgcn_mfma_f32_16x16x32_bf16(Bt[n][k], At[m][k], acc[ai][bj][m][n], 0, 0, 0); __builtin_amdgcn_s_setprio(0); } while (0)
; #define PG8_WAIT_V(n) asm volatile("s_waitcnt vmcnt(" #n ")" ::: "memory")
; #define PG8_WAIT_L(n) asm volatile("s_waitcnt lgkmcnt(" #n ")" ::: "memory")
; #define PG8_BAR __builtin_amdgcn_s_barrier()
; #define PG8_SCHED __builtin_amdgcn_sched_barrier(0)
; template <class Epi, bool ALIGN_EPI>
; __device__ __forceinline__ void gemm_phase(LAS unsigned char* lds, const Gemm g, const StaticOrder& S, const Epi& E) {
;     ...
;             PG8_WAIT_V(8); PG8_WAIT_L(0); PG8_BAR; PG8_MMA(1, 0, At, B0); PG8_MMA(1, 1, At, B1); PG8_BAR; PG8_SCHED;
;             PG8_LDB(B0, 1, 0); PG8_LDB(B1, 1, 1); PG8_SCHED; PG8_LDA(At, 1, 0); PG8_STAGE(PG8_SA(0, 1), a2 + hstepA, voffA);
;             PG8_WAIT_V(8); PG8_WAIT_L(0); PG8_BAR; PG8_MMA(0, 0, At, B0); PG8_MMA(0, 1, At, B1); PG8_BAR; PG8_SCHED;
	s_waitcnt lgkmcnt(0)
	v_mfma_f32_16x16x32_bf16 v[62:65], v[140:143], v[192:195], v[62:65]
	v_mfma_f32_16x16x32_bf16 v[62:65], v[144:147], v[196:199], v[62:65]
	v_mfma_f32_16x16x32_bf16 v[58:61], v[156:159], v[192:195], v[58:61]
	v_mfma_f32_16x16x32_bf16 v[58:61], v[160:163], v[196:199], v[58:61]
	v_mfma_f32_16x16x32_bf16 v[46:49], v[140:143], v[200:203], v[46:49]
	v_mfma_f32_16x16x32_bf16 v[46:49], v[144:147], v[204:207], v[46:49]
	v_mfma_f32_16x16x32_bf16 v[42:45], v[156:159], v[200:203], v[42:45]
	v_mfma_f32_16x16x32_bf16 v[42:45], v[160:163], v[204:207], v[42:45]
	v_mfma_f32_16x16x32_bf16 v[30:33], v[140:143], v[208:211], v[30:33]
	v_mfma_f32_16x16x32_bf16 v[30:33], v[144:147], v[212:215], v[30:33]
	v_mfma_f32_16x16x32_bf16 v[26:29], v[156:159], v[208:211], v[26:29]
	v_mfma_f32_16x16x32_bf16 v[26:29], v[160:163], v[212:215], v[26:29]
	v_mfma_f32_16x16x32_bf16 v[14:17], v[140:143], v[216:219], v[14:17]
	v_mfma_f32_16x16x32_bf16 v[14:17], v[144:147], v[220:223], v[14:17]
	v_mfma_f32_16x16x32_bf16 v[10:13], v[156:159], v[216:219], v[10:13]
	v_mfma_f32_16x16x32_bf16 v[10:13], v[160:163], v[220:223], v[10:13]
	v_mfma_f32_16x16x32_bf16 v[54:57], v[170:173], v[192:195], v[54:57]
	v_mfma_f32_16x16x32_bf16 v[54:57], v[180:183], v[196:199], v[54:57]
	v_mfma_f32_16x16x32_bf16 v[50:53], v[184:187], v[192:195], v[50:53]
	v_mfma_f32_16x16x32_bf16 v[50:53], v[188:191], v[196:199], v[50:53]
	v_mfma_f32_16x16x32_bf16 v[38:41], v[170:173], v[200:203], v[38:41]
	v_mfma_f32_16x16x32_bf16 v[38:41], v[180:183], v[204:207], v[38:41]
	v_mfma_f32_16x16x32_bf16 v[34:37], v[184:187], v[200:203], v[34:37]
	v_mfma_f32_16x16x32_bf16 v[34:37], v[188:191], v[204:207], v[34:37]
	v_mfma_f32_16x16x32_bf16 v[22:25], v[170:173], v[208:211], v[22:25]
	v_mfma_f32_16x16x32_bf16 v[22:25], v[180:183], v[212:215], v[22:25]
	v_mfma_f32_16x16x32_bf16 v[18:21], v[184:187], v[208:211], v[18:21]
	v_mfma_f32_16x16x32_bf16 v[18:21], v[188:191], v[212:215], v[18:21]
	v_mfma_f32_16x16x32_bf16 v[6:9], v[170:173], v[216:219], v[6:9]
	v_mfma_f32_16x16x32_bf16 v[6:9], v[180:183], v[220:223], v[6:9]
	v_mfma_f32_16x16x32_bf16 v[2:5], v[184:187], v[216:219], v[2:5]
	v_mfma_f32_16x16x32_bf16 v[2:5], v[188:191], v[220:223], v[2:5]
	s_barrier
	s_add_i32 s49, 0, 0x18000
	s_add_i32 s50, 0, 0x1c000
	v_add_u32_e32 v160, s49, v148
	v_add_u32_e32 v188, s50, v148
	ds_read_b128 v[140:143], v160
	ds_read_b128 v[144:147], v160 offset:1024
	ds_read_b128 v[156:159], v160 offset:2048
	ds_read_b128 v[160:163], v160 offset:3072
	ds_read_b128 v[170:173], v188
	ds_read_b128 v[180:183], v188 offset:1024
	ds_read_b128 v[184:187], v188 offset:2048
	ds_read_b128 v[188:191], v188 offset:3072
	s_add_u32 s8, s8, 0x40000
	s_addc_u32 s9, s9, 0
	s_mov_b32 m0, s43
	v_lshl_add_u64 v[224:225], s[8:9], 0, v[130:131]
	ds_read_b128 v[192:195], v150 offset:32768
	ds_read_b128 v[196:199], v150 offset:33792
	ds_read_b128 v[200:203], v150 offset:34816
	ds_read_b128 v[204:207], v150 offset:35840
	ds_read_b128 v[208:211], v150 offset:36864
	ds_read_b128 v[212:215], v150 offset:37888
	ds_read_b128 v[216:219], v150 offset:38912
	ds_read_b128 v[220:223], v150 offset:39936
	global_load_lds_dwordx4 v[224:225], off
	v_lshl_add_u64 v[224:225], s[8:9], 0, v[132:133]
	s_mov_b32 m0, s44
	s_nop 0
	global_load_lds_dwordx4 v[224:225], off
	s_waitcnt vmcnt(8)
	s_waitcnt lgkmcnt(0)
	s_barrier
	s_waitcnt lgkmcnt(0)
	v_mfma_f32_16x16x32_bf16 v[122:125], v[140:143], v[192:195], v[122:125]
	v_mfma_f32_16x16x32_bf16 v[122:125], v[144:147], v[196:199], v[122:125]
	v_mfma_f32_16x16x32_bf16 v[126:129], v[156:159], v[192:195], v[126:129]
	v_mfma_f32_16x16x32_bf16 v[126:129], v[160:163], v[196:199], v[126:129]
	v_mfma_f32_16x16x32_bf16 v[110:113], v[140:143], v[200:203], v[110:113]
	v_mfma_f32_16x16x32_bf16 v[110:113], v[144:147], v[204:207], v[110:113]
	v_mfma_f32_16x16x32_bf16 v[106:109], v[156:159], v[200:203], v[106:109]
	v_mfma_f32_16x16x32_bf16 v[106:109], v[160:163], v[204:207], v[106:109]
	v_mfma_f32_16x16x32_bf16 v[94:97], v[140:143], v[208:211], v[94:97]
	v_mfma_f32_16x16x32_bf16 v[94:97], v[144:147], v[212:215], v[94:97]
	v_mfma_f32_16x16x32_bf16 v[90:93], v[156:159], v[208:211], v[90:93]
	v_mfma_f32_16x16x32_bf16 v[90:93], v[160:163], v[212:215], v[90:93]
	v_mfma_f32_16x16x32_bf16 v[78:81], v[140:143], v[216:219], v[78:81]
	v_mfma_f32_16x16x32_bf16 v[78:81], v[144:147], v[220:223], v[78:81]
	v_mfma_f32_16x16x32_bf16 v[74:77], v[156:159], v[216:219], v[74:77]
	v_mfma_f32_16x16x32_bf16 v[74:77], v[160:163], v[220:223], v[74:77]
	v_mfma_f32_16x16x32_bf16 v[118:121], v[170:173], v[192:195], v[118:121]
	v_mfma_f32_16x16x32_bf16 v[118:121], v[180:183], v[196:199], v[118:121]
	v_mfma_f32_16x16x32_bf16 v[114:117], v[184:187], v[192:195], v[114:117]
	v_mfma_f32_16x16x32_bf16 v[114:117], v[188:191], v[196:199], v[114:117]
	v_mfma_f32_16x16x32_bf16 v[102:105], v[170:173], v[200:203], v[102:105]
	v_mfma_f32_16x16x32_bf16 v[102:105], v[180:183], v[204:207], v[102:105]
	v_mfma_f32_16x16x32_bf16 v[98:101], v[184:187], v[200:203], v[98:101]
	v_mfma_f32_16x16x32_bf16 v[98:101], v[188:191], v[204:207], v[98:101]
	v_mfma_f32_16x16x32_bf16 v[86:89], v[170:173], v[208:211], v[86:89]
	v_mfma_f32_16x16x32_bf16 v[86:89], v[180:183], v[212:215], v[86:89]
	v_mfma_f32_16x16x32_bf16 v[82:85], v[184:187], v[208:211], v[82:85]
	v_mfma_f32_16x16x32_bf16 v[82:85], v[188:191], v[212:215], v[82:85]
	v_mfma_f32_16x16x32_bf16 v[70:73], v[170:173], v[216:219], v[70:73]
	v_mfma_f32_16x16x32_bf16 v[70:73], v[180:183], v[220:223], v[70:73]
	v_mfma_f32_16x16x32_bf16 v[66:69], v[184:187], v[216:219], v[66:69]
	v_mfma_f32_16x16x32_bf16 v[66:69], v[188:191], v[220:223], v[66:69]
	s_barrier
; #define PG8_STAGE(bufoff, gbase, voff) do { _Pragma("unroll") for (int _i = 0; _i < 2; ++_i) \
;         __builtin_amdgcn_global_load_lds((const unsigned*)((const char*)(gbase) + (voff)[_i]), (LAS unsigned*)(lds + (bufoff) + ldsw + _i * 8192), 16, 0, 0); } while (0)
; #define PG8_LDA(dst, b, h) do { _Pragma("unroll") for (int m = 0; m < 4; ++m) _Pragma("unroll") for (int k = 0; k < 2; ++k) dst[m][k] = *(const LAS bf16x8*)(lds + PG8_SA(b, h) + aoff + m * 2048 + k * 1024); } while (0)
; #define PG8_MMA(ai, bj, At, Bt) do { __builtin_amdgcn_s_setprio(1); _Pragma("unroll") for (int m = 0; m < 4; ++m) _Pragma("unroll") for (int n = 0; n < 2; ++n) _Pragma("unroll") for (int k = 0; k < 2; ++k) \
;         acc[ai][bj][m][n] = __builtin_amdgcn_mfma_f32_16x16x32_bf16(Bt[n][k], At[m][k], acc[ai][bj][m][n], 0, 0, 0); __builtin_amdgcn_s_setprio(0); } while (0)
; #define PG8_WAIT_V(n) asm volatile("s_waitcnt vmcnt(" #n ")" ::: "memory")
; #define PG8_WAIT_L(n) asm volatile("s_waitcnt lgkmcnt(" #n ")" ::: "memory")
; #define PG8_BAR __builtin_amdgcn_s_barrier()
; #define PG8_SCHED __builtin_amdgcn_sched_barrier(0)
; template <class Epi, bool ALIGN_EPI>
; __device__ __forceinline__ void gemm_phase(LAS unsigned char* lds, const Gemm g, const StaticOrder& S, const Epi& E) {
;     ...
;             PG8_LDA(At, 1, 1); PG8_STAGE(PG8_SB(1, 0), b3, voffB); PG8_STAGE(PG8_SB(1, 1), b3 + hstepB, voffB); PG8_STAGE(PG8_SA(1, 0), a3, voffA);
;             PG8_WAIT_V(8); PG8_WAIT_L(0); PG8_BAR; PG8_MMA(1, 0, At, B0); PG8_MMA(1, 1, At, B1); PG8_BAR; PG8_SCHED;
	s_add_i32 s8, s49, s40
	v_lshl_add_u64 v[152:153], v[152:153], 0, s[94:95]
	s_mov_b32 m0, s8
	ds_read_b128 v[192:195], v150 offset:49152
	ds_read_b128 v[196:199], v150 offset:50176
	ds_read_b128 v[200:203], v150 offset:51200
	ds_read_b128 v[204:207], v150 offset:52224
	ds_read_b128 v[208:211], v150 offset:53248
	ds_read_b128 v[212:215], v150 offset:54272
	ds_read_b128 v[216:219], v150 offset:55296
	ds_read_b128 v[220:223], v150 offset:56320
	global_load_lds_dwordx4 v[152:153], off
	s_add_i32 m0, s8, 0x2000
	s_add_u32 s6, s6, 0x40080
	v_lshl_add_u64 v[152:153], v[164:165], 0, s[94:95]
	s_addc_u32 s7, s7, 0
	s_add_i32 s8, s50, s40
	global_load_lds_dwordx4 v[152:153], off
	v_lshl_add_u64 v[152:153], s[6:7], 0, v[0:1]
	s_mov_b32 m0, s8
	s_nop 0
	global_load_lds_dwordx4 v[152:153], off
	v_lshl_add_u64 v[152:153], s[6:7], 0, v[134:135]
	s_add_i32 m0, s8, 0x2000
	s_nop 0
	global_load_lds_dwordx4 v[152:153], off
	v_lshl_add_u64 v[152:153], v[168:169], 0, s[94:95]
	s_mov_b32 m0, s46
	s_nop 0
	global_load_lds_dwordx4 v[152:153], off
	v_lshl_add_u64 v[152:153], v[174:175], 0, s[94:95]
	s_mov_b32 m0, s47
	s_nop 0
	global_load_lds_dwordx4 v[152:153], off
	s_waitcnt vmcnt(8)
	s_waitcnt lgkmcnt(0)
	s_barrier
	s_waitcnt lgkmcnt(0)
	v_mfma_f32_16x16x32_bf16 v[62:65], v[140:143], v[192:195], v[62:65]
	v_mfma_f32_16x16x32_bf16 v[62:65], v[144:147], v[196:199], v[62:65]
	v_mfma_f32_16x16x32_bf16 v[58:61], v[156:159], v[192:195], v[58:61]
	v_mfma_f32_16x16x32_bf16 v[58:61], v[160:163], v[196:199], v[58:61]
	v_mfma_f32_16x16x32_bf16 v[46:49], v[140:143], v[200:203], v[46:49]
	v_mfma_f32_16x16x32_bf16 v[46:49], v[144:147], v[204:207], v[46:49]
	v_mfma_f32_16x16x32_bf16 v[42:45], v[156:159], v[200:203], v[42:45]
	v_mfma_f32_16x16x32_bf16 v[42:45], v[160:163], v[204:207], v[42:45]
	v_mfma_f32_16x16x32_bf16 v[30:33], v[140:143], v[208:211], v[30:33]
	v_mfma_f32_16x16x32_bf16 v[30:33], v[144:147], v[212:215], v[30:33]
	v_mfma_f32_16x16x32_bf16 v[26:29], v[156:159], v[208:211], v[26:29]
	v_mfma_f32_16x16x32_bf16 v[26:29], v[160:163], v[212:215], v[26:29]
	v_mfma_f32_16x16x32_bf16 v[14:17], v[140:143], v[216:219], v[14:17]
	v_mfma_f32_16x16x32_bf16 v[14:17], v[144:147], v[220:223], v[14:17]
	v_mfma_f32_16x16x32_bf16 v[10:13], v[156:159], v[216:219], v[10:13]
	v_mfma_f32_16x16x32_bf16 v[10:13], v[160:163], v[220:223], v[10:13]
	v_mfma_f32_16x16x32_bf16 v[54:57], v[170:173], v[192:195], v[54:57]
	v_mfma_f32_16x16x32_bf16 v[54:57], v[180:183], v[196:199], v[54:57]
	v_mfma_f32_16x16x32_bf16 v[50:53], v[184:187], v[192:195], v[50:53]
	v_mfma_f32_16x16x32_bf16 v[50:53], v[188:191], v[196:199], v[50:53]
	v_mfma_f32_16x16x32_bf16 v[38:41], v[170:173], v[200:203], v[38:41]
	v_mfma_f32_16x16x32_bf16 v[38:41], v[180:183], v[204:207], v[38:41]
	v_mfma_f32_16x16x32_bf16 v[34:37], v[184:187], v[200:203], v[34:37]
	v_mfma_f32_16x16x32_bf16 v[34:37], v[188:191], v[204:207], v[34:37]
	v_mfma_f32_16x16x32_bf16 v[22:25], v[170:173], v[208:211], v[22:25]
	v_mfma_f32_16x16x32_bf16 v[22:25], v[180:183], v[212:215], v[22:25]
	v_mfma_f32_16x16x32_bf16 v[18:21], v[184:187], v[208:211], v[18:21]
	v_mfma_f32_16x16x32_bf16 v[18:21], v[188:191], v[212:215], v[18:21]
	v_mfma_f32_16x16x32_bf16 v[6:9], v[170:173], v[216:219], v[6:9]
	v_mfma_f32_16x16x32_bf16 v[6:9], v[180:183], v[220:223], v[6:9]
	v_mfma_f32_16x16x32_bf16 v[2:5], v[184:187], v[216:219], v[2:5]
	v_mfma_f32_16x16x32_bf16 v[2:5], v[188:191], v[220:223], v[2:5]
	s_cmp_lg_u32 s37, 12
	s_cbranch_scc1 .Ltail_bar_10
	s_cmp_eq_u64 s[20:21], 0
	s_cbranch_scc1 .Ltail_skip_10

; #define PG8_STAGE(bufoff, gbase, voff) do { _Pragma("unroll") for (int _i = 0; _i < 2; ++_i) \
;         __builtin_amdgcn_global_load_lds((const unsigned*)((const char*)(gbase) + (voff)[_i]), (LAS unsigned*)(lds + (bufoff) + ldsw + _i * 8192), 16, 0, 0); } while (0)
; #define PG8_LDA(dst, b, h) do { _Pragma("unroll") for (int m = 0; m < 4; ++m) _Pragma("unroll") for (int k = 0; k < 2; ++k) dst[m][k] = *(const LAS bf16x8*)(lds + PG8_SA(b, h) + aoff + m * 2048 + k * 1024); } while (0)
; #define PG8_LDB(dst, b, h) do { _Pragma("unroll") for (int n = 0; n < 2; ++n) _Pragma("unroll") for (int k = 0; k < 2; ++k) dst[n][k] = *(const LAS bf16x8*)(lds + PG8_SB(b, h) + boff + n * 2048 + k * 1024); } while (0)
; #define PG8_MMA(ai, bj, At, Bt) do { __builtin_amdgcn_s_setprio(1); _Pragma("unroll") for (int m = 0; m < 4; ++m) _Pragma("unroll") for (int n = 0; n < 2; ++n) _Pragma("unroll") for (int k = 0; k < 2; ++k) \
;         acc[ai][bj][m][n] = __builtin_amdgcn_mfma_f32_16x16x32_bf16(Bt[n][k], At[m][k], acc[ai][bj][m][n], 0, 0, 0); __builtin_amdgcn_s_setprio(0); } while (0)
; #define PG8_WAIT_V(n) asm volatile("s_waitcnt vmcnt(" #n ")" ::: "memory")
; #define PG8_WAIT_L(n) asm volatile("s_waitcnt lgkmcnt(" #n ")" ::: "memory")
; #define PG8_BAR __builtin_amdgcn_s_barrier()
; #define PG8_SCHED __builtin_amdgcn_sched_barrier(0)
; template <class Epi, bool ALIGN_EPI>
; __device__ __forceinline__ void gemm_phase(LAS unsigned char* lds, const Gemm g, const StaticOrder& S, const Epi& E) {
;     ...
;         for (int t = 0; t < nt; t += 2) {
;             const bool last = (t == nt - 2);
;             const char* a1 = cA + (size_t)(t + 1) * kstep;
;             const char* a2 = last ? nA : cA + (size_t)(t + 2) * kstep; const char* b2 = last ? nB : cB + (size_t)(t + 2) * kstep;
;             const char* a3 = a2 + kstep; const char* b3 = b2 + kstep;
;             PG8_LDB(B0, 0, 0); PG8_LDB(B1, 0, 1); PG8_SCHED; PG8_LDA(At, 0, 0); PG8_STAGE(PG8_SA(1, 1), a1 + hstepA, voffA);
;             PG8_WAIT_V(8); PG8_WAIT_L(0); PG8_BAR; PG8_MMA(0, 0, At, B0); PG8_MMA(0, 1, At, B1); PG8_BAR; PG8_SCHED;
;             PG8_LDA(At, 0, 1); PG8_STAGE(PG8_SB(0, 0), b2, voffB); PG8_STAGE(PG8_SB(0, 1), b2 + hstepB, voffB); PG8_STAGE(PG8_SA(0, 0), a2, voffA);
.LBB0_216:
	s_add_u32 s12, s10, 0x100
	s_addc_u32 s13, s11, 0
	s_add_i32 s44, 0, 0x10000
	s_cmp_eq_u32 s43, 40
	s_cselect_b32 s25, s19, s13
	s_cselect_b32 s24, s18, s12
	v_add_u32_e32 v144, s44, v146
	s_cselect_b32 s23, s21, s42
	s_cselect_b32 s22, s20, s41
	s_add_i32 s45, 0, 0x14000
	ds_read_b128 v[140:143], v144
	ds_read_b128 v[148:151], v144 offset:1024
	ds_read_b128 v[156:159], v144 offset:2048
	ds_read_b128 v[180:183], v144 offset:3072
	v_add_u32_e32 v144, s45, v146
	ds_read_b128 v[184:187], v144
	ds_read_b128 v[188:191], v144 offset:1024
	ds_read_b128 v[192:195], v144 offset:2048
	ds_read_b128 v[196:199], v144 offset:3072
	v_lshl_add_u64 v[144:145], s[10:11], 0, v[136:137]
	s_add_i32 m0, s29, 0xc000
	ds_read_b128 v[200:203], v147
	ds_read_b128 v[204:207], v147 offset:1024
	ds_read_b128 v[208:211], v147 offset:2048
	ds_read_b128 v[212:215], v147 offset:3072
	ds_read_b128 v[216:219], v147 offset:4096
	ds_read_b128 v[220:223], v147 offset:5120
	ds_read_b128 v[224:227], v147 offset:6144
	ds_read_b128 v[228:231], v147 offset:7168
	global_load_lds_dwordx4 v[144:145], off
	v_lshl_add_u64 v[144:145], s[10:11], 0, v[138:139]
	s_add_i32 m0, s29, 0xe000
	s_nop 0
	global_load_lds_dwordx4 v[144:145], off
	s_waitcnt vmcnt(8)
	s_waitcnt lgkmcnt(0)
	s_barrier
	s_waitcnt lgkmcnt(0)
	v_mfma_f32_16x16x32_bf16 v[126:129], v[140:143], v[200:203], v[126:129]
	v_mfma_f32_16x16x32_bf16 v[126:129], v[148:151], v[204:207], v[126:129]
	v_mfma_f32_16x16x32_bf16 v[122:125], v[156:159], v[200:203], v[122:125]
	v_mfma_f32_16x16x32_bf16 v[122:125], v[180:183], v[204:207], v[122:125]
	v_mfma_f32_16x16x32_bf16 v[110:113], v[140:143], v[208:211], v[110:113]
	v_mfma_f32_16x16x32_bf16 v[110:113], v[148:151], v[212:215], v[110:113]
	v_mfma_f32_16x16x32_bf16 v[106:109], v[156:159], v[208:211], v[106:109]
	v_mfma_f32_16x16x32_bf16 v[106:109], v[180:183], v[212:215], v[106:109]
	v_mfma_f32_16x16x32_bf16 v[94:97], v[140:143], v[216:219], v[94:97]
	v_mfma_f32_16x16x32_bf16 v[94:97], v[148:151], v[220:223], v[94:97]
	v_mfma_f32_16x16x32_bf16 v[90:93], v[156:159], v[216:219], v[90:93]
	v_mfma_f32_16x16x32_bf16 v[90:93], v[180:183], v[220:223], v[90:93]
	v_mfma_f32_16x16x32_bf16 v[78:81], v[140:143], v[224:227], v[78:81]
	v_mfma_f32_16x16x32_bf16 v[78:81], v[148:151], v[228:231], v[78:81]
	v_mfma_f32_16x16x32_bf16 v[74:77], v[156:159], v[224:227], v[74:77]
	v_mfma_f32_16x16x32_bf16 v[74:77], v[180:183], v[228:231], v[74:77]
	v_mfma_f32_16x16x32_bf16 v[118:121], v[184:187], v[200:203], v[118:121]
	v_mfma_f32_16x16x32_bf16 v[118:121], v[188:191], v[204:207], v[118:121]
	v_mfma_f32_16x16x32_bf16 v[114:117], v[192:195], v[200:203], v[114:117]
	v_mfma_f32_16x16x32_bf16 v[114:117], v[196:199], v[204:207], v[114:117]
	v_mfma_f32_16x16x32_bf16 v[102:105], v[184:187], v[208:211], v[102:105]
	v_mfma_f32_16x16x32_bf16 v[102:105], v[188:191], v[212:215], v[102:105]
	v_mfma_f32_16x16x32_bf16 v[98:101], v[192:195], v[208:211], v[98:101]
	v_mfma_f32_16x16x32_bf16 v[98:101], v[196:199], v[212:215], v[98:101]
	v_mfma_f32_16x16x32_bf16 v[86:89], v[184:187], v[216:219], v[86:89]
	v_mfma_f32_16x16x32_bf16 v[86:89], v[188:191], v[220:223], v[86:89]
	v_mfma_f32_16x16x32_bf16 v[82:85], v[192:195], v[216:219], v[82:85]
	v_mfma_f32_16x16x32_bf16 v[82:85], v[196:199], v[220:223], v[82:85]
	v_mfma_f32_16x16x32_bf16 v[70:73], v[184:187], v[224:227], v[70:73]
	v_mfma_f32_16x16x32_bf16 v[70:73], v[188:191], v[228:231], v[70:73]
	v_mfma_f32_16x16x32_bf16 v[66:69], v[192:195], v[224:227], v[66:69]
	v_mfma_f32_16x16x32_bf16 v[66:69], v[196:199], v[228:231], v[66:69]
	s_barrier
	s_add_i32 s10, s44, s28
	v_lshl_add_u64 v[144:145], s[22:23], 0, v[0:1]
	s_mov_b32 m0, s10
	ds_read_b128 v[200:203], v147 offset:16384
	ds_read_b128 v[204:207], v147 offset:17408
	ds_read_b128 v[208:211], v147 offset:18432
	ds_read_b128 v[212:215], v147 offset:19456
	ds_read_b128 v[216:219], v147 offset:20480
	ds_read_b128 v[220:223], v147 offset:21504
	ds_read_b128 v[224:227], v147 offset:22528
	ds_read_b128 v[228:231], v147 offset:23552
	global_load_lds_dwordx4 v[144:145], off
	s_add_i32 m0, s10, 0x2000
	s_add_u32 s10, s22, 0xb0000
	v_lshl_add_u64 v[152:153], s[22:23], 0, v[134:135]
	s_addc_u32 s11, s23, 0
	s_add_i32 s44, s45, s28
	global_load_lds_dwordx4 v[152:153], off
	v_lshl_add_u64 v[160:161], s[10:11], 0, v[0:1]
	s_mov_b32 m0, s44
	v_lshl_add_u64 v[162:163], s[24:25], 0, v[132:133]
	global_load_lds_dwordx4 v[160:161], off
	v_lshl_add_u64 v[160:161], s[10:11], 0, v[134:135]
	s_add_i32 m0, s44, 0x2000
	s_nop 0
	global_load_lds_dwordx4 v[160:161], off
	v_lshl_add_u64 v[160:161], s[24:25], 0, v[130:131]
	s_mov_b32 m0, s29
	s_nop 0
	global_load_lds_dwordx4 v[160:161], off
	s_mov_b32 m0, s30
	s_nop 0
	global_load_lds_dwordx4 v[162:163], off
	s_waitcnt vmcnt(8)
	s_waitcnt lgkmcnt(0)
	s_barrier
; #define PG8_STAGE(bufoff, gbase, voff) do { _Pragma("unroll") for (int _i = 0; _i < 2; ++_i) \
;         __builtin_amdgcn_global_load_lds((const unsigned*)((const char*)(gbase) + (voff)[_i]), (LAS unsigned*)(lds + (bufoff) + ldsw + _i * 8192), 16, 0, 0); } while (0)
; #define PG8_LDA(dst, b, h) do { _Pragma("unroll") for (int m = 0; m < 4; ++m) _Pragma("unroll") for (int k = 0; k < 2; ++k) dst[m][k] = *(const LAS bf16x8*)(lds + PG8_SA(b, h) + aoff + m * 2048 + k * 1024); } while (0)
; #define PG8_LDB(dst, b, h) do { _Pragma("unroll") for (int n = 0; n < 2; ++n) _Pragma("unroll") for (int k = 0; k < 2; ++k) dst[n][k] = *(const LAS bf16x8*)(lds + PG8_SB(b, h) + boff + n * 2048 + k * 1024); } while (0)
; #define PG8_MMA(ai, bj, At, Bt) do { __builtin_amdgcn_s_setprio(1); _Pragma("unroll") for (int m = 0; m < 4; ++m) _Pragma("unroll") for (int n = 0; n < 2; ++n) _Pragma("unroll") for (int k = 0; k < 2; ++k) \
;         acc[ai][bj][m][n] = __builtin_amdgcn_mfma_f32_16x16x32_bf16(Bt[n][k], At[m][k], acc[ai][bj][m][n], 0, 0, 0); __builtin_amdgcn_s_setprio(0); } while (0)
; #define PG8_WAIT_V(n) asm volatile("s_waitcnt vmcnt(" #n ")" ::: "memory")
; #define PG8_WAIT_L(n) asm volatile("s_waitcnt lgkmcnt(" #n ")" ::: "memory")
; #define PG8_BAR __builtin_amdgcn_s_barrier()
; #define PG8_SCHED __builtin_amdgcn_sched_barrier(0)
; template <class Epi, bool ALIGN_EPI>
; __device__ __forceinline__ void gemm_phase(LAS unsigned char* lds, const Gemm g, const StaticOrder& S, const Epi& E) {
;     ...
;             PG8_WAIT_V(8); PG8_WAIT_L(0); PG8_BAR; PG8_MMA(1, 0, At, B0); PG8_MMA(1, 1, At, B1); PG8_BAR; PG8_SCHED;
;             PG8_LDB(B0, 1, 0); PG8_LDB(B1, 1, 1); PG8_SCHED; PG8_LDA(At, 1, 0); PG8_STAGE(PG8_SA(0, 1), a2 + hstepA, voffA);
;             PG8_WAIT_V(8); PG8_WAIT_L(0); PG8_BAR; PG8_MMA(0, 0, At, B0); PG8_MMA(0, 1, At, B1); PG8_BAR; PG8_SCHED;
	s_waitcnt lgkmcnt(0)
	v_mfma_f32_16x16x32_bf16 v[62:65], v[140:143], v[200:203], v[62:65]
	v_mfma_f32_16x16x32_bf16 v[62:65], v[148:151], v[204:207], v[62:65]
	v_mfma_f32_16x16x32_bf16 v[58:61], v[156:159], v[200:203], v[58:61]
	v_mfma_f32_16x16x32_bf16 v[58:61], v[180:183], v[204:207], v[58:61]
	v_mfma_f32_16x16x32_bf16 v[46:49], v[140:143], v[208:211], v[46:49]
	v_mfma_f32_16x16x32_bf16 v[46:49], v[148:151], v[212:215], v[46:49]
	v_mfma_f32_16x16x32_bf16 v[42:45], v[156:159], v[208:211], v[42:45]
	v_mfma_f32_16x16x32_bf16 v[42:45], v[180:183], v[212:215], v[42:45]
	v_mfma_f32_16x16x32_bf16 v[30:33], v[140:143], v[216:219], v[30:33]
	v_mfma_f32_16x16x32_bf16 v[30:33], v[148:151], v[220:223], v[30:33]
	v_mfma_f32_16x16x32_bf16 v[26:29], v[156:159], v[216:219], v[26:29]
	v_mfma_f32_16x16x32_bf16 v[26:29], v[180:183], v[220:223], v[26:29]
	v_mfma_f32_16x16x32_bf16 v[14:17], v[140:143], v[224:227], v[14:17]
	v_mfma_f32_16x16x32_bf16 v[14:17], v[148:151], v[228:231], v[14:17]
	v_mfma_f32_16x16x32_bf16 v[10:13], v[156:159], v[224:227], v[10:13]
	v_mfma_f32_16x16x32_bf16 v[10:13], v[180:183], v[228:231], v[10:13]
	v_mfma_f32_16x16x32_bf16 v[54:57], v[184:187], v[200:203], v[54:57]
	v_mfma_f32_16x16x32_bf16 v[54:57], v[188:191], v[204:207], v[54:57]
	v_mfma_f32_16x16x32_bf16 v[50:53], v[192:195], v[200:203], v[50:53]
	v_mfma_f32_16x16x32_bf16 v[50:53], v[196:199], v[204:207], v[50:53]
	v_mfma_f32_16x16x32_bf16 v[38:41], v[184:187], v[208:211], v[38:41]
	v_mfma_f32_16x16x32_bf16 v[38:41], v[188:191], v[212:215], v[38:41]
	v_mfma_f32_16x16x32_bf16 v[34:37], v[192:195], v[208:211], v[34:37]
	v_mfma_f32_16x16x32_bf16 v[34:37], v[196:199], v[212:215], v[34:37]
	v_mfma_f32_16x16x32_bf16 v[22:25], v[184:187], v[216:219], v[22:25]
	v_mfma_f32_16x16x32_bf16 v[22:25], v[188:191], v[220:223], v[22:25]
	v_mfma_f32_16x16x32_bf16 v[18:21], v[192:195], v[216:219], v[18:21]
	v_mfma_f32_16x16x32_bf16 v[18:21], v[196:199], v[220:223], v[18:21]
	v_mfma_f32_16x16x32_bf16 v[6:9], v[184:187], v[224:227], v[6:9]
	v_mfma_f32_16x16x32_bf16 v[6:9], v[188:191], v[228:231], v[6:9]
	v_mfma_f32_16x16x32_bf16 v[2:5], v[192:195], v[224:227], v[2:5]
	v_mfma_f32_16x16x32_bf16 v[2:5], v[196:199], v[228:231], v[2:5]
	s_barrier
	s_add_i32 s44, 0, 0x18000
	v_add_u32_e32 v164, s44, v146
	s_add_i32 s45, 0, 0x1c000
	ds_read_b128 v[140:143], v164
	ds_read_b128 v[148:151], v164 offset:1024
	ds_read_b128 v[156:159], v164 offset:2048
	ds_read_b128 v[180:183], v164 offset:3072
	v_add_u32_e32 v164, s45, v146
	ds_read_b128 v[184:187], v164
	ds_read_b128 v[188:191], v164 offset:1024
	ds_read_b128 v[192:195], v164 offset:2048
	ds_read_b128 v[196:199], v164 offset:3072
	s_add_u32 s10, s24, 0xb0000
	s_addc_u32 s11, s25, 0
	s_mov_b32 m0, s31
	v_lshl_add_u64 v[170:171], s[10:11], 0, v[130:131]
	ds_read_b128 v[200:203], v147 offset:32768
	ds_read_b128 v[204:207], v147 offset:33792
	ds_read_b128 v[208:211], v147 offset:34816
	ds_read_b128 v[212:215], v147 offset:35840
	ds_read_b128 v[216:219], v147 offset:36864
	ds_read_b128 v[220:223], v147 offset:37888
	ds_read_b128 v[224:227], v147 offset:38912
	ds_read_b128 v[228:231], v147 offset:39936
	global_load_lds_dwordx4 v[170:171], off
	v_lshl_add_u64 v[170:171], s[10:11], 0, v[132:133]
	s_mov_b32 m0, s34
	s_nop 0
	global_load_lds_dwordx4 v[170:171], off
	s_waitcnt vmcnt(8)
	s_waitcnt lgkmcnt(0)
	s_barrier
	s_waitcnt lgkmcnt(0)
	v_mfma_f32_16x16x32_bf16 v[126:129], v[140:143], v[200:203], v[126:129]
	v_mfma_f32_16x16x32_bf16 v[126:129], v[148:151], v[204:207], v[126:129]
	v_mfma_f32_16x16x32_bf16 v[122:125], v[156:159], v[200:203], v[122:125]
	v_mfma_f32_16x16x32_bf16 v[122:125], v[180:183], v[204:207], v[122:125]
	v_mfma_f32_16x16x32_bf16 v[110:113], v[140:143], v[208:211], v[110:113]
	v_mfma_f32_16x16x32_bf16 v[110:113], v[148:151], v[212:215], v[110:113]
	v_mfma_f32_16x16x32_bf16 v[106:109], v[156:159], v[208:211], v[106:109]
	v_mfma_f32_16x16x32_bf16 v[106:109], v[180:183], v[212:215], v[106:109]
	v_mfma_f32_16x16x32_bf16 v[94:97], v[140:143], v[216:219], v[94:97]
	v_mfma_f32_16x16x32_bf16 v[94:97], v[148:151], v[220:223], v[94:97]
	v_mfma_f32_16x16x32_bf16 v[90:93], v[156:159], v[216:219], v[90:93]
	v_mfma_f32_16x16x32_bf16 v[90:93], v[180:183], v[220:223], v[90:93]
	v_mfma_f32_16x16x32_bf16 v[78:81], v[140:143], v[224:227], v[78:81]
	v_mfma_f32_16x16x32_bf16 v[78:81], v[148:151], v[228:231], v[78:81]
	v_mfma_f32_16x16x32_bf16 v[74:77], v[156:159], v[224:227], v[74:77]
	v_mfma_f32_16x16x32_bf16 v[74:77], v[180:183], v[228:231], v[74:77]
	v_mfma_f32_16x16x32_bf16 v[118:121], v[184:187], v[200:203], v[118:121]
	v_mfma_f32_16x16x32_bf16 v[118:121], v[188:191], v[204:207], v[118:121]
	v_mfma_f32_16x16x32_bf16 v[114:117], v[192:195], v[200:203], v[114:117]
	v_mfma_f32_16x16x32_bf16 v[114:117], v[196:199], v[204:207], v[114:117]
	v_mfma_f32_16x16x32_bf16 v[102:105], v[184:187], v[208:211], v[102:105]
	v_mfma_f32_16x16x32_bf16 v[102:105], v[188:191], v[212:215], v[102:105]
	v_mfma_f32_16x16x32_bf16 v[98:101], v[192:195], v[208:211], v[98:101]
	v_mfma_f32_16x16x32_bf16 v[98:101], v[196:199], v[212:215], v[98:101]
	v_mfma_f32_16x16x32_bf16 v[86:89], v[184:187], v[216:219], v[86:89]
	v_mfma_f32_16x16x32_bf16 v[86:89], v[188:191], v[220:223], v[86:89]
	v_mfma_f32_16x16x32_bf16 v[82:85], v[192:195], v[216:219], v[82:85]
	v_mfma_f32_16x16x32_bf16 v[82:85], v[196:199], v[220:223], v[82:85]
	v_mfma_f32_16x16x32_bf16 v[70:73], v[184:187], v[224:227], v[70:73]
	v_mfma_f32_16x16x32_bf16 v[70:73], v[188:191], v[228:231], v[70:73]
	v_mfma_f32_16x16x32_bf16 v[66:69], v[192:195], v[224:227], v[66:69]
	v_mfma_f32_16x16x32_bf16 v[66:69], v[196:199], v[228:231], v[66:69]
	s_barrier
; #define PG8_STAGE(bufoff, gbase, voff) do { _Pragma("unroll") for (int _i = 0; _i < 2; ++_i) \
;         __builtin_amdgcn_global_load_lds((const unsigned*)((const char*)(gbase) + (voff)[_i]), (LAS unsigned*)(lds + (bufoff) + ldsw + _i * 8192), 16, 0, 0); } while (0)
; #define PG8_LDA(dst, b, h) do { _Pragma("unroll") for (int m = 0; m < 4; ++m) _Pragma("unroll") for (int k = 0; k < 2; ++k) dst[m][k] = *(const LAS bf16x8*)(lds + PG8_SA(b, h) + aoff + m * 2048 + k * 1024); } while (0)
; #define PG8_MMA(ai, bj, At, Bt) do { __builtin_amdgcn_s_setprio(1); _Pragma("unroll") for (int m = 0; m < 4; ++m) _Pragma("unroll") for (int n = 0; n < 2; ++n) _Pragma("unroll") for (int k = 0; k < 2; ++k) \
;         acc[ai][bj][m][n] = __builtin_amdgcn_mfma_f32_16x16x32_bf16(Bt[n][k], At[m][k], acc[ai][bj][m][n], 0, 0, 0); __builtin_amdgcn_s_setprio(0); } while (0)
; #define PG8_WAIT_V(n) asm volatile("s_waitcnt vmcnt(" #n ")" ::: "memory")
; #define PG8_WAIT_L(n) asm volatile("s_waitcnt lgkmcnt(" #n ")" ::: "memory")
; #define PG8_BAR __builtin_amdgcn_s_barrier()
; #define PG8_SCHED __builtin_amdgcn_sched_barrier(0)
; template <class Epi, bool ALIGN_EPI>
; __device__ __forceinline__ void gemm_phase(LAS unsigned char* lds, const Gemm g, const StaticOrder& S, const Epi& E) {
;     ...
;             PG8_LDA(At, 1, 1); PG8_STAGE(PG8_SB(1, 0), b3, voffB); PG8_STAGE(PG8_SB(1, 1), b3 + hstepB, voffB); PG8_STAGE(PG8_SA(1, 0), a3, voffA);
;             PG8_WAIT_V(8); PG8_WAIT_L(0); PG8_BAR; PG8_MMA(1, 0, At, B0); PG8_MMA(1, 1, At, B1); PG8_BAR; PG8_SCHED;
	s_add_i32 s10, s44, s28
	v_lshl_add_u64 v[144:145], v[144:145], 0, s[94:95]
	s_mov_b32 m0, s10
	ds_read_b128 v[200:203], v147 offset:49152
	ds_read_b128 v[204:207], v147 offset:50176
	ds_read_b128 v[208:211], v147 offset:51200
	ds_read_b128 v[212:215], v147 offset:52224
	ds_read_b128 v[216:219], v147 offset:53248
	ds_read_b128 v[220:223], v147 offset:54272
	ds_read_b128 v[224:227], v147 offset:55296
	ds_read_b128 v[228:231], v147 offset:56320
	global_load_lds_dwordx4 v[144:145], off
	s_add_i32 m0, s10, 0x2000
	s_add_u32 s10, s22, 0xb0080
	v_lshl_add_u64 v[144:145], v[152:153], 0, s[94:95]
	s_addc_u32 s11, s23, 0
	s_add_i32 s22, s45, s28
	global_load_lds_dwordx4 v[144:145], off
	v_lshl_add_u64 v[144:145], s[10:11], 0, v[0:1]
	s_mov_b32 m0, s22
	s_nop 0
	global_load_lds_dwordx4 v[144:145], off
	v_lshl_add_u64 v[144:145], s[10:11], 0, v[134:135]
	s_add_i32 m0, s22, 0x2000
	s_nop 0
	global_load_lds_dwordx4 v[144:145], off
	v_lshl_add_u64 v[144:145], v[160:161], 0, s[94:95]
	s_mov_b32 m0, s35
	s_nop 0
	global_load_lds_dwordx4 v[144:145], off
	v_lshl_add_u64 v[144:145], v[162:163], 0, s[94:95]
	s_mov_b32 m0, s36
	s_nop 0
	global_load_lds_dwordx4 v[144:145], off
	s_waitcnt vmcnt(8)
	s_waitcnt lgkmcnt(0)
	s_barrier
	s_waitcnt lgkmcnt(0)
	v_mfma_f32_16x16x32_bf16 v[62:65], v[140:143], v[200:203], v[62:65]
	v_mfma_f32_16x16x32_bf16 v[62:65], v[148:151], v[204:207], v[62:65]
	v_mfma_f32_16x16x32_bf16 v[58:61], v[156:159], v[200:203], v[58:61]
	v_mfma_f32_16x16x32_bf16 v[58:61], v[180:183], v[204:207], v[58:61]
	v_mfma_f32_16x16x32_bf16 v[46:49], v[140:143], v[208:211], v[46:49]
	v_mfma_f32_16x16x32_bf16 v[46:49], v[148:151], v[212:215], v[46:49]
	v_mfma_f32_16x16x32_bf16 v[42:45], v[156:159], v[208:211], v[42:45]
	v_mfma_f32_16x16x32_bf16 v[42:45], v[180:183], v[212:215], v[42:45]
	v_mfma_f32_16x16x32_bf16 v[30:33], v[140:143], v[216:219], v[30:33]
	v_mfma_f32_16x16x32_bf16 v[30:33], v[148:151], v[220:223], v[30:33]
	v_mfma_f32_16x16x32_bf16 v[26:29], v[156:159], v[216:219], v[26:29]
	v_mfma_f32_16x16x32_bf16 v[26:29], v[180:183], v[220:223], v[26:29]
	v_mfma_f32_16x16x32_bf16 v[14:17], v[140:143], v[224:227], v[14:17]
	v_mfma_f32_16x16x32_bf16 v[14:17], v[148:151], v[228:231], v[14:17]
	v_mfma_f32_16x16x32_bf16 v[10:13], v[156:159], v[224:227], v[10:13]
	v_mfma_f32_16x16x32_bf16 v[10:13], v[180:183], v[228:231], v[10:13]
	v_mfma_f32_16x16x32_bf16 v[54:57], v[184:187], v[200:203], v[54:57]
	v_mfma_f32_16x16x32_bf16 v[54:57], v[188:191], v[204:207], v[54:57]
	v_mfma_f32_16x16x32_bf16 v[50:53], v[192:195], v[200:203], v[50:53]
	v_mfma_f32_16x16x32_bf16 v[50:53], v[196:199], v[204:207], v[50:53]
	v_mfma_f32_16x16x32_bf16 v[38:41], v[184:187], v[208:211], v[38:41]
	v_mfma_f32_16x16x32_bf16 v[38:41], v[188:191], v[212:215], v[38:41]
	v_mfma_f32_16x16x32_bf16 v[34:37], v[192:195], v[208:211], v[34:37]
	v_mfma_f32_16x16x32_bf16 v[34:37], v[196:199], v[212:215], v[34:37]
	v_mfma_f32_16x16x32_bf16 v[22:25], v[184:187], v[216:219], v[22:25]
	v_mfma_f32_16x16x32_bf16 v[22:25], v[188:191], v[220:223], v[22:25]
	v_mfma_f32_16x16x32_bf16 v[18:21], v[192:195], v[216:219], v[18:21]
	v_mfma_f32_16x16x32_bf16 v[18:21], v[196:199], v[220:223], v[18:21]
	v_mfma_f32_16x16x32_bf16 v[6:9], v[184:187], v[224:227], v[6:9]
	v_mfma_f32_16x16x32_bf16 v[6:9], v[188:191], v[228:231], v[6:9]
	v_mfma_f32_16x16x32_bf16 v[2:5], v[192:195], v[224:227], v[2:5]
	v_mfma_f32_16x16x32_bf16 v[2:5], v[196:199], v[228:231], v[2:5]
	s_cmp_lg_u32 s43, 40
	s_cbranch_scc1 .Ltail_bar_9
	s_cmp_eq_u64 s[2:3], 0
	s_cbranch_scc1 .Ltail_skip_9

; #define PG8_STAGE(bufoff, gbase, voff) do { _Pragma("unroll") for (int _i = 0; _i < 2; ++_i) \
;         __builtin_amdgcn_global_load_lds((const unsigned*)((const char*)(gbase) + (voff)[_i]), (LAS unsigned*)(lds + (bufoff) + ldsw + _i * 8192), 16, 0, 0); } while (0)
; #define PG8_LDA(dst, b, h) do { _Pragma("unroll") for (int m = 0; m < 4; ++m) _Pragma("unroll") for (int k = 0; k < 2; ++k) dst[m][k] = *(const LAS bf16x8*)(lds + PG8_SA(b, h) + aoff + m * 2048 + k * 1024); } while (0)
; #define PG8_LDB(dst, b, h) do { _Pragma("unroll") for (int n = 0; n < 2; ++n) _Pragma("unroll") for (int k = 0; k < 2; ++k) dst[n][k] = *(const LAS bf16x8*)(lds + PG8_SB(b, h) + boff + n * 2048 + k * 1024); } while (0)
; #define PG8_MMA(ai, bj, At, Bt) do { __builtin_amdgcn_s_setprio(1); _Pragma("unroll") for (int m = 0; m < 4; ++m) _Pragma("unroll") for (int n = 0; n < 2; ++n) _Pragma("unroll") for (int k = 0; k < 2; ++k) \
;         acc[ai][bj][m][n] = __builtin_amdgcn_mfma_f32_16x16x32_bf16(Bt[n][k], At[m][k], acc[ai][bj][m][n], 0, 0, 0); __builtin_amdgcn_s_setprio(0); } while (0)
; #define PG8_BAR __builtin_amdgcn_s_barrier()
; template <class Epi, bool ALIGN_EPI>
; __device__ __forceinline__ void gemm_phase(LAS unsigned char* lds, const Gemm g, const StaticOrder& S, const Epi& E) {
;     ...
;         const bool has_next = S.next(ui + 1, nxt);
;         const char* nA = has_next ? (const char*)g.A + (size_t)nxt.pm * tstepA : cA; const char* nB = has_next ? (const char*)g.Bt + (size_t)nxt.pn * tstepB : cB;
;         for (int t = 0; t < nt; t += 2) {
;             const bool last = (t == nt - 2);
;             const char* a1 = cA + (size_t)(t + 1) * kstep;
;             const char* a2 = last ? nA : cA + (size_t)(t + 2) * kstep; const char* b2 = last ? nB : cB + (size_t)(t + 2) * kstep;
;             const char* a3 = a2 + kstep; const char* b3 = b2 + kstep;
;             PG8_LDB(B0, 0, 0); PG8_LDB(B1, 0, 1); PG8_SCHED; PG8_LDA(At, 0, 0); PG8_STAGE(PG8_SA(1, 1), a1 + hstepA, voffA);
;             PG8_WAIT_V(8); PG8_WAIT_L(0); PG8_BAR; PG8_MMA(0, 0, At, B0); PG8_MMA(0, 1, At, B1); PG8_BAR; PG8_SCHED;
;             PG8_LDA(At, 0, 1); PG8_STAGE(PG8_SB(0, 0), b2, voffB); PG8_STAGE(PG8_SB(0, 1), b2 + hstepB, voffB); PG8_STAGE(PG8_SA(0, 0), a2, voffA);
;             PG8_WAIT_V(8); PG8_WAIT_L(0); PG8_BAR; PG8_MMA(1, 0, At, B0); PG8_MMA(1, 1, At, B1); PG8_BAR; PG8_SCHED;
.LBB0_287:
	s_ashr_i32 s9, s8, 31
	s_lshl_b64 s[16:17], s[8:9], 17
	s_add_u32 s16, s4, s16
	s_addc_u32 s17, s28, s17
	s_and_b64 s[18:19], s[12:13], exec
	s_cselect_b32 s27, s17, s21
	s_cselect_b32 s26, s16, s20
	s_ashr_i32 s11, s10, 31
	s_lshl_b64 s[18:19], s[10:11], 17
	s_add_u32 s18, s29, s18
	s_addc_u32 s19, s30, s19
	s_and_b64 s[24:25], s[12:13], exec
	s_cselect_b32 s25, s19, s23
	s_cselect_b32 s24, s18, s22
	s_add_i32 s11, 0, 0x10000
	s_add_i32 s41, 0, 0x14000
	v_add_u32_e32 v164, s11, v136
	v_add_u32_e32 v165, s41, v136
	ds_read_b128 v[2:5], v164
	ds_read_b128 v[6:9], v164 offset:1024
	ds_read_b128 v[10:13], v164 offset:2048
	ds_read_b128 v[14:17], v164 offset:3072
	ds_read_b128 v[18:21], v165
	ds_read_b128 v[22:25], v165 offset:1024
	ds_read_b128 v[26:29], v165 offset:2048
	ds_read_b128 v[30:33], v165 offset:3072
	s_add_u32 s42, s20, 0x10080
	s_addc_u32 s43, s21, 0
	s_add_i32 s45, s34, 0xc000
	v_lshl_add_u64 v[66:67], s[42:43], 0, v[130:131]
	s_mov_b32 m0, s45
	s_add_i32 s9, s34, 0xe000
	ds_read_b128 v[34:37], v137
	ds_read_b128 v[38:41], v137 offset:1024
	ds_read_b128 v[42:45], v137 offset:2048
	ds_read_b128 v[46:49], v137 offset:3072
	ds_read_b128 v[50:53], v137 offset:4096
	ds_read_b128 v[54:57], v137 offset:5120
	ds_read_b128 v[58:61], v137 offset:6144
	ds_read_b128 v[62:65], v137 offset:7168
	global_load_lds_dwordx4 v[66:67], off
	v_lshl_add_u64 v[66:67], s[42:43], 0, v[132:133]
	s_mov_b32 m0, s9
	s_nop 0
	global_load_lds_dwordx4 v[66:67], off
	s_waitcnt vmcnt(8)
	s_waitcnt lgkmcnt(0)
	s_barrier
	s_waitcnt lgkmcnt(0)
	v_mfma_f32_16x16x32_bf16 v[66:69], v[2:5], v[34:37], 0
	v_mfma_f32_16x16x32_bf16 v[70:73], v[10:13], v[34:37], 0
	v_mfma_f32_16x16x32_bf16 v[74:77], v[2:5], v[42:45], 0
	v_mfma_f32_16x16x32_bf16 v[78:81], v[10:13], v[42:45], 0
	v_mfma_f32_16x16x32_bf16 v[82:85], v[2:5], v[50:53], 0
	v_mfma_f32_16x16x32_bf16 v[86:89], v[10:13], v[50:53], 0
	v_mfma_f32_16x16x32_bf16 v[90:93], v[2:5], v[58:61], 0
	v_mfma_f32_16x16x32_bf16 v[94:97], v[10:13], v[58:61], 0
	v_mfma_f32_16x16x32_bf16 v[66:69], v[6:9], v[38:41], v[66:69]
	v_mfma_f32_16x16x32_bf16 v[70:73], v[14:17], v[38:41], v[70:73]
	v_mfma_f32_16x16x32_bf16 v[74:77], v[6:9], v[46:49], v[74:77]
	v_mfma_f32_16x16x32_bf16 v[78:81], v[14:17], v[46:49], v[78:81]
	v_mfma_f32_16x16x32_bf16 v[82:85], v[6:9], v[54:57], v[82:85]
	v_mfma_f32_16x16x32_bf16 v[86:89], v[14:17], v[54:57], v[86:89]
	v_mfma_f32_16x16x32_bf16 v[90:93], v[6:9], v[62:65], v[90:93]
	v_mfma_f32_16x16x32_bf16 v[94:97], v[14:17], v[62:65], v[94:97]
	v_mfma_f32_16x16x32_bf16 v[98:101], v[18:21], v[34:37], 0
	v_mfma_f32_16x16x32_bf16 v[34:37], v[26:29], v[34:37], 0
	v_mfma_f32_16x16x32_bf16 v[98:101], v[22:25], v[38:41], v[98:101]
	v_mfma_f32_16x16x32_bf16 v[34:37], v[30:33], v[38:41], v[34:37]
	v_mfma_f32_16x16x32_bf16 v[38:41], v[18:21], v[42:45], 0
	v_mfma_f32_16x16x32_bf16 v[42:45], v[26:29], v[42:45], 0
	v_mfma_f32_16x16x32_bf16 v[38:41], v[22:25], v[46:49], v[38:41]
	v_mfma_f32_16x16x32_bf16 v[42:45], v[30:33], v[46:49], v[42:45]
	v_mfma_f32_16x16x32_bf16 v[46:49], v[18:21], v[50:53], 0
	v_mfma_f32_16x16x32_bf16 v[50:53], v[26:29], v[50:53], 0
	v_mfma_f32_16x16x32_bf16 v[46:49], v[22:25], v[54:57], v[46:49]
	v_mfma_f32_16x16x32_bf16 v[50:53], v[30:33], v[54:57], v[50:53]
	v_mfma_f32_16x16x32_bf16 v[54:57], v[18:21], v[58:61], 0
	v_mfma_f32_16x16x32_bf16 v[58:61], v[26:29], v[58:61], 0
	v_mfma_f32_16x16x32_bf16 v[54:57], v[22:25], v[62:65], v[54:57]
	v_mfma_f32_16x16x32_bf16 v[58:61], v[30:33], v[62:65], v[58:61]
	s_barrier
	s_add_i32 s43, s11, s31
	v_lshl_add_u64 v[160:161], s[22:23], 0, v[0:1]
	s_mov_b64 s[48:49], 0x100
	s_add_i32 s11, s43, 0x2000
	v_lshl_add_u64 v[138:139], v[160:161], 0, s[48:49]
	s_mov_b32 m0, s43
	v_lshl_add_u64 v[162:163], s[22:23], 0, v[134:135]
	s_add_u32 s46, s22, 0x10100
	ds_read_b128 v[62:65], v137 offset:16384
	ds_read_b128 v[102:105], v137 offset:17408
	ds_read_b128 v[106:109], v137 offset:18432
	ds_read_b128 v[110:113], v137 offset:19456
	ds_read_b128 v[114:117], v137 offset:20480
	ds_read_b128 v[118:121], v137 offset:21504
	ds_read_b128 v[122:125], v137 offset:22528
	ds_read_b128 v[126:129], v137 offset:23552
	global_load_lds_dwordx4 v[138:139], off
	v_lshl_add_u64 v[138:139], v[162:163], 0, s[48:49]
	s_mov_b32 m0, s11
	s_addc_u32 s47, s23, 0
	s_add_i32 s41, s41, s31
	global_load_lds_dwordx4 v[138:139], off
	v_lshl_add_u64 v[138:139], s[46:47], 0, v[0:1]
	s_mov_b32 m0, s41
	s_add_i32 s42, s41, 0x2000
	global_load_lds_dwordx4 v[138:139], off
	v_lshl_add_u64 v[138:139], s[46:47], 0, v[134:135]
	s_mov_b32 m0, s42
	v_lshl_add_u64 v[170:171], s[20:21], 0, v[130:131]
	global_load_lds_dwordx4 v[138:139], off
	v_lshl_add_u64 v[138:139], v[170:171], 0, s[48:49]
	s_mov_b32 m0, s34
	v_lshl_add_u64 v[172:173], s[20:21], 0, v[132:133]
	global_load_lds_dwordx4 v[138:139], off
	v_lshl_add_u64 v[138:139], v[172:173], 0, s[48:49]
	s_mov_b32 m0, s35
	s_nop 0
	global_load_lds_dwordx4 v[138:139], off
	s_waitcnt vmcnt(8)
	s_waitcnt lgkmcnt(0)
	s_barrier
; #define PG8_STAGE(bufoff, gbase, voff) do { _Pragma("unroll") for (int _i = 0; _i < 2; ++_i) \
;         __builtin_amdgcn_global_load_lds((const unsigned*)((const char*)(gbase) + (voff)[_i]), (LAS unsigned*)(lds + (bufoff) + ldsw + _i * 8192), 16, 0, 0); } while (0)
; #define PG8_LDA(dst, b, h) do { _Pragma("unroll") for (int m = 0; m < 4; ++m) _Pragma("unroll") for (int k = 0; k < 2; ++k) dst[m][k] = *(const LAS bf16x8*)(lds + PG8_SA(b, h) + aoff + m * 2048 + k * 1024); } while (0)
; #define PG8_LDB(dst, b, h) do { _Pragma("unroll") for (int n = 0; n < 2; ++n) _Pragma("unroll") for (int k = 0; k < 2; ++k) dst[n][k] = *(const LAS bf16x8*)(lds + PG8_SB(b, h) + boff + n * 2048 + k * 1024); } while (0)
; #define PG8_MMA(ai, bj, At, Bt) do { __builtin_amdgcn_s_setprio(1); _Pragma("unroll") for (int m = 0; m < 4; ++m) _Pragma("unroll") for (int n = 0; n < 2; ++n) _Pragma("unroll") for (int k = 0; k < 2; ++k) \
;         acc[ai][bj][m][n] = __builtin_amdgcn_mfma_f32_16x16x32_bf16(Bt[n][k], At[m][k], acc[ai][bj][m][n], 0, 0, 0); __builtin_amdgcn_s_setprio(0); } while (0)
; #define PG8_WAIT_V(n) asm volatile("s_waitcnt vmcnt(" #n ")" ::: "memory")
; #define PG8_WAIT_L(n) asm volatile("s_waitcnt lgkmcnt(" #n ")" ::: "memory")
; #define PG8_BAR __builtin_amdgcn_s_barrier()
; #define PG8_SCHED __builtin_amdgcn_sched_barrier(0)
; template <class Epi, bool ALIGN_EPI>
; __device__ __forceinline__ void gemm_phase(LAS unsigned char* lds, const Gemm g, const StaticOrder& S, const Epi& E) {
;     ...
;             PG8_WAIT_V(8); PG8_WAIT_L(0); PG8_BAR; PG8_MMA(1, 0, At, B0); PG8_MMA(1, 1, At, B1); PG8_BAR; PG8_SCHED;
;             PG8_LDB(B0, 1, 0); PG8_LDB(B1, 1, 1); PG8_SCHED; PG8_LDA(At, 1, 0); PG8_STAGE(PG8_SA(0, 1), a2 + hstepA, voffA);
;             PG8_WAIT_V(8); PG8_WAIT_L(0); PG8_BAR; PG8_MMA(0, 0, At, B0); PG8_MMA(0, 1, At, B1); PG8_BAR; PG8_SCHED;
	s_waitcnt lgkmcnt(0)
	v_mfma_f32_16x16x32_bf16 v[138:141], v[2:5], v[62:65], 0
	v_mfma_f32_16x16x32_bf16 v[146:149], v[2:5], v[106:109], 0
	v_mfma_f32_16x16x32_bf16 v[156:159], v[2:5], v[114:117], 0
	v_mfma_f32_16x16x32_bf16 v[2:5], v[2:5], v[122:125], 0
	v_mfma_f32_16x16x32_bf16 v[138:141], v[6:9], v[102:105], v[138:141]
	v_mfma_f32_16x16x32_bf16 v[146:149], v[6:9], v[110:113], v[146:149]
	v_mfma_f32_16x16x32_bf16 v[156:159], v[6:9], v[118:121], v[156:159]
	v_mfma_f32_16x16x32_bf16 v[2:5], v[6:9], v[126:129], v[2:5]
	v_mfma_f32_16x16x32_bf16 v[6:9], v[10:13], v[122:125], 0
	v_mfma_f32_16x16x32_bf16 v[142:145], v[10:13], v[62:65], 0
	v_mfma_f32_16x16x32_bf16 v[150:153], v[10:13], v[106:109], 0
	v_mfma_f32_16x16x32_bf16 v[180:183], v[10:13], v[114:117], 0
	v_mfma_f32_16x16x32_bf16 v[6:9], v[14:17], v[126:129], v[6:9]
	v_mfma_f32_16x16x32_bf16 v[142:145], v[14:17], v[102:105], v[142:145]
	v_mfma_f32_16x16x32_bf16 v[150:153], v[14:17], v[110:113], v[150:153]
	v_mfma_f32_16x16x32_bf16 v[180:183], v[14:17], v[118:121], v[180:183]
	v_mfma_f32_16x16x32_bf16 v[10:13], v[18:21], v[62:65], 0
	v_mfma_f32_16x16x32_bf16 v[14:17], v[26:29], v[62:65], 0
	v_mfma_f32_16x16x32_bf16 v[10:13], v[22:25], v[102:105], v[10:13]
	v_mfma_f32_16x16x32_bf16 v[14:17], v[30:33], v[102:105], v[14:17]
	v_mfma_f32_16x16x32_bf16 v[62:65], v[18:21], v[106:109], 0
	v_mfma_f32_16x16x32_bf16 v[102:105], v[26:29], v[106:109], 0
	v_mfma_f32_16x16x32_bf16 v[106:109], v[18:21], v[114:117], 0
	v_mfma_f32_16x16x32_bf16 v[18:21], v[18:21], v[122:125], 0
	v_mfma_f32_16x16x32_bf16 v[62:65], v[22:25], v[110:113], v[62:65]
	v_mfma_f32_16x16x32_bf16 v[102:105], v[30:33], v[110:113], v[102:105]
	v_mfma_f32_16x16x32_bf16 v[106:109], v[22:25], v[118:121], v[106:109]
	v_mfma_f32_16x16x32_bf16 v[110:113], v[26:29], v[114:117], 0
	v_mfma_f32_16x16x32_bf16 v[18:21], v[22:25], v[126:129], v[18:21]
	v_mfma_f32_16x16x32_bf16 v[22:25], v[26:29], v[122:125], 0
	v_mfma_f32_16x16x32_bf16 v[110:113], v[30:33], v[118:121], v[110:113]
	v_mfma_f32_16x16x32_bf16 v[22:25], v[30:33], v[126:129], v[22:25]
	s_barrier
	s_add_i32 s44, 0, 0x18000
	s_add_i32 s50, 0, 0x1c000
	v_add_u32_e32 v228, s44, v136
	v_add_u32_e32 v236, s50, v136
	ds_read_b128 v[26:29], v228
	ds_read_b128 v[30:33], v228 offset:1024
	ds_read_b128 v[114:117], v228 offset:2048
	ds_read_b128 v[118:121], v228 offset:3072
	ds_read_b128 v[122:125], v236
	ds_read_b128 v[126:129], v236 offset:1024
	ds_read_b128 v[184:187], v236 offset:2048
	ds_read_b128 v[188:191], v236 offset:3072
	s_add_u32 s46, s20, 0x10100
	s_addc_u32 s47, s21, 0
	s_mov_b32 m0, s36
	v_lshl_add_u64 v[224:225], s[46:47], 0, v[130:131]
	ds_read_b128 v[192:195], v137 offset:32768
	ds_read_b128 v[196:199], v137 offset:33792
	ds_read_b128 v[200:203], v137 offset:34816
	ds_read_b128 v[204:207], v137 offset:35840
	ds_read_b128 v[208:211], v137 offset:36864
	ds_read_b128 v[212:215], v137 offset:37888
	ds_read_b128 v[216:219], v137 offset:38912
	ds_read_b128 v[220:223], v137 offset:39936
	global_load_lds_dwordx4 v[224:225], off
	v_lshl_add_u64 v[224:225], s[46:47], 0, v[132:133]
	s_mov_b32 m0, s37
	s_nop 0
	global_load_lds_dwordx4 v[224:225], off
	s_waitcnt vmcnt(8)
	s_waitcnt lgkmcnt(0)
	s_barrier
	s_waitcnt lgkmcnt(0)
	v_mfma_f32_16x16x32_bf16 v[66:69], v[26:29], v[192:195], v[66:69]
	v_mfma_f32_16x16x32_bf16 v[66:69], v[30:33], v[196:199], v[66:69]
	v_mfma_f32_16x16x32_bf16 v[70:73], v[114:117], v[192:195], v[70:73]
	v_mfma_f32_16x16x32_bf16 v[70:73], v[118:121], v[196:199], v[70:73]
	v_mfma_f32_16x16x32_bf16 v[74:77], v[26:29], v[200:203], v[74:77]
	v_mfma_f32_16x16x32_bf16 v[74:77], v[30:33], v[204:207], v[74:77]
	v_mfma_f32_16x16x32_bf16 v[78:81], v[114:117], v[200:203], v[78:81]
	v_mfma_f32_16x16x32_bf16 v[78:81], v[118:121], v[204:207], v[78:81]
	v_mfma_f32_16x16x32_bf16 v[82:85], v[26:29], v[208:211], v[82:85]
	v_mfma_f32_16x16x32_bf16 v[82:85], v[30:33], v[212:215], v[82:85]
	v_mfma_f32_16x16x32_bf16 v[86:89], v[114:117], v[208:211], v[86:89]
	v_mfma_f32_16x16x32_bf16 v[86:89], v[118:121], v[212:215], v[86:89]
	v_mfma_f32_16x16x32_bf16 v[90:93], v[26:29], v[216:219], v[90:93]
	v_mfma_f32_16x16x32_bf16 v[90:93], v[30:33], v[220:223], v[90:93]
	v_mfma_f32_16x16x32_bf16 v[94:97], v[114:117], v[216:219], v[94:97]
	v_mfma_f32_16x16x32_bf16 v[94:97], v[118:121], v[220:223], v[94:97]
	v_mfma_f32_16x16x32_bf16 v[98:101], v[122:125], v[192:195], v[98:101]
	v_mfma_f32_16x16x32_bf16 v[98:101], v[126:129], v[196:199], v[98:101]
	v_mfma_f32_16x16x32_bf16 v[34:37], v[184:187], v[192:195], v[34:37]
	v_mfma_f32_16x16x32_bf16 v[34:37], v[188:191], v[196:199], v[34:37]
	v_mfma_f32_16x16x32_bf16 v[38:41], v[122:125], v[200:203], v[38:41]
	v_mfma_f32_16x16x32_bf16 v[38:41], v[126:129], v[204:207], v[38:41]
	v_mfma_f32_16x16x32_bf16 v[42:45], v[184:187], v[200:203], v[42:45]
	v_mfma_f32_16x16x32_bf16 v[42:45], v[188:191], v[204:207], v[42:45]
	v_mfma_f32_16x16x32_bf16 v[46:49], v[122:125], v[208:211], v[46:49]
	v_mfma_f32_16x16x32_bf16 v[46:49], v[126:129], v[212:215], v[46:49]
	v_mfma_f32_16x16x32_bf16 v[50:53], v[184:187], v[208:211], v[50:53]
	v_mfma_f32_16x16x32_bf16 v[50:53], v[188:191], v[212:215], v[50:53]
	v_mfma_f32_16x16x32_bf16 v[54:57], v[122:125], v[216:219], v[54:57]
	v_mfma_f32_16x16x32_bf16 v[54:57], v[126:129], v[220:223], v[54:57]
	v_mfma_f32_16x16x32_bf16 v[58:61], v[184:187], v[216:219], v[58:61]
	v_mfma_f32_16x16x32_bf16 v[58:61], v[188:191], v[220:223], v[58:61]
	s_barrier
; #define PG8_STAGE(bufoff, gbase, voff) do { _Pragma("unroll") for (int _i = 0; _i < 2; ++_i) \
;         __builtin_amdgcn_global_load_lds((const unsigned*)((const char*)(gbase) + (voff)[_i]), (LAS unsigned*)(lds + (bufoff) + ldsw + _i * 8192), 16, 0, 0); } while (0)
; #define PG8_LDA(dst, b, h) do { _Pragma("unroll") for (int m = 0; m < 4; ++m) _Pragma("unroll") for (int k = 0; k < 2; ++k) dst[m][k] = *(const LAS bf16x8*)(lds + PG8_SA(b, h) + aoff + m * 2048 + k * 1024); } while (0)
; #define PG8_LDB(dst, b, h) do { _Pragma("unroll") for (int n = 0; n < 2; ++n) _Pragma("unroll") for (int k = 0; k < 2; ++k) dst[n][k] = *(const LAS bf16x8*)(lds + PG8_SB(b, h) + boff + n * 2048 + k * 1024); } while (0)
; #define PG8_MMA(ai, bj, At, Bt) do { __builtin_amdgcn_s_setprio(1); _Pragma("unroll") for (int m = 0; m < 4; ++m) _Pragma("unroll") for (int n = 0; n < 2; ++n) _Pragma("unroll") for (int k = 0; k < 2; ++k) \
;         acc[ai][bj][m][n] = __builtin_amdgcn_mfma_f32_16x16x32_bf16(Bt[n][k], At[m][k], acc[ai][bj][m][n], 0, 0, 0); __builtin_amdgcn_s_setprio(0); } while (0)
; #define PG8_WAIT_V(n) asm volatile("s_waitcnt vmcnt(" #n ")" ::: "memory")
; #define PG8_WAIT_L(n) asm volatile("s_waitcnt lgkmcnt(" #n ")" ::: "memory")
; #define PG8_BAR __builtin_amdgcn_s_barrier()
; #define PG8_SCHED __builtin_amdgcn_sched_barrier(0)
; template <class Epi, bool ALIGN_EPI>
; __device__ __forceinline__ void gemm_phase(LAS unsigned char* lds, const Gemm g, const StaticOrder& S, const Epi& E) {
;     ...
;             PG8_LDB(B0, 0, 0); PG8_LDB(B1, 0, 1); PG8_SCHED; PG8_LDA(At, 0, 0); PG8_STAGE(PG8_SA(1, 1), a1 + hstepA, voffA);
;             PG8_WAIT_V(8); PG8_WAIT_L(0); PG8_BAR; PG8_MMA(0, 0, At, B0); PG8_MMA(0, 1, At, B1); PG8_BAR; PG8_SCHED;
;     ...
;             PG8_LDA(At, 1, 1); PG8_STAGE(PG8_SB(1, 0), b3, voffB); PG8_STAGE(PG8_SB(1, 1), b3 + hstepB, voffB); PG8_STAGE(PG8_SA(1, 0), a3, voffA);
;             PG8_WAIT_V(8); PG8_WAIT_L(0); PG8_BAR; PG8_MMA(1, 0, At, B0); PG8_MMA(1, 1, At, B1); PG8_BAR; PG8_SCHED;
	s_add_i32 s46, s44, s31
	s_mov_b64 s[52:53], 0x180
	s_add_i32 s44, s46, 0x2000
	v_lshl_add_u64 v[160:161], v[160:161], 0, s[52:53]
	s_mov_b32 m0, s46
	s_add_u32 s48, s22, 0x10180
	ds_read_b128 v[192:195], v137 offset:49152
	ds_read_b128 v[196:199], v137 offset:50176
	ds_read_b128 v[200:203], v137 offset:51200
	ds_read_b128 v[204:207], v137 offset:52224
	ds_read_b128 v[208:211], v137 offset:53248
	ds_read_b128 v[212:215], v137 offset:54272
	ds_read_b128 v[216:219], v137 offset:55296
	ds_read_b128 v[220:223], v137 offset:56320
	global_load_lds_dwordx4 v[160:161], off
	v_lshl_add_u64 v[160:161], v[162:163], 0, s[52:53]
	s_mov_b32 m0, s44
	s_addc_u32 s49, s23, 0
	s_add_i32 s22, s50, s31
	global_load_lds_dwordx4 v[160:161], off
	v_lshl_add_u64 v[160:161], s[48:49], 0, v[0:1]
	s_mov_b32 m0, s22
	s_add_i32 s23, s22, 0x2000
	global_load_lds_dwordx4 v[160:161], off
	v_lshl_add_u64 v[160:161], s[48:49], 0, v[134:135]
	s_mov_b32 m0, s23
	s_nop 0
	global_load_lds_dwordx4 v[160:161], off
	v_lshl_add_u64 v[160:161], v[170:171], 0, s[52:53]
	s_mov_b32 m0, s38
	s_nop 0
	global_load_lds_dwordx4 v[160:161], off
	v_lshl_add_u64 v[160:161], v[172:173], 0, s[52:53]
	s_mov_b32 m0, s39
	s_nop 0
	global_load_lds_dwordx4 v[160:161], off
	s_waitcnt vmcnt(8)
	s_waitcnt lgkmcnt(0)
	s_barrier
	s_waitcnt lgkmcnt(0)
	v_mfma_f32_16x16x32_bf16 v[2:5], v[26:29], v[216:219], v[2:5]
	v_mfma_f32_16x16x32_bf16 v[2:5], v[30:33], v[220:223], v[2:5]
	v_mfma_f32_16x16x32_bf16 v[6:9], v[114:117], v[216:219], v[6:9]
	v_mfma_f32_16x16x32_bf16 v[6:9], v[118:121], v[220:223], v[6:9]
	v_mfma_f32_16x16x32_bf16 v[138:141], v[26:29], v[192:195], v[138:141]
	v_mfma_f32_16x16x32_bf16 v[138:141], v[30:33], v[196:199], v[138:141]
	v_mfma_f32_16x16x32_bf16 v[142:145], v[114:117], v[192:195], v[142:145]
	v_mfma_f32_16x16x32_bf16 v[142:145], v[118:121], v[196:199], v[142:145]
	v_mfma_f32_16x16x32_bf16 v[146:149], v[26:29], v[200:203], v[146:149]
	v_mfma_f32_16x16x32_bf16 v[146:149], v[30:33], v[204:207], v[146:149]
	v_mfma_f32_16x16x32_bf16 v[150:153], v[114:117], v[200:203], v[150:153]
	v_mfma_f32_16x16x32_bf16 v[150:153], v[118:121], v[204:207], v[150:153]
	v_mfma_f32_16x16x32_bf16 v[156:159], v[26:29], v[208:211], v[156:159]
	v_mfma_f32_16x16x32_bf16 v[156:159], v[30:33], v[212:215], v[156:159]
	v_mfma_f32_16x16x32_bf16 v[180:183], v[114:117], v[208:211], v[180:183]
	v_mfma_f32_16x16x32_bf16 v[180:183], v[118:121], v[212:215], v[180:183]
	v_mfma_f32_16x16x32_bf16 v[10:13], v[122:125], v[192:195], v[10:13]
	v_mfma_f32_16x16x32_bf16 v[14:17], v[184:187], v[192:195], v[14:17]
	v_mfma_f32_16x16x32_bf16 v[26:29], v[122:125], v[200:203], v[62:65]
	v_mfma_f32_16x16x32_bf16 v[30:33], v[184:187], v[200:203], v[102:105]
	v_mfma_f32_16x16x32_bf16 v[62:65], v[122:125], v[208:211], v[106:109]
	v_mfma_f32_16x16x32_bf16 v[102:105], v[184:187], v[208:211], v[110:113]
	v_mfma_f32_16x16x32_bf16 v[18:21], v[122:125], v[216:219], v[18:21]
	v_mfma_f32_16x16x32_bf16 v[22:25], v[184:187], v[216:219], v[22:25]
	v_mfma_f32_16x16x32_bf16 v[10:13], v[126:129], v[196:199], v[10:13]
	v_mfma_f32_16x16x32_bf16 v[14:17], v[188:191], v[196:199], v[14:17]
	v_mfma_f32_16x16x32_bf16 v[26:29], v[126:129], v[204:207], v[26:29]
	v_mfma_f32_16x16x32_bf16 v[30:33], v[188:191], v[204:207], v[30:33]
	v_mfma_f32_16x16x32_bf16 v[62:65], v[126:129], v[212:215], v[62:65]
	v_mfma_f32_16x16x32_bf16 v[102:105], v[188:191], v[212:215], v[102:105]
	v_mfma_f32_16x16x32_bf16 v[18:21], v[126:129], v[220:223], v[18:21]
	v_mfma_f32_16x16x32_bf16 v[22:25], v[188:191], v[220:223], v[22:25]
	s_barrier
	ds_read_b128 v[106:109], v164
	ds_read_b128 v[110:113], v164 offset:1024
	ds_read_b128 v[114:117], v164 offset:2048
	ds_read_b128 v[118:121], v164 offset:3072
	ds_read_b128 v[122:125], v165
	ds_read_b128 v[126:129], v165 offset:1024
	ds_read_b128 v[184:187], v165 offset:2048
	ds_read_b128 v[188:191], v165 offset:3072
	s_add_u32 s20, s20, 0x10180
	s_addc_u32 s21, s21, 0
	s_mov_b32 m0, s45
	v_lshl_add_u64 v[160:161], s[20:21], 0, v[130:131]
	ds_read_b128 v[192:195], v137
	ds_read_b128 v[196:199], v137 offset:1024
	ds_read_b128 v[200:203], v137 offset:2048
	ds_read_b128 v[204:207], v137 offset:3072
	ds_read_b128 v[208:211], v137 offset:4096
	ds_read_b128 v[212:215], v137 offset:5120
	ds_read_b128 v[216:219], v137 offset:6144
	ds_read_b128 v[220:223], v137 offset:7168
	global_load_lds_dwordx4 v[160:161], off
	v_lshl_add_u64 v[160:161], s[20:21], 0, v[132:133]
	s_mov_b32 m0, s9
	s_nop 0
	global_load_lds_dwordx4 v[160:161], off
	s_waitcnt vmcnt(8)
	s_waitcnt lgkmcnt(0)
	s_barrier
; #define PG8_STAGE(bufoff, gbase, voff) do { _Pragma("unroll") for (int _i = 0; _i < 2; ++_i) \
;         __builtin_amdgcn_global_load_lds((const unsigned*)((const char*)(gbase) + (voff)[_i]), (LAS unsigned*)(lds + (bufoff) + ldsw + _i * 8192), 16, 0, 0); } while (0)
; #define PG8_LDA(dst, b, h) do { _Pragma("unroll") for (int m = 0; m < 4; ++m) _Pragma("unroll") for (int k = 0; k < 2; ++k) dst[m][k] = *(const LAS bf16x8*)(lds + PG8_SA(b, h) + aoff + m * 2048 + k * 1024); } while (0)
; #define PG8_LDB(dst, b, h) do { _Pragma("unroll") for (int n = 0; n < 2; ++n) _Pragma("unroll") for (int k = 0; k < 2; ++k) dst[n][k] = *(const LAS bf16x8*)(lds + PG8_SB(b, h) + boff + n * 2048 + k * 1024); } while (0)
; #define PG8_MMA(ai, bj, At, Bt) do { __builtin_amdgcn_s_setprio(1); _Pragma("unroll") for (int m = 0; m < 4; ++m) _Pragma("unroll") for (int n = 0; n < 2; ++n) _Pragma("unroll") for (int k = 0; k < 2; ++k) \
;         acc[ai][bj][m][n] = __builtin_amdgcn_mfma_f32_16x16x32_bf16(Bt[n][k], At[m][k], acc[ai][bj][m][n], 0, 0, 0); __builtin_amdgcn_s_setprio(0); } while (0)
; #define PG8_WAIT_V(n) asm volatile("s_waitcnt vmcnt(" #n ")" ::: "memory")
; #define PG8_WAIT_L(n) asm volatile("s_waitcnt lgkmcnt(" #n ")" ::: "memory")
; #define PG8_BAR __builtin_amdgcn_s_barrier()
; #define PG8_SCHED __builtin_amdgcn_sched_barrier(0)
; template <class Epi, bool ALIGN_EPI>
; __device__ __forceinline__ void gemm_phase(LAS unsigned char* lds, const Gemm g, const StaticOrder& S, const Epi& E) {
;     ...
;             PG8_WAIT_V(8); PG8_WAIT_L(0); PG8_BAR; PG8_MMA(0, 0, At, B0); PG8_MMA(0, 1, At, B1); PG8_BAR; PG8_SCHED;
;             PG8_LDA(At, 0, 1); PG8_STAGE(PG8_SB(0, 0), b2, voffB); PG8_STAGE(PG8_SB(0, 1), b2 + hstepB, voffB); PG8_STAGE(PG8_SA(0, 0), a2, voffA);
;             PG8_WAIT_V(8); PG8_WAIT_L(0); PG8_BAR; PG8_MMA(1, 0, At, B0); PG8_MMA(1, 1, At, B1); PG8_BAR; PG8_SCHED;
;             PG8_LDB(B0, 1, 0); PG8_LDB(B1, 1, 1); PG8_SCHED; PG8_LDA(At, 1, 0); PG8_STAGE(PG8_SA(0, 1), a2 + hstepA, voffA);
;             PG8_WAIT_V(8); PG8_WAIT_L(0); PG8_BAR; PG8_MMA(0, 0, At, B0); PG8_MMA(0, 1, At, B1); PG8_BAR; PG8_SCHED;
	s_waitcnt lgkmcnt(0)
	v_mfma_f32_16x16x32_bf16 v[66:69], v[106:109], v[192:195], v[66:69]
	v_mfma_f32_16x16x32_bf16 v[66:69], v[110:113], v[196:199], v[66:69]
	v_mfma_f32_16x16x32_bf16 v[70:73], v[114:117], v[192:195], v[70:73]
	v_mfma_f32_16x16x32_bf16 v[70:73], v[118:121], v[196:199], v[70:73]
	v_mfma_f32_16x16x32_bf16 v[74:77], v[106:109], v[200:203], v[74:77]
	v_mfma_f32_16x16x32_bf16 v[74:77], v[110:113], v[204:207], v[74:77]
	v_mfma_f32_16x16x32_bf16 v[78:81], v[114:117], v[200:203], v[78:81]
	v_mfma_f32_16x16x32_bf16 v[78:81], v[118:121], v[204:207], v[78:81]
	v_mfma_f32_16x16x32_bf16 v[82:85], v[106:109], v[208:211], v[82:85]
	v_mfma_f32_16x16x32_bf16 v[82:85], v[110:113], v[212:215], v[82:85]
	v_mfma_f32_16x16x32_bf16 v[86:89], v[114:117], v[208:211], v[86:89]
	v_mfma_f32_16x16x32_bf16 v[86:89], v[118:121], v[212:215], v[86:89]
	v_mfma_f32_16x16x32_bf16 v[90:93], v[106:109], v[216:219], v[90:93]
	v_mfma_f32_16x16x32_bf16 v[90:93], v[110:113], v[220:223], v[90:93]
	v_mfma_f32_16x16x32_bf16 v[94:97], v[114:117], v[216:219], v[94:97]
	v_mfma_f32_16x16x32_bf16 v[94:97], v[118:121], v[220:223], v[94:97]
	v_mfma_f32_16x16x32_bf16 v[34:37], v[184:187], v[192:195], v[34:37]
	v_mfma_f32_16x16x32_bf16 v[98:101], v[122:125], v[192:195], v[98:101]
	v_mfma_f32_16x16x32_bf16 v[192:195], v[188:191], v[196:199], v[34:37]
	v_mfma_f32_16x16x32_bf16 v[34:37], v[122:125], v[200:203], v[38:41]
	v_mfma_f32_16x16x32_bf16 v[224:227], v[126:129], v[196:199], v[98:101]
	v_mfma_f32_16x16x32_bf16 v[196:199], v[126:129], v[204:207], v[34:37]
	v_mfma_f32_16x16x32_bf16 v[34:37], v[184:187], v[200:203], v[42:45]
	v_mfma_f32_16x16x32_bf16 v[42:45], v[188:191], v[204:207], v[34:37]
	v_mfma_f32_16x16x32_bf16 v[34:37], v[122:125], v[208:211], v[46:49]
	v_mfma_f32_16x16x32_bf16 v[46:49], v[126:129], v[212:215], v[34:37]
	v_mfma_f32_16x16x32_bf16 v[34:37], v[184:187], v[208:211], v[50:53]
	v_mfma_f32_16x16x32_bf16 v[50:53], v[188:191], v[212:215], v[34:37]
	v_mfma_f32_16x16x32_bf16 v[34:37], v[122:125], v[216:219], v[54:57]
	v_mfma_f32_16x16x32_bf16 v[54:57], v[126:129], v[220:223], v[34:37]
	v_mfma_f32_16x16x32_bf16 v[34:37], v[184:187], v[216:219], v[58:61]
	v_mfma_f32_16x16x32_bf16 v[58:61], v[188:191], v[220:223], v[34:37]
	s_barrier
	s_mov_b32 m0, s43
	v_lshl_add_u64 v[164:165], s[24:25], 0, v[0:1]
	s_add_u32 s20, s24, 0x10000
	s_nop 1
	ds_read_b128 v[34:37], v137 offset:16384
	ds_read_b128 v[38:41], v137 offset:17408
	ds_read_b128 v[98:101], v137 offset:18432
	ds_read_b128 v[200:203], v137 offset:19456
	ds_read_b128 v[204:207], v137 offset:20480
	ds_read_b128 v[208:211], v137 offset:21504
	ds_read_b128 v[212:215], v137 offset:22528
	ds_read_b128 v[216:219], v137 offset:23552
	global_load_lds_dwordx4 v[164:165], off
	v_lshl_add_u64 v[252:253], s[24:25], 0, v[134:135]
	s_mov_b32 m0, s11
	s_addc_u32 s21, s25, 0
	global_load_lds_dwordx4 v[252:253], off
	v_lshl_add_u64 v[160:161], s[20:21], 0, v[0:1]
	s_mov_b32 m0, s41
	v_lshl_add_u64 v[174:175], s[26:27], 0, v[130:131]
	global_load_lds_dwordx4 v[160:161], off
	v_lshl_add_u64 v[160:161], s[20:21], 0, v[134:135]
	s_mov_b32 m0, s42
	v_lshl_add_u64 v[168:169], s[26:27], 0, v[132:133]
	global_load_lds_dwordx4 v[160:161], off
	s_mov_b32 m0, s34
	s_nop 0
	global_load_lds_dwordx4 v[174:175], off
	s_mov_b32 m0, s35
	s_nop 0
	global_load_lds_dwordx4 v[168:169], off
	s_waitcnt vmcnt(8)
	s_waitcnt lgkmcnt(0)
	s_barrier
	s_waitcnt lgkmcnt(0)
	v_mfma_f32_16x16x32_bf16 v[2:5], v[106:109], v[212:215], v[2:5]
	v_mfma_f32_16x16x32_bf16 v[2:5], v[110:113], v[216:219], v[2:5]
	v_mfma_f32_16x16x32_bf16 v[6:9], v[114:117], v[212:215], v[6:9]
	v_mfma_f32_16x16x32_bf16 v[6:9], v[118:121], v[216:219], v[6:9]
	v_mfma_f32_16x16x32_bf16 v[138:141], v[106:109], v[34:37], v[138:141]
	v_mfma_f32_16x16x32_bf16 v[138:141], v[110:113], v[38:41], v[138:141]
	v_mfma_f32_16x16x32_bf16 v[142:145], v[114:117], v[34:37], v[142:145]
	v_mfma_f32_16x16x32_bf16 v[142:145], v[118:121], v[38:41], v[142:145]
	v_mfma_f32_16x16x32_bf16 v[146:149], v[106:109], v[98:101], v[146:149]
	v_mfma_f32_16x16x32_bf16 v[146:149], v[110:113], v[200:203], v[146:149]
	v_mfma_f32_16x16x32_bf16 v[150:153], v[114:117], v[98:101], v[150:153]
	v_mfma_f32_16x16x32_bf16 v[150:153], v[118:121], v[200:203], v[150:153]
	v_mfma_f32_16x16x32_bf16 v[156:159], v[106:109], v[204:207], v[156:159]
	v_mfma_f32_16x16x32_bf16 v[156:159], v[110:113], v[208:211], v[156:159]
	v_mfma_f32_16x16x32_bf16 v[180:183], v[114:117], v[204:207], v[180:183]
	v_mfma_f32_16x16x32_bf16 v[180:183], v[118:121], v[208:211], v[180:183]
	v_mfma_f32_16x16x32_bf16 v[10:13], v[122:125], v[34:37], v[10:13]
	v_mfma_f32_16x16x32_bf16 v[14:17], v[184:187], v[34:37], v[14:17]
	v_mfma_f32_16x16x32_bf16 v[26:29], v[122:125], v[98:101], v[26:29]
	v_mfma_f32_16x16x32_bf16 v[30:33], v[184:187], v[98:101], v[30:33]
	v_mfma_f32_16x16x32_bf16 v[34:37], v[122:125], v[204:207], v[62:65]
	v_mfma_f32_16x16x32_bf16 v[26:29], v[126:129], v[200:203], v[26:29]
	v_mfma_f32_16x16x32_bf16 v[30:33], v[188:191], v[200:203], v[30:33]
	v_mfma_f32_16x16x32_bf16 v[200:203], v[126:129], v[208:211], v[34:37]
	v_mfma_f32_16x16x32_bf16 v[34:37], v[184:187], v[204:207], v[102:105]
	v_mfma_f32_16x16x32_bf16 v[18:21], v[122:125], v[212:215], v[18:21]
	v_mfma_f32_16x16x32_bf16 v[10:13], v[126:129], v[38:41], v[10:13]
	v_mfma_f32_16x16x32_bf16 v[14:17], v[188:191], v[38:41], v[14:17]
	v_mfma_f32_16x16x32_bf16 v[204:207], v[188:191], v[208:211], v[34:37]
	v_mfma_f32_16x16x32_bf16 v[208:211], v[126:129], v[216:219], v[18:21]
	v_mfma_f32_16x16x32_bf16 v[18:21], v[184:187], v[212:215], v[22:25]
	v_mfma_f32_16x16x32_bf16 v[184:187], v[188:191], v[216:219], v[18:21]
	s_barrier
; #define PG8_STAGE(bufoff, gbase, voff) do { _Pragma("unroll") for (int _i = 0; _i < 2; ++_i) \
;         __builtin_amdgcn_global_load_lds((const unsigned*)((const char*)(gbase) + (voff)[_i]), (LAS unsigned*)(lds + (bufoff) + ldsw + _i * 8192), 16, 0, 0); } while (0)
; #define PG8_LDA(dst, b, h) do { _Pragma("unroll") for (int m = 0; m < 4; ++m) _Pragma("unroll") for (int k = 0; k < 2; ++k) dst[m][k] = *(const LAS bf16x8*)(lds + PG8_SA(b, h) + aoff + m * 2048 + k * 1024); } while (0)
; #define PG8_MMA(ai, bj, At, Bt) do { __builtin_amdgcn_s_setprio(1); _Pragma("unroll") for (int m = 0; m < 4; ++m) _Pragma("unroll") for (int n = 0; n < 2; ++n) _Pragma("unroll") for (int k = 0; k < 2; ++k) \
;         acc[ai][bj][m][n] = __builtin_amdgcn_mfma_f32_16x16x32_bf16(Bt[n][k], At[m][k], acc[ai][bj][m][n], 0, 0, 0); __builtin_amdgcn_s_setprio(0); } while (0)
; #define PG8_WAIT_V(n) asm volatile("s_waitcnt vmcnt(" #n ")" ::: "memory")
; #define PG8_WAIT_L(n) asm volatile("s_waitcnt lgkmcnt(" #n ")" ::: "memory")
; #define PG8_BAR __builtin_amdgcn_s_barrier()
; #define PG8_SCHED __builtin_amdgcn_sched_barrier(0)
; template <class Epi, bool ALIGN_EPI>
; __device__ __forceinline__ void gemm_phase(LAS unsigned char* lds, const Gemm g, const StaticOrder& S, const Epi& E) {
;     ...
;             PG8_LDA(At, 1, 1); PG8_STAGE(PG8_SB(1, 0), b3, voffB); PG8_STAGE(PG8_SB(1, 1), b3 + hstepB, voffB); PG8_STAGE(PG8_SA(1, 0), a3, voffA);
;             PG8_WAIT_V(8); PG8_WAIT_L(0); PG8_BAR; PG8_MMA(1, 0, At, B0); PG8_MMA(1, 1, At, B1); PG8_BAR; PG8_SCHED;
;         }
;         if constexpr (ALIGN_EPI) { if (wr == 0) PG8_BAR; }
	ds_read_b128 v[62:65], v228
	ds_read_b128 v[188:191], v228 offset:1024
	ds_read_b128 v[212:215], v228 offset:2048
	ds_read_b128 v[216:219], v228 offset:3072
	ds_read_b128 v[220:223], v236
	ds_read_b128 v[228:231], v236 offset:1024
	ds_read_b128 v[232:235], v236 offset:2048
	ds_read_b128 v[236:239], v236 offset:3072
	s_add_u32 s20, s26, 0x10000
	s_addc_u32 s21, s27, 0
	s_mov_b32 m0, s36
	v_lshl_add_u64 v[34:35], s[20:21], 0, v[130:131]
	ds_read_b128 v[18:21], v137 offset:32768
	ds_read_b128 v[22:25], v137 offset:33792
	ds_read_b128 v[110:113], v137 offset:34816
	ds_read_b128 v[240:243], v137 offset:35840
	ds_read_b128 v[244:247], v137 offset:36864
	ds_read_b128 v[248:251], v137 offset:37888
	ds_read_b128 v[160:163], v137 offset:38912
	ds_read_b128 v[170:173], v137 offset:39936
	global_load_lds_dwordx4 v[34:35], off
	v_lshl_add_u64 v[34:35], s[20:21], 0, v[132:133]
	s_mov_b32 m0, s37
	s_nop 0
	global_load_lds_dwordx4 v[34:35], off
	s_waitcnt vmcnt(8)
	s_waitcnt lgkmcnt(0)
	s_barrier
	s_waitcnt lgkmcnt(0)
	v_mfma_f32_16x16x32_bf16 v[34:37], v[62:65], v[18:21], v[66:69]
	v_mfma_f32_16x16x32_bf16 v[114:117], v[188:191], v[22:25], v[34:37]
	v_mfma_f32_16x16x32_bf16 v[34:37], v[212:215], v[18:21], v[70:73]
	v_mfma_f32_16x16x32_bf16 v[118:121], v[216:219], v[22:25], v[34:37]
	v_mfma_f32_16x16x32_bf16 v[34:37], v[62:65], v[110:113], v[74:77]
	v_mfma_f32_16x16x32_bf16 v[98:101], v[188:191], v[240:243], v[34:37]
	v_mfma_f32_16x16x32_bf16 v[34:37], v[212:215], v[110:113], v[78:81]
	v_mfma_f32_16x16x32_bf16 v[102:105], v[216:219], v[240:243], v[34:37]
	v_mfma_f32_16x16x32_bf16 v[34:37], v[62:65], v[244:247], v[82:85]
	v_mfma_f32_16x16x32_bf16 v[66:69], v[188:191], v[248:251], v[34:37]
	v_mfma_f32_16x16x32_bf16 v[34:37], v[212:215], v[244:247], v[86:89]
	v_mfma_f32_16x16x32_bf16 v[70:73], v[216:219], v[248:251], v[34:37]
	v_mfma_f32_16x16x32_bf16 v[34:37], v[62:65], v[160:163], v[90:93]
	v_mfma_f32_16x16x32_bf16 v[38:41], v[212:215], v[160:163], v[94:97]
	v_mfma_f32_16x16x32_bf16 v[34:37], v[188:191], v[170:173], v[34:37]
	v_mfma_f32_16x16x32_bf16 v[38:41], v[216:219], v[170:173], v[38:41]
	v_mfma_f32_16x16x32_bf16 v[74:77], v[220:223], v[18:21], v[224:227]
	v_mfma_f32_16x16x32_bf16 v[18:21], v[232:235], v[18:21], v[192:195]
	v_mfma_f32_16x16x32_bf16 v[126:129], v[236:239], v[22:25], v[18:21]
	v_mfma_f32_16x16x32_bf16 v[18:21], v[220:223], v[110:113], v[196:199]
	v_mfma_f32_16x16x32_bf16 v[106:109], v[228:231], v[240:243], v[18:21]
	v_mfma_f32_16x16x32_bf16 v[18:21], v[232:235], v[110:113], v[42:45]
	v_mfma_f32_16x16x32_bf16 v[110:113], v[236:239], v[240:243], v[18:21]
	v_mfma_f32_16x16x32_bf16 v[18:21], v[220:223], v[244:247], v[46:49]
	v_mfma_f32_16x16x32_bf16 v[122:125], v[228:231], v[22:25], v[74:77]
	v_mfma_f32_16x16x32_bf16 v[74:77], v[228:231], v[248:251], v[18:21]
	v_mfma_f32_16x16x32_bf16 v[18:21], v[232:235], v[244:247], v[50:53]
	v_mfma_f32_16x16x32_bf16 v[78:81], v[236:239], v[248:251], v[18:21]
	v_mfma_f32_16x16x32_bf16 v[18:21], v[220:223], v[160:163], v[54:57]
	v_mfma_f32_16x16x32_bf16 v[42:45], v[228:231], v[170:173], v[18:21]
	v_mfma_f32_16x16x32_bf16 v[18:21], v[232:235], v[160:163], v[58:61]
	v_mfma_f32_16x16x32_bf16 v[46:49], v[236:239], v[170:173], v[18:21]
	s_barrier
	s_mov_b32 m0, s46
	s_nop 3
	v_lshl_add_u64 v[18:19], v[164:165], 0, s[94:95]
	s_add_u32 s20, s24, 0x10080
	ds_read_b128 v[58:61], v137 offset:49152
	ds_read_b128 v[94:97], v137 offset:50176
	ds_read_b128 v[160:163], v137 offset:51200
	ds_read_b128 v[170:173], v137 offset:52224
	ds_read_b128 v[192:195], v137 offset:53248
	ds_read_b128 v[196:199], v137 offset:54272
	ds_read_b128 v[224:227], v137 offset:55296
	ds_read_b128 v[240:243], v137 offset:56320
	global_load_lds_dwordx4 v[18:19], off
	v_lshl_add_u64 v[18:19], v[252:253], 0, s[94:95]
	s_mov_b32 m0, s44
	s_addc_u32 s21, s25, 0
	global_load_lds_dwordx4 v[18:19], off
	v_lshl_add_u64 v[18:19], s[20:21], 0, v[0:1]
	s_mov_b32 m0, s22
	s_nop 0
	global_load_lds_dwordx4 v[18:19], off
	v_lshl_add_u64 v[18:19], s[20:21], 0, v[134:135]
	s_mov_b32 m0, s23
	s_nop 0
	global_load_lds_dwordx4 v[18:19], off
	v_lshl_add_u64 v[18:19], v[174:175], 0, s[94:95]
	s_mov_b32 m0, s38
	s_nop 0
	global_load_lds_dwordx4 v[18:19], off
	v_lshl_add_u64 v[18:19], v[168:169], 0, s[94:95]
	s_mov_b32 m0, s39
	s_nop 0
	global_load_lds_dwordx4 v[18:19], off
	s_waitcnt vmcnt(8)
	s_waitcnt lgkmcnt(0)
	s_barrier
	s_waitcnt lgkmcnt(0)
	v_mfma_f32_16x16x32_bf16 v[18:21], v[62:65], v[58:61], v[138:141]
	v_mfma_f32_16x16x32_bf16 v[82:85], v[188:191], v[94:97], v[18:21]
	v_mfma_f32_16x16x32_bf16 v[18:21], v[212:215], v[58:61], v[142:145]
	v_mfma_f32_16x16x32_bf16 v[86:89], v[216:219], v[94:97], v[18:21]
	v_mfma_f32_16x16x32_bf16 v[18:21], v[62:65], v[160:163], v[146:149]
	v_mfma_f32_16x16x32_bf16 v[50:53], v[188:191], v[170:173], v[18:21]
	v_mfma_f32_16x16x32_bf16 v[18:21], v[212:215], v[160:163], v[150:153]
	v_mfma_f32_16x16x32_bf16 v[54:57], v[216:219], v[170:173], v[18:21]
	v_mfma_f32_16x16x32_bf16 v[18:21], v[62:65], v[192:195], v[156:159]
	v_mfma_f32_16x16x32_bf16 v[22:25], v[212:215], v[192:195], v[180:183]
	v_mfma_f32_16x16x32_bf16 v[2:5], v[62:65], v[224:227], v[2:5]
	v_mfma_f32_16x16x32_bf16 v[6:9], v[212:215], v[224:227], v[6:9]
	v_mfma_f32_16x16x32_bf16 v[18:21], v[188:191], v[196:199], v[18:21]
	v_mfma_f32_16x16x32_bf16 v[22:25], v[216:219], v[196:199], v[22:25]
	v_mfma_f32_16x16x32_bf16 v[2:5], v[188:191], v[240:243], v[2:5]
	v_mfma_f32_16x16x32_bf16 v[6:9], v[216:219], v[240:243], v[6:9]
	v_mfma_f32_16x16x32_bf16 v[10:13], v[220:223], v[58:61], v[10:13]
	v_mfma_f32_16x16x32_bf16 v[90:93], v[228:231], v[94:97], v[10:13]
	v_mfma_f32_16x16x32_bf16 v[10:13], v[232:235], v[58:61], v[14:17]
	v_mfma_f32_16x16x32_bf16 v[94:97], v[236:239], v[94:97], v[10:13]
	v_mfma_f32_16x16x32_bf16 v[10:13], v[220:223], v[160:163], v[26:29]
	v_mfma_f32_16x16x32_bf16 v[58:61], v[228:231], v[170:173], v[10:13]
	v_mfma_f32_16x16x32_bf16 v[10:13], v[232:235], v[160:163], v[30:33]
	v_mfma_f32_16x16x32_bf16 v[62:65], v[236:239], v[170:173], v[10:13]
	v_mfma_f32_16x16x32_bf16 v[10:13], v[220:223], v[192:195], v[200:203]
	v_mfma_f32_16x16x32_bf16 v[26:29], v[228:231], v[196:199], v[10:13]
	v_mfma_f32_16x16x32_bf16 v[10:13], v[232:235], v[192:195], v[204:207]
	v_mfma_f32_16x16x32_bf16 v[30:33], v[236:239], v[196:199], v[10:13]
	v_mfma_f32_16x16x32_bf16 v[10:13], v[220:223], v[224:227], v[208:211]
	v_mfma_f32_16x16x32_bf16 v[14:17], v[232:235], v[224:227], v[184:187]
	v_mfma_f32_16x16x32_bf16 v[10:13], v[228:231], v[240:243], v[10:13]
	v_mfma_f32_16x16x32_bf16 v[14:17], v[236:239], v[240:243], v[14:17]
	s_barrier
	s_andn2_b64 vcc, exec, s[2:3]
	s_cbranch_vccnz .LBB0_289
	s_barrier

; #define PG8_STAGE(bufoff, gbase, voff) do { _Pragma("unroll") for (int _i = 0; _i < 2; ++_i) \
;         __builtin_amdgcn_global_load_lds((const unsigned*)((const char*)(gbase) + (voff)[_i]), (LAS unsigned*)(lds + (bufoff) + ldsw + _i * 8192), 16, 0, 0); } while (0)
; #define PG8_LDA(dst, b, h) do { _Pragma("unroll") for (int m = 0; m < 4; ++m) _Pragma("unroll") for (int k = 0; k < 2; ++k) dst[m][k] = *(const LAS bf16x8*)(lds + PG8_SA(b, h) + aoff + m * 2048 + k * 1024); } while (0)
; #define PG8_LDB(dst, b, h) do { _Pragma("unroll") for (int n = 0; n < 2; ++n) _Pragma("unroll") for (int k = 0; k < 2; ++k) dst[n][k] = *(const LAS bf16x8*)(lds + PG8_SB(b, h) + boff + n * 2048 + k * 1024); } while (0)
; #define PG8_MMA(ai, bj, At, Bt) do { __builtin_amdgcn_s_setprio(1); _Pragma("unroll") for (int m = 0; m < 4; ++m) _Pragma("unroll") for (int n = 0; n < 2; ++n) _Pragma("unroll") for (int k = 0; k < 2; ++k) \
;         acc[ai][bj][m][n] = __builtin_amdgcn_mfma_f32_16x16x32_bf16(Bt[n][k], At[m][k], acc[ai][bj][m][n], 0, 0, 0); __builtin_amdgcn_s_setprio(0); } while (0)
; #define PG8_WAIT_V(n) asm volatile("s_waitcnt vmcnt(" #n ")" ::: "memory")
; #define PG8_WAIT_L(n) asm volatile("s_waitcnt lgkmcnt(" #n ")" ::: "memory")
; #define PG8_BAR __builtin_amdgcn_s_barrier()
; #define PG8_SCHED __builtin_amdgcn_sched_barrier(0)
; template <class Epi, bool ALIGN_EPI>
; __device__ __forceinline__ void gemm_phase(LAS unsigned char* lds, const Gemm g, const StaticOrder& S, const Epi& E) {
;     ...
;         for (int t = 0; t < nt; t += 2) {
;             const bool last = (t == nt - 2);
;             const char* a1 = cA + (size_t)(t + 1) * kstep;
;             const char* a2 = last ? nA : cA + (size_t)(t + 2) * kstep; const char* b2 = last ? nB : cB + (size_t)(t + 2) * kstep;
;             const char* a3 = a2 + kstep; const char* b3 = b2 + kstep;
;             PG8_LDB(B0, 0, 0); PG8_LDB(B1, 0, 1); PG8_SCHED; PG8_LDA(At, 0, 0); PG8_STAGE(PG8_SA(1, 1), a1 + hstepA, voffA);
;             PG8_WAIT_V(8); PG8_WAIT_L(0); PG8_BAR; PG8_MMA(0, 0, At, B0); PG8_MMA(0, 1, At, B1); PG8_BAR; PG8_SCHED;
;             PG8_LDA(At, 0, 1); PG8_STAGE(PG8_SB(0, 0), b2, voffB); PG8_STAGE(PG8_SB(0, 1), b2 + hstepB, voffB); PG8_STAGE(PG8_SA(0, 0), a2, voffA);
.LBB0_304:
	s_add_u32 s18, s6, 0xfffc0080
	s_addc_u32 s19, s7, -1
	s_add_i32 s41, 0, 0x10000
	s_cmp_eq_u32 s40, 12
	s_cselect_b32 s21, s1, s19
	s_cselect_b32 s20, s36, s18
	v_add_u32_e32 v152, s41, v144
	s_cselect_b32 s19, s11, s39
	s_cselect_b32 s18, s37, s38
	s_add_i32 s44, 0, 0x14000
	ds_read_b128 v[140:143], v152
	ds_read_b128 v[148:151], v152 offset:1024
	ds_read_b128 v[156:159], v152 offset:2048
	ds_read_b128 v[180:183], v152 offset:3072
	v_add_u32_e32 v152, s44, v144
	ds_read_b128 v[184:187], v152
	ds_read_b128 v[188:191], v152 offset:1024
	ds_read_b128 v[192:195], v152 offset:2048
	ds_read_b128 v[196:199], v152 offset:3072
	v_lshl_add_u64 v[152:153], s[6:7], 0, v[136:137]
	s_add_i32 m0, s25, 0xc000
	ds_read_b128 v[200:203], v146
	ds_read_b128 v[204:207], v146 offset:1024
	ds_read_b128 v[208:211], v146 offset:2048
	ds_read_b128 v[212:215], v146 offset:3072
	ds_read_b128 v[216:219], v146 offset:4096
	ds_read_b128 v[220:223], v146 offset:5120
	ds_read_b128 v[224:227], v146 offset:6144
	ds_read_b128 v[228:231], v146 offset:7168
	global_load_lds_dwordx4 v[152:153], off
	v_lshl_add_u64 v[152:153], s[6:7], 0, v[138:139]
	s_add_i32 m0, s25, 0xe000
	s_nop 0
	global_load_lds_dwordx4 v[152:153], off
	s_waitcnt vmcnt(8)
	s_waitcnt lgkmcnt(0)
	s_barrier
	s_waitcnt lgkmcnt(0)
	v_mfma_f32_16x16x32_bf16 v[126:129], v[140:143], v[200:203], v[126:129]
	v_mfma_f32_16x16x32_bf16 v[126:129], v[148:151], v[204:207], v[126:129]
	v_mfma_f32_16x16x32_bf16 v[118:121], v[156:159], v[200:203], v[118:121]
	v_mfma_f32_16x16x32_bf16 v[118:121], v[180:183], v[204:207], v[118:121]
	v_mfma_f32_16x16x32_bf16 v[110:113], v[140:143], v[208:211], v[110:113]
	v_mfma_f32_16x16x32_bf16 v[110:113], v[148:151], v[212:215], v[110:113]
	v_mfma_f32_16x16x32_bf16 v[102:105], v[156:159], v[208:211], v[102:105]
	v_mfma_f32_16x16x32_bf16 v[102:105], v[180:183], v[212:215], v[102:105]
	v_mfma_f32_16x16x32_bf16 v[94:97], v[140:143], v[216:219], v[94:97]
	v_mfma_f32_16x16x32_bf16 v[94:97], v[148:151], v[220:223], v[94:97]
	v_mfma_f32_16x16x32_bf16 v[86:89], v[156:159], v[216:219], v[86:89]
	v_mfma_f32_16x16x32_bf16 v[86:89], v[180:183], v[220:223], v[86:89]
	v_mfma_f32_16x16x32_bf16 v[78:81], v[140:143], v[224:227], v[78:81]
	v_mfma_f32_16x16x32_bf16 v[78:81], v[148:151], v[228:231], v[78:81]
	v_mfma_f32_16x16x32_bf16 v[70:73], v[156:159], v[224:227], v[70:73]
	v_mfma_f32_16x16x32_bf16 v[70:73], v[180:183], v[228:231], v[70:73]
	v_mfma_f32_16x16x32_bf16 v[122:125], v[184:187], v[200:203], v[122:125]
	v_mfma_f32_16x16x32_bf16 v[122:125], v[188:191], v[204:207], v[122:125]
	v_mfma_f32_16x16x32_bf16 v[114:117], v[192:195], v[200:203], v[114:117]
	v_mfma_f32_16x16x32_bf16 v[114:117], v[196:199], v[204:207], v[114:117]
	v_mfma_f32_16x16x32_bf16 v[106:109], v[184:187], v[208:211], v[106:109]
	v_mfma_f32_16x16x32_bf16 v[106:109], v[188:191], v[212:215], v[106:109]
	v_mfma_f32_16x16x32_bf16 v[98:101], v[192:195], v[208:211], v[98:101]
	v_mfma_f32_16x16x32_bf16 v[98:101], v[196:199], v[212:215], v[98:101]
	v_mfma_f32_16x16x32_bf16 v[90:93], v[184:187], v[216:219], v[90:93]
	v_mfma_f32_16x16x32_bf16 v[90:93], v[188:191], v[220:223], v[90:93]
	v_mfma_f32_16x16x32_bf16 v[82:85], v[192:195], v[216:219], v[82:85]
	v_mfma_f32_16x16x32_bf16 v[82:85], v[196:199], v[220:223], v[82:85]
	v_mfma_f32_16x16x32_bf16 v[74:77], v[184:187], v[224:227], v[74:77]
	v_mfma_f32_16x16x32_bf16 v[74:77], v[188:191], v[228:231], v[74:77]
	v_mfma_f32_16x16x32_bf16 v[66:69], v[192:195], v[224:227], v[66:69]
	v_mfma_f32_16x16x32_bf16 v[66:69], v[196:199], v[228:231], v[66:69]
	s_barrier
	s_add_i32 s41, s41, s24
	v_lshl_add_u64 v[152:153], s[18:19], 0, v[0:1]
	s_mov_b32 m0, s41
	ds_read_b128 v[200:203], v146 offset:16384
	ds_read_b128 v[204:207], v146 offset:17408
	ds_read_b128 v[208:211], v146 offset:18432
	ds_read_b128 v[212:215], v146 offset:19456
	ds_read_b128 v[216:219], v146 offset:20480
	ds_read_b128 v[220:223], v146 offset:21504
	ds_read_b128 v[224:227], v146 offset:22528
	ds_read_b128 v[228:231], v146 offset:23552
	global_load_lds_dwordx4 v[152:153], off
	s_add_i32 m0, s41, 0x2000
	s_add_u32 s42, s18, 0x40000
	v_lshl_add_u64 v[160:161], s[18:19], 0, v[130:131]
	s_addc_u32 s43, s19, 0
	s_add_i32 s41, s44, s24
	global_load_lds_dwordx4 v[160:161], off
	v_lshl_add_u64 v[162:163], s[42:43], 0, v[0:1]
	s_mov_b32 m0, s41
	v_lshl_add_u64 v[170:171], s[20:21], 0, v[132:133]
	global_load_lds_dwordx4 v[162:163], off
	v_lshl_add_u64 v[162:163], s[42:43], 0, v[130:131]
	s_add_i32 m0, s41, 0x2000
	s_nop 0
	global_load_lds_dwordx4 v[162:163], off
	v_lshl_add_u64 v[162:163], s[20:21], 0, v[134:135]
	s_mov_b32 m0, s25
	s_nop 0
	global_load_lds_dwordx4 v[162:163], off
	s_mov_b32 m0, s26
	s_nop 0
	global_load_lds_dwordx4 v[170:171], off
	s_waitcnt vmcnt(8)
	s_waitcnt lgkmcnt(0)
	s_barrier
; #define PG8_STAGE(bufoff, gbase, voff) do { _Pragma("unroll") for (int _i = 0; _i < 2; ++_i) \
;         __builtin_amdgcn_global_load_lds((const unsigned*)((const char*)(gbase) + (voff)[_i]), (LAS unsigned*)(lds + (bufoff) + ldsw + _i * 8192), 16, 0, 0); } while (0)
; #define PG8_LDA(dst, b, h) do { _Pragma("unroll") for (int m = 0; m < 4; ++m) _Pragma("unroll") for (int k = 0; k < 2; ++k) dst[m][k] = *(const LAS bf16x8*)(lds + PG8_SA(b, h) + aoff + m * 2048 + k * 1024); } while (0)
; #define PG8_LDB(dst, b, h) do { _Pragma("unroll") for (int n = 0; n < 2; ++n) _Pragma("unroll") for (int k = 0; k < 2; ++k) dst[n][k] = *(const LAS bf16x8*)(lds + PG8_SB(b, h) + boff + n * 2048 + k * 1024); } while (0)
; #define PG8_MMA(ai, bj, At, Bt) do { __builtin_amdgcn_s_setprio(1); _Pragma("unroll") for (int m = 0; m < 4; ++m) _Pragma("unroll") for (int n = 0; n < 2; ++n) _Pragma("unroll") for (int k = 0; k < 2; ++k) \
;         acc[ai][bj][m][n] = __builtin_amdgcn_mfma_f32_16x16x32_bf16(Bt[n][k], At[m][k], acc[ai][bj][m][n], 0, 0, 0); __builtin_amdgcn_s_setprio(0); } while (0)
; #define PG8_WAIT_V(n) asm volatile("s_waitcnt vmcnt(" #n ")" ::: "memory")
; #define PG8_WAIT_L(n) asm volatile("s_waitcnt lgkmcnt(" #n ")" ::: "memory")
; #define PG8_BAR __builtin_amdgcn_s_barrier()
; #define PG8_SCHED __builtin_amdgcn_sched_barrier(0)
; template <class Epi, bool ALIGN_EPI>
; __device__ __forceinline__ void gemm_phase(LAS unsigned char* lds, const Gemm g, const StaticOrder& S, const Epi& E) {
;     ...
;             PG8_WAIT_V(8); PG8_WAIT_L(0); PG8_BAR; PG8_MMA(1, 0, At, B0); PG8_MMA(1, 1, At, B1); PG8_BAR; PG8_SCHED;
;             PG8_LDB(B0, 1, 0); PG8_LDB(B1, 1, 1); PG8_SCHED; PG8_LDA(At, 1, 0); PG8_STAGE(PG8_SA(0, 1), a2 + hstepA, voffA);
;             PG8_WAIT_V(8); PG8_WAIT_L(0); PG8_BAR; PG8_MMA(0, 0, At, B0); PG8_MMA(0, 1, At, B1); PG8_BAR; PG8_SCHED;
	s_waitcnt lgkmcnt(0)
	v_mfma_f32_16x16x32_bf16 v[62:65], v[140:143], v[200:203], v[62:65]
	v_mfma_f32_16x16x32_bf16 v[62:65], v[148:151], v[204:207], v[62:65]
	v_mfma_f32_16x16x32_bf16 v[54:57], v[156:159], v[200:203], v[54:57]
	v_mfma_f32_16x16x32_bf16 v[54:57], v[180:183], v[204:207], v[54:57]
	v_mfma_f32_16x16x32_bf16 v[46:49], v[140:143], v[208:211], v[46:49]
	v_mfma_f32_16x16x32_bf16 v[46:49], v[148:151], v[212:215], v[46:49]
	v_mfma_f32_16x16x32_bf16 v[38:41], v[156:159], v[208:211], v[38:41]
	v_mfma_f32_16x16x32_bf16 v[38:41], v[180:183], v[212:215], v[38:41]
	v_mfma_f32_16x16x32_bf16 v[30:33], v[140:143], v[216:219], v[30:33]
	v_mfma_f32_16x16x32_bf16 v[30:33], v[148:151], v[220:223], v[30:33]
	v_mfma_f32_16x16x32_bf16 v[22:25], v[156:159], v[216:219], v[22:25]
	v_mfma_f32_16x16x32_bf16 v[22:25], v[180:183], v[220:223], v[22:25]
	v_mfma_f32_16x16x32_bf16 v[14:17], v[140:143], v[224:227], v[14:17]
	v_mfma_f32_16x16x32_bf16 v[14:17], v[148:151], v[228:231], v[14:17]
	v_mfma_f32_16x16x32_bf16 v[6:9], v[156:159], v[224:227], v[6:9]
	v_mfma_f32_16x16x32_bf16 v[6:9], v[180:183], v[228:231], v[6:9]
	v_mfma_f32_16x16x32_bf16 v[58:61], v[184:187], v[200:203], v[58:61]
	v_mfma_f32_16x16x32_bf16 v[58:61], v[188:191], v[204:207], v[58:61]
	v_mfma_f32_16x16x32_bf16 v[50:53], v[192:195], v[200:203], v[50:53]
	v_mfma_f32_16x16x32_bf16 v[50:53], v[196:199], v[204:207], v[50:53]
	v_mfma_f32_16x16x32_bf16 v[42:45], v[184:187], v[208:211], v[42:45]
	v_mfma_f32_16x16x32_bf16 v[42:45], v[188:191], v[212:215], v[42:45]
	v_mfma_f32_16x16x32_bf16 v[34:37], v[192:195], v[208:211], v[34:37]
	v_mfma_f32_16x16x32_bf16 v[34:37], v[196:199], v[212:215], v[34:37]
	v_mfma_f32_16x16x32_bf16 v[26:29], v[184:187], v[216:219], v[26:29]
	v_mfma_f32_16x16x32_bf16 v[26:29], v[188:191], v[220:223], v[26:29]
	v_mfma_f32_16x16x32_bf16 v[18:21], v[192:195], v[216:219], v[18:21]
	v_mfma_f32_16x16x32_bf16 v[18:21], v[196:199], v[220:223], v[18:21]
	v_mfma_f32_16x16x32_bf16 v[10:13], v[184:187], v[224:227], v[10:13]
	v_mfma_f32_16x16x32_bf16 v[10:13], v[188:191], v[228:231], v[10:13]
	v_mfma_f32_16x16x32_bf16 v[2:5], v[192:195], v[224:227], v[2:5]
	v_mfma_f32_16x16x32_bf16 v[2:5], v[196:199], v[228:231], v[2:5]
	s_barrier
	s_add_i32 s41, 0, 0x18000
	v_add_u32_e32 v164, s41, v144
	s_add_i32 s42, 0, 0x1c000
	ds_read_b128 v[140:143], v164
	ds_read_b128 v[148:151], v164 offset:1024
	ds_read_b128 v[156:159], v164 offset:2048
	ds_read_b128 v[180:183], v164 offset:3072
	v_add_u32_e32 v164, s42, v144
	ds_read_b128 v[184:187], v164
	ds_read_b128 v[188:191], v164 offset:1024
	ds_read_b128 v[192:195], v164 offset:2048
	ds_read_b128 v[196:199], v164 offset:3072
	s_add_u32 s20, s20, 0x40000
	s_addc_u32 s21, s21, 0
	s_mov_b32 m0, s27
	v_lshl_add_u64 v[172:173], s[20:21], 0, v[134:135]
	ds_read_b128 v[200:203], v146 offset:32768
	ds_read_b128 v[204:207], v146 offset:33792
	ds_read_b128 v[208:211], v146 offset:34816
	ds_read_b128 v[212:215], v146 offset:35840
	ds_read_b128 v[216:219], v146 offset:36864
	ds_read_b128 v[220:223], v146 offset:37888
	ds_read_b128 v[224:227], v146 offset:38912
	ds_read_b128 v[228:231], v146 offset:39936
	global_load_lds_dwordx4 v[172:173], off
	v_lshl_add_u64 v[172:173], s[20:21], 0, v[132:133]
	s_mov_b32 m0, s28
	s_nop 0
	global_load_lds_dwordx4 v[172:173], off
	s_waitcnt vmcnt(8)
	s_waitcnt lgkmcnt(0)
	s_barrier
	s_waitcnt lgkmcnt(0)
	v_mfma_f32_16x16x32_bf16 v[126:129], v[140:143], v[200:203], v[126:129]
	v_mfma_f32_16x16x32_bf16 v[126:129], v[148:151], v[204:207], v[126:129]
	v_mfma_f32_16x16x32_bf16 v[118:121], v[156:159], v[200:203], v[118:121]
	v_mfma_f32_16x16x32_bf16 v[118:121], v[180:183], v[204:207], v[118:121]
	v_mfma_f32_16x16x32_bf16 v[110:113], v[140:143], v[208:211], v[110:113]
	v_mfma_f32_16x16x32_bf16 v[110:113], v[148:151], v[212:215], v[110:113]
	v_mfma_f32_16x16x32_bf16 v[102:105], v[156:159], v[208:211], v[102:105]
	v_mfma_f32_16x16x32_bf16 v[102:105], v[180:183], v[212:215], v[102:105]
	v_mfma_f32_16x16x32_bf16 v[94:97], v[140:143], v[216:219], v[94:97]
	v_mfma_f32_16x16x32_bf16 v[94:97], v[148:151], v[220:223], v[94:97]
	v_mfma_f32_16x16x32_bf16 v[86:89], v[156:159], v[216:219], v[86:89]
	v_mfma_f32_16x16x32_bf16 v[86:89], v[180:183], v[220:223], v[86:89]
	v_mfma_f32_16x16x32_bf16 v[78:81], v[140:143], v[224:227], v[78:81]
	v_mfma_f32_16x16x32_bf16 v[78:81], v[148:151], v[228:231], v[78:81]
	v_mfma_f32_16x16x32_bf16 v[70:73], v[156:159], v[224:227], v[70:73]
	v_mfma_f32_16x16x32_bf16 v[70:73], v[180:183], v[228:231], v[70:73]
	v_mfma_f32_16x16x32_bf16 v[122:125], v[184:187], v[200:203], v[122:125]
	v_mfma_f32_16x16x32_bf16 v[122:125], v[188:191], v[204:207], v[122:125]
	v_mfma_f32_16x16x32_bf16 v[114:117], v[192:195], v[200:203], v[114:117]
	v_mfma_f32_16x16x32_bf16 v[114:117], v[196:199], v[204:207], v[114:117]
	v_mfma_f32_16x16x32_bf16 v[106:109], v[184:187], v[208:211], v[106:109]
	v_mfma_f32_16x16x32_bf16 v[106:109], v[188:191], v[212:215], v[106:109]
	v_mfma_f32_16x16x32_bf16 v[98:101], v[192:195], v[208:211], v[98:101]
	v_mfma_f32_16x16x32_bf16 v[98:101], v[196:199], v[212:215], v[98:101]
	v_mfma_f32_16x16x32_bf16 v[90:93], v[184:187], v[216:219], v[90:93]
	v_mfma_f32_16x16x32_bf16 v[90:93], v[188:191], v[220:223], v[90:93]
	v_mfma_f32_16x16x32_bf16 v[82:85], v[192:195], v[216:219], v[82:85]
	v_mfma_f32_16x16x32_bf16 v[82:85], v[196:199], v[220:223], v[82:85]
	v_mfma_f32_16x16x32_bf16 v[74:77], v[184:187], v[224:227], v[74:77]
	v_mfma_f32_16x16x32_bf16 v[74:77], v[188:191], v[228:231], v[74:77]
	v_mfma_f32_16x16x32_bf16 v[66:69], v[192:195], v[224:227], v[66:69]
	v_mfma_f32_16x16x32_bf16 v[66:69], v[196:199], v[228:231], v[66:69]
	s_barrier
; #define PG8_STAGE(bufoff, gbase, voff) do { _Pragma("unroll") for (int _i = 0; _i < 2; ++_i) \
;         __builtin_amdgcn_global_load_lds((const unsigned*)((const char*)(gbase) + (voff)[_i]), (LAS unsigned*)(lds + (bufoff) + ldsw + _i * 8192), 16, 0, 0); } while (0)
; #define PG8_LDA(dst, b, h) do { _Pragma("unroll") for (int m = 0; m < 4; ++m) _Pragma("unroll") for (int k = 0; k < 2; ++k) dst[m][k] = *(const LAS bf16x8*)(lds + PG8_SA(b, h) + aoff + m * 2048 + k * 1024); } while (0)
; #define PG8_MMA(ai, bj, At, Bt) do { __builtin_amdgcn_s_setprio(1); _Pragma("unroll") for (int m = 0; m < 4; ++m) _Pragma("unroll") for (int n = 0; n < 2; ++n) _Pragma("unroll") for (int k = 0; k < 2; ++k) \
;         acc[ai][bj][m][n] = __builtin_amdgcn_mfma_f32_16x16x32_bf16(Bt[n][k], At[m][k], acc[ai][bj][m][n], 0, 0, 0); __builtin_amdgcn_s_setprio(0); } while (0)
; #define PG8_WAIT_V(n) asm volatile("s_waitcnt vmcnt(" #n ")" ::: "memory")
; #define PG8_WAIT_L(n) asm volatile("s_waitcnt lgkmcnt(" #n ")" ::: "memory")
; #define PG8_BAR __builtin_amdgcn_s_barrier()
; #define PG8_SCHED __builtin_amdgcn_sched_barrier(0)
; template <class Epi, bool ALIGN_EPI>
; __device__ __forceinline__ void gemm_phase(LAS unsigned char* lds, const Gemm g, const StaticOrder& S, const Epi& E) {
;     ...
;             PG8_LDA(At, 1, 1); PG8_STAGE(PG8_SB(1, 0), b3, voffB); PG8_STAGE(PG8_SB(1, 1), b3 + hstepB, voffB); PG8_STAGE(PG8_SA(1, 0), a3, voffA);
;             PG8_WAIT_V(8); PG8_WAIT_L(0); PG8_BAR; PG8_MMA(1, 0, At, B0); PG8_MMA(1, 1, At, B1); PG8_BAR; PG8_SCHED;
	s_add_i32 s20, s41, s24
	v_lshl_add_u64 v[152:153], v[152:153], 0, s[94:95]
	s_mov_b32 m0, s20
	ds_read_b128 v[200:203], v146 offset:49152
	ds_read_b128 v[204:207], v146 offset:50176
	ds_read_b128 v[208:211], v146 offset:51200
	ds_read_b128 v[212:215], v146 offset:52224
	ds_read_b128 v[216:219], v146 offset:53248
	ds_read_b128 v[220:223], v146 offset:54272
	ds_read_b128 v[224:227], v146 offset:55296
	ds_read_b128 v[228:231], v146 offset:56320
	global_load_lds_dwordx4 v[152:153], off
	s_add_i32 m0, s20, 0x2000
	s_add_u32 s18, s18, 0x40080
	v_lshl_add_u64 v[152:153], v[160:161], 0, s[94:95]
	s_addc_u32 s19, s19, 0
	s_add_i32 s20, s42, s24
	global_load_lds_dwordx4 v[152:153], off
	v_lshl_add_u64 v[152:153], s[18:19], 0, v[0:1]
	s_mov_b32 m0, s20
	s_nop 0
	global_load_lds_dwordx4 v[152:153], off
	v_lshl_add_u64 v[152:153], s[18:19], 0, v[130:131]
	s_add_i32 m0, s20, 0x2000
	s_nop 0
	global_load_lds_dwordx4 v[152:153], off
	v_lshl_add_u64 v[152:153], v[162:163], 0, s[94:95]
	s_mov_b32 m0, s4
	s_nop 0
	global_load_lds_dwordx4 v[152:153], off
	v_lshl_add_u64 v[152:153], v[170:171], 0, s[94:95]
	s_mov_b32 m0, s29
	s_nop 0
	global_load_lds_dwordx4 v[152:153], off
	s_waitcnt vmcnt(8)
	s_waitcnt lgkmcnt(0)
	s_barrier
	s_waitcnt lgkmcnt(0)
	v_mfma_f32_16x16x32_bf16 v[62:65], v[140:143], v[200:203], v[62:65]
	v_mfma_f32_16x16x32_bf16 v[62:65], v[148:151], v[204:207], v[62:65]
	v_mfma_f32_16x16x32_bf16 v[54:57], v[156:159], v[200:203], v[54:57]
	v_mfma_f32_16x16x32_bf16 v[54:57], v[180:183], v[204:207], v[54:57]
	v_mfma_f32_16x16x32_bf16 v[46:49], v[140:143], v[208:211], v[46:49]
	v_mfma_f32_16x16x32_bf16 v[46:49], v[148:151], v[212:215], v[46:49]
	v_mfma_f32_16x16x32_bf16 v[38:41], v[156:159], v[208:211], v[38:41]
	v_mfma_f32_16x16x32_bf16 v[38:41], v[180:183], v[212:215], v[38:41]
	v_mfma_f32_16x16x32_bf16 v[30:33], v[140:143], v[216:219], v[30:33]
	v_mfma_f32_16x16x32_bf16 v[30:33], v[148:151], v[220:223], v[30:33]
	v_mfma_f32_16x16x32_bf16 v[22:25], v[156:159], v[216:219], v[22:25]
	v_mfma_f32_16x16x32_bf16 v[22:25], v[180:183], v[220:223], v[22:25]
	v_mfma_f32_16x16x32_bf16 v[14:17], v[140:143], v[224:227], v[14:17]
	v_mfma_f32_16x16x32_bf16 v[14:17], v[148:151], v[228:231], v[14:17]
	v_mfma_f32_16x16x32_bf16 v[6:9], v[156:159], v[224:227], v[6:9]
	v_mfma_f32_16x16x32_bf16 v[6:9], v[180:183], v[228:231], v[6:9]
	v_mfma_f32_16x16x32_bf16 v[58:61], v[184:187], v[200:203], v[58:61]
	v_mfma_f32_16x16x32_bf16 v[58:61], v[188:191], v[204:207], v[58:61]
	v_mfma_f32_16x16x32_bf16 v[50:53], v[192:195], v[200:203], v[50:53]
	v_mfma_f32_16x16x32_bf16 v[50:53], v[196:199], v[204:207], v[50:53]
	v_mfma_f32_16x16x32_bf16 v[42:45], v[184:187], v[208:211], v[42:45]
	v_mfma_f32_16x16x32_bf16 v[42:45], v[188:191], v[212:215], v[42:45]
	v_mfma_f32_16x16x32_bf16 v[34:37], v[192:195], v[208:211], v[34:37]
	v_mfma_f32_16x16x32_bf16 v[34:37], v[196:199], v[212:215], v[34:37]
	v_mfma_f32_16x16x32_bf16 v[26:29], v[184:187], v[216:219], v[26:29]
	v_mfma_f32_16x16x32_bf16 v[26:29], v[188:191], v[220:223], v[26:29]
	v_mfma_f32_16x16x32_bf16 v[18:21], v[192:195], v[216:219], v[18:21]
	v_mfma_f32_16x16x32_bf16 v[18:21], v[196:199], v[220:223], v[18:21]
	v_mfma_f32_16x16x32_bf16 v[10:13], v[184:187], v[224:227], v[10:13]
	v_mfma_f32_16x16x32_bf16 v[10:13], v[188:191], v[228:231], v[10:13]
	v_mfma_f32_16x16x32_bf16 v[2:5], v[192:195], v[224:227], v[2:5]
	v_mfma_f32_16x16x32_bf16 v[2:5], v[196:199], v[228:231], v[2:5]
	s_cmp_lg_u32 s40, 12
	s_cbranch_scc1 .Ltail_bar_8
	s_cmp_eq_u64 s[8:9], 0
	s_cbranch_scc1 .Ltail_skip_8

; #define PG8_STAGE(bufoff, gbase, voff) do { _Pragma("unroll") for (int _i = 0; _i < 2; ++_i) \
;         __builtin_amdgcn_global_load_lds((const unsigned*)((const char*)(gbase) + (voff)[_i]), (LAS unsigned*)(lds + (bufoff) + ldsw + _i * 8192), 16, 0, 0); } while (0)
; #define PG8_LDA(dst, b, h) do { _Pragma("unroll") for (int m = 0; m < 4; ++m) _Pragma("unroll") for (int k = 0; k < 2; ++k) dst[m][k] = *(const LAS bf16x8*)(lds + PG8_SA(b, h) + aoff + m * 2048 + k * 1024); } while (0)
; #define PG8_LDB(dst, b, h) do { _Pragma("unroll") for (int n = 0; n < 2; ++n) _Pragma("unroll") for (int k = 0; k < 2; ++k) dst[n][k] = *(const LAS bf16x8*)(lds + PG8_SB(b, h) + boff + n * 2048 + k * 1024); } while (0)
; #define PG8_MMA(ai, bj, At, Bt) do { __builtin_amdgcn_s_setprio(1); _Pragma("unroll") for (int m = 0; m < 4; ++m) _Pragma("unroll") for (int n = 0; n < 2; ++n) _Pragma("unroll") for (int k = 0; k < 2; ++k) \
;         acc[ai][bj][m][n] = __builtin_amdgcn_mfma_f32_16x16x32_bf16(Bt[n][k], At[m][k], acc[ai][bj][m][n], 0, 0, 0); __builtin_amdgcn_s_setprio(0); } while (0)
; #define PG8_WAIT_V(n) asm volatile("s_waitcnt vmcnt(" #n ")" ::: "memory")
; #define PG8_WAIT_L(n) asm volatile("s_waitcnt lgkmcnt(" #n ")" ::: "memory")
; #define PG8_BAR __builtin_amdgcn_s_barrier()
; #define PG8_SCHED __builtin_amdgcn_sched_barrier(0)
; template <class Epi, bool ALIGN_EPI>
; __device__ __forceinline__ void gemm_phase(LAS unsigned char* lds, const Gemm g, const StaticOrder& S, const Epi& E) {
;     ...
;         for (int t = 0; t < nt; t += 2) {
;             const bool last = (t == nt - 2);
;             const char* a1 = cA + (size_t)(t + 1) * kstep;
;             const char* a2 = last ? nA : cA + (size_t)(t + 2) * kstep; const char* b2 = last ? nB : cB + (size_t)(t + 2) * kstep;
;             const char* a3 = a2 + kstep; const char* b3 = b2 + kstep;
;             PG8_LDB(B0, 0, 0); PG8_LDB(B1, 0, 1); PG8_SCHED; PG8_LDA(At, 0, 0); PG8_STAGE(PG8_SA(1, 1), a1 + hstepA, voffA);
;             PG8_WAIT_V(8); PG8_WAIT_L(0); PG8_BAR; PG8_MMA(0, 0, At, B0); PG8_MMA(0, 1, At, B1); PG8_BAR; PG8_SCHED;
;             PG8_LDA(At, 0, 1); PG8_STAGE(PG8_SB(0, 0), b2, voffB); PG8_STAGE(PG8_SB(0, 1), b2 + hstepB, voffB); PG8_STAGE(PG8_SA(0, 0), a2, voffA);
.LBB0_338:
	s_add_u32 s10, s8, 0x100
	s_addc_u32 s11, s9, 0
	s_add_i32 s42, 0, 0x10000
	s_cmp_eq_u32 s41, 12
	s_cselect_b32 s25, s17, s11
	s_cselect_b32 s24, s16, s10
	v_add_u32_e32 v144, s42, v146
	s_cselect_b32 s23, s15, s40
	s_cselect_b32 s22, s21, s39
	s_add_i32 s43, 0, 0x14000
	ds_read_b128 v[140:143], v144
	ds_read_b128 v[148:151], v144 offset:1024
	ds_read_b128 v[156:159], v144 offset:2048
	ds_read_b128 v[180:183], v144 offset:3072
	v_add_u32_e32 v144, s43, v146
	ds_read_b128 v[184:187], v144
	ds_read_b128 v[188:191], v144 offset:1024
	ds_read_b128 v[192:195], v144 offset:2048
	ds_read_b128 v[196:199], v144 offset:3072
	v_lshl_add_u64 v[144:145], s[8:9], 0, v[136:137]
	s_add_i32 m0, s29, 0xc000
	ds_read_b128 v[200:203], v147
	ds_read_b128 v[204:207], v147 offset:1024
	ds_read_b128 v[208:211], v147 offset:2048
	ds_read_b128 v[212:215], v147 offset:3072
	ds_read_b128 v[216:219], v147 offset:4096
	ds_read_b128 v[220:223], v147 offset:5120
	ds_read_b128 v[224:227], v147 offset:6144
	ds_read_b128 v[228:231], v147 offset:7168
	global_load_lds_dwordx4 v[144:145], off
	v_lshl_add_u64 v[144:145], s[8:9], 0, v[138:139]
	s_add_i32 m0, s29, 0xe000
	s_nop 0
	global_load_lds_dwordx4 v[144:145], off
	s_waitcnt vmcnt(8)
	s_waitcnt lgkmcnt(0)
	s_barrier
	s_waitcnt lgkmcnt(0)
	v_mfma_f32_16x16x32_bf16 v[126:129], v[140:143], v[200:203], v[126:129]
	v_mfma_f32_16x16x32_bf16 v[126:129], v[148:151], v[204:207], v[126:129]
	v_mfma_f32_16x16x32_bf16 v[122:125], v[156:159], v[200:203], v[122:125]
	v_mfma_f32_16x16x32_bf16 v[122:125], v[180:183], v[204:207], v[122:125]
	v_mfma_f32_16x16x32_bf16 v[110:113], v[140:143], v[208:211], v[110:113]
	v_mfma_f32_16x16x32_bf16 v[110:113], v[148:151], v[212:215], v[110:113]
	v_mfma_f32_16x16x32_bf16 v[106:109], v[156:159], v[208:211], v[106:109]
	v_mfma_f32_16x16x32_bf16 v[106:109], v[180:183], v[212:215], v[106:109]
	v_mfma_f32_16x16x32_bf16 v[94:97], v[140:143], v[216:219], v[94:97]
	v_mfma_f32_16x16x32_bf16 v[94:97], v[148:151], v[220:223], v[94:97]
	v_mfma_f32_16x16x32_bf16 v[90:93], v[156:159], v[216:219], v[90:93]
	v_mfma_f32_16x16x32_bf16 v[90:93], v[180:183], v[220:223], v[90:93]
	v_mfma_f32_16x16x32_bf16 v[78:81], v[140:143], v[224:227], v[78:81]
	v_mfma_f32_16x16x32_bf16 v[78:81], v[148:151], v[228:231], v[78:81]
	v_mfma_f32_16x16x32_bf16 v[74:77], v[156:159], v[224:227], v[74:77]
	v_mfma_f32_16x16x32_bf16 v[74:77], v[180:183], v[228:231], v[74:77]
	v_mfma_f32_16x16x32_bf16 v[118:121], v[184:187], v[200:203], v[118:121]
	v_mfma_f32_16x16x32_bf16 v[118:121], v[188:191], v[204:207], v[118:121]
	v_mfma_f32_16x16x32_bf16 v[114:117], v[192:195], v[200:203], v[114:117]
	v_mfma_f32_16x16x32_bf16 v[114:117], v[196:199], v[204:207], v[114:117]
	v_mfma_f32_16x16x32_bf16 v[102:105], v[184:187], v[208:211], v[102:105]
	v_mfma_f32_16x16x32_bf16 v[102:105], v[188:191], v[212:215], v[102:105]
	v_mfma_f32_16x16x32_bf16 v[98:101], v[192:195], v[208:211], v[98:101]
	v_mfma_f32_16x16x32_bf16 v[98:101], v[196:199], v[212:215], v[98:101]
	v_mfma_f32_16x16x32_bf16 v[86:89], v[184:187], v[216:219], v[86:89]
	v_mfma_f32_16x16x32_bf16 v[86:89], v[188:191], v[220:223], v[86:89]
	v_mfma_f32_16x16x32_bf16 v[82:85], v[192:195], v[216:219], v[82:85]
	v_mfma_f32_16x16x32_bf16 v[82:85], v[196:199], v[220:223], v[82:85]
	v_mfma_f32_16x16x32_bf16 v[70:73], v[184:187], v[224:227], v[70:73]
	v_mfma_f32_16x16x32_bf16 v[70:73], v[188:191], v[228:231], v[70:73]
	v_mfma_f32_16x16x32_bf16 v[66:69], v[192:195], v[224:227], v[66:69]
	v_mfma_f32_16x16x32_bf16 v[66:69], v[196:199], v[228:231], v[66:69]
	s_barrier
	s_add_i32 s8, s42, s28
	v_lshl_add_u64 v[144:145], s[22:23], 0, v[0:1]
	s_mov_b32 m0, s8
	ds_read_b128 v[200:203], v147 offset:16384
	ds_read_b128 v[204:207], v147 offset:17408
	ds_read_b128 v[208:211], v147 offset:18432
	ds_read_b128 v[212:215], v147 offset:19456
	ds_read_b128 v[216:219], v147 offset:20480
	ds_read_b128 v[220:223], v147 offset:21504
	ds_read_b128 v[224:227], v147 offset:22528
	ds_read_b128 v[228:231], v147 offset:23552
	global_load_lds_dwordx4 v[144:145], off
	s_add_i32 m0, s8, 0x2000
	s_add_u32 s8, s22, 0x40000
	v_lshl_add_u64 v[152:153], s[22:23], 0, v[134:135]
	s_addc_u32 s9, s23, 0
	s_add_i32 s42, s43, s28
	global_load_lds_dwordx4 v[152:153], off
	v_lshl_add_u64 v[160:161], s[8:9], 0, v[0:1]
	s_mov_b32 m0, s42
	v_lshl_add_u64 v[162:163], s[24:25], 0, v[132:133]
	global_load_lds_dwordx4 v[160:161], off
	v_lshl_add_u64 v[160:161], s[8:9], 0, v[134:135]
	s_add_i32 m0, s42, 0x2000
	s_nop 0
	global_load_lds_dwordx4 v[160:161], off
	v_lshl_add_u64 v[160:161], s[24:25], 0, v[130:131]
	s_mov_b32 m0, s29
	s_nop 0
	global_load_lds_dwordx4 v[160:161], off
	s_mov_b32 m0, s30
	s_nop 0
	global_load_lds_dwordx4 v[162:163], off
	s_waitcnt vmcnt(8)
	s_waitcnt lgkmcnt(0)
	s_barrier
; #define PG8_STAGE(bufoff, gbase, voff) do { _Pragma("unroll") for (int _i = 0; _i < 2; ++_i) \
;         __builtin_amdgcn_global_load_lds((const unsigned*)((const char*)(gbase) + (voff)[_i]), (LAS unsigned*)(lds + (bufoff) + ldsw + _i * 8192), 16, 0, 0); } while (0)
; #define PG8_LDA(dst, b, h) do { _Pragma("unroll") for (int m = 0; m < 4; ++m) _Pragma("unroll") for (int k = 0; k < 2; ++k) dst[m][k] = *(const LAS bf16x8*)(lds + PG8_SA(b, h) + aoff + m * 2048 + k * 1024); } while (0)
; #define PG8_LDB(dst, b, h) do { _Pragma("unroll") for (int n = 0; n < 2; ++n) _Pragma("unroll") for (int k = 0; k < 2; ++k) dst[n][k] = *(const LAS bf16x8*)(lds + PG8_SB(b, h) + boff + n * 2048 + k * 1024); } while (0)
; #define PG8_MMA(ai, bj, At, Bt) do { __builtin_amdgcn_s_setprio(1); _Pragma("unroll") for (int m = 0; m < 4; ++m) _Pragma("unroll") for (int n = 0; n < 2; ++n) _Pragma("unroll") for (int k = 0; k < 2; ++k) \
;         acc[ai][bj][m][n] = __builtin_amdgcn_mfma_f32_16x16x32_bf16(Bt[n][k], At[m][k], acc[ai][bj][m][n], 0, 0, 0); __builtin_amdgcn_s_setprio(0); } while (0)
; #define PG8_WAIT_V(n) asm volatile("s_waitcnt vmcnt(" #n ")" ::: "memory")
; #define PG8_WAIT_L(n) asm volatile("s_waitcnt lgkmcnt(" #n ")" ::: "memory")
; #define PG8_BAR __builtin_amdgcn_s_barrier()
; #define PG8_SCHED __builtin_amdgcn_sched_barrier(0)
; template <class Epi, bool ALIGN_EPI>
; __device__ __forceinline__ void gemm_phase(LAS unsigned char* lds, const Gemm g, const StaticOrder& S, const Epi& E) {
;     ...
;             PG8_WAIT_V(8); PG8_WAIT_L(0); PG8_BAR; PG8_MMA(1, 0, At, B0); PG8_MMA(1, 1, At, B1); PG8_BAR; PG8_SCHED;
;             PG8_LDB(B0, 1, 0); PG8_LDB(B1, 1, 1); PG8_SCHED; PG8_LDA(At, 1, 0); PG8_STAGE(PG8_SA(0, 1), a2 + hstepA, voffA);
;             PG8_WAIT_V(8); PG8_WAIT_L(0); PG8_BAR; PG8_MMA(0, 0, At, B0); PG8_MMA(0, 1, At, B1); PG8_BAR; PG8_SCHED;
	s_waitcnt lgkmcnt(0)
	v_mfma_f32_16x16x32_bf16 v[62:65], v[140:143], v[200:203], v[62:65]
	v_mfma_f32_16x16x32_bf16 v[62:65], v[148:151], v[204:207], v[62:65]
	v_mfma_f32_16x16x32_bf16 v[58:61], v[156:159], v[200:203], v[58:61]
	v_mfma_f32_16x16x32_bf16 v[58:61], v[180:183], v[204:207], v[58:61]
	v_mfma_f32_16x16x32_bf16 v[46:49], v[140:143], v[208:211], v[46:49]
	v_mfma_f32_16x16x32_bf16 v[46:49], v[148:151], v[212:215], v[46:49]
	v_mfma_f32_16x16x32_bf16 v[42:45], v[156:159], v[208:211], v[42:45]
	v_mfma_f32_16x16x32_bf16 v[42:45], v[180:183], v[212:215], v[42:45]
	v_mfma_f32_16x16x32_bf16 v[30:33], v[140:143], v[216:219], v[30:33]
	v_mfma_f32_16x16x32_bf16 v[30:33], v[148:151], v[220:223], v[30:33]
	v_mfma_f32_16x16x32_bf16 v[26:29], v[156:159], v[216:219], v[26:29]
	v_mfma_f32_16x16x32_bf16 v[26:29], v[180:183], v[220:223], v[26:29]
	v_mfma_f32_16x16x32_bf16 v[14:17], v[140:143], v[224:227], v[14:17]
	v_mfma_f32_16x16x32_bf16 v[14:17], v[148:151], v[228:231], v[14:17]
	v_mfma_f32_16x16x32_bf16 v[10:13], v[156:159], v[224:227], v[10:13]
	v_mfma_f32_16x16x32_bf16 v[10:13], v[180:183], v[228:231], v[10:13]
	v_mfma_f32_16x16x32_bf16 v[54:57], v[184:187], v[200:203], v[54:57]
	v_mfma_f32_16x16x32_bf16 v[54:57], v[188:191], v[204:207], v[54:57]
	v_mfma_f32_16x16x32_bf16 v[50:53], v[192:195], v[200:203], v[50:53]
	v_mfma_f32_16x16x32_bf16 v[50:53], v[196:199], v[204:207], v[50:53]
	v_mfma_f32_16x16x32_bf16 v[38:41], v[184:187], v[208:211], v[38:41]
	v_mfma_f32_16x16x32_bf16 v[38:41], v[188:191], v[212:215], v[38:41]
	v_mfma_f32_16x16x32_bf16 v[34:37], v[192:195], v[208:211], v[34:37]
	v_mfma_f32_16x16x32_bf16 v[34:37], v[196:199], v[212:215], v[34:37]
	v_mfma_f32_16x16x32_bf16 v[22:25], v[184:187], v[216:219], v[22:25]
	v_mfma_f32_16x16x32_bf16 v[22:25], v[188:191], v[220:223], v[22:25]
	v_mfma_f32_16x16x32_bf16 v[18:21], v[192:195], v[216:219], v[18:21]
	v_mfma_f32_16x16x32_bf16 v[18:21], v[196:199], v[220:223], v[18:21]
	v_mfma_f32_16x16x32_bf16 v[6:9], v[184:187], v[224:227], v[6:9]
	v_mfma_f32_16x16x32_bf16 v[6:9], v[188:191], v[228:231], v[6:9]
	v_mfma_f32_16x16x32_bf16 v[2:5], v[192:195], v[224:227], v[2:5]
	v_mfma_f32_16x16x32_bf16 v[2:5], v[196:199], v[228:231], v[2:5]
	s_barrier
	s_add_i32 s42, 0, 0x18000
	v_add_u32_e32 v164, s42, v146
	s_add_i32 s43, 0, 0x1c000
	ds_read_b128 v[140:143], v164
	ds_read_b128 v[148:151], v164 offset:1024
	ds_read_b128 v[156:159], v164 offset:2048
	ds_read_b128 v[180:183], v164 offset:3072
	v_add_u32_e32 v164, s43, v146
	ds_read_b128 v[184:187], v164
	ds_read_b128 v[188:191], v164 offset:1024
	ds_read_b128 v[192:195], v164 offset:2048
	ds_read_b128 v[196:199], v164 offset:3072
	s_add_u32 s8, s24, 0x160000
	s_addc_u32 s9, s25, 0
	s_mov_b32 m0, s31
	v_lshl_add_u64 v[170:171], s[8:9], 0, v[130:131]
	ds_read_b128 v[200:203], v147 offset:32768
	ds_read_b128 v[204:207], v147 offset:33792
	ds_read_b128 v[208:211], v147 offset:34816
	ds_read_b128 v[212:215], v147 offset:35840
	ds_read_b128 v[216:219], v147 offset:36864
	ds_read_b128 v[220:223], v147 offset:37888
	ds_read_b128 v[224:227], v147 offset:38912
	ds_read_b128 v[228:231], v147 offset:39936
	global_load_lds_dwordx4 v[170:171], off
	v_lshl_add_u64 v[170:171], s[8:9], 0, v[132:133]
	s_mov_b32 m0, s34
	s_nop 0
	global_load_lds_dwordx4 v[170:171], off
	s_waitcnt vmcnt(8)
	s_waitcnt lgkmcnt(0)
	s_barrier
	s_waitcnt lgkmcnt(0)
	v_mfma_f32_16x16x32_bf16 v[126:129], v[140:143], v[200:203], v[126:129]
	v_mfma_f32_16x16x32_bf16 v[126:129], v[148:151], v[204:207], v[126:129]
	v_mfma_f32_16x16x32_bf16 v[122:125], v[156:159], v[200:203], v[122:125]
	v_mfma_f32_16x16x32_bf16 v[122:125], v[180:183], v[204:207], v[122:125]
	v_mfma_f32_16x16x32_bf16 v[110:113], v[140:143], v[208:211], v[110:113]
	v_mfma_f32_16x16x32_bf16 v[110:113], v[148:151], v[212:215], v[110:113]
	v_mfma_f32_16x16x32_bf16 v[106:109], v[156:159], v[208:211], v[106:109]
	v_mfma_f32_16x16x32_bf16 v[106:109], v[180:183], v[212:215], v[106:109]
	v_mfma_f32_16x16x32_bf16 v[94:97], v[140:143], v[216:219], v[94:97]
	v_mfma_f32_16x16x32_bf16 v[94:97], v[148:151], v[220:223], v[94:97]
	v_mfma_f32_16x16x32_bf16 v[90:93], v[156:159], v[216:219], v[90:93]
	v_mfma_f32_16x16x32_bf16 v[90:93], v[180:183], v[220:223], v[90:93]
	v_mfma_f32_16x16x32_bf16 v[78:81], v[140:143], v[224:227], v[78:81]
	v_mfma_f32_16x16x32_bf16 v[78:81], v[148:151], v[228:231], v[78:81]
	v_mfma_f32_16x16x32_bf16 v[74:77], v[156:159], v[224:227], v[74:77]
	v_mfma_f32_16x16x32_bf16 v[74:77], v[180:183], v[228:231], v[74:77]
	v_mfma_f32_16x16x32_bf16 v[118:121], v[184:187], v[200:203], v[118:121]
	v_mfma_f32_16x16x32_bf16 v[118:121], v[188:191], v[204:207], v[118:121]
	v_mfma_f32_16x16x32_bf16 v[114:117], v[192:195], v[200:203], v[114:117]
	v_mfma_f32_16x16x32_bf16 v[114:117], v[196:199], v[204:207], v[114:117]
	v_mfma_f32_16x16x32_bf16 v[102:105], v[184:187], v[208:211], v[102:105]
	v_mfma_f32_16x16x32_bf16 v[102:105], v[188:191], v[212:215], v[102:105]
	v_mfma_f32_16x16x32_bf16 v[98:101], v[192:195], v[208:211], v[98:101]
	v_mfma_f32_16x16x32_bf16 v[98:101], v[196:199], v[212:215], v[98:101]
	v_mfma_f32_16x16x32_bf16 v[86:89], v[184:187], v[216:219], v[86:89]
	v_mfma_f32_16x16x32_bf16 v[86:89], v[188:191], v[220:223], v[86:89]
	v_mfma_f32_16x16x32_bf16 v[82:85], v[192:195], v[216:219], v[82:85]
	v_mfma_f32_16x16x32_bf16 v[82:85], v[196:199], v[220:223], v[82:85]
	v_mfma_f32_16x16x32_bf16 v[70:73], v[184:187], v[224:227], v[70:73]
	v_mfma_f32_16x16x32_bf16 v[70:73], v[188:191], v[228:231], v[70:73]
	v_mfma_f32_16x16x32_bf16 v[66:69], v[192:195], v[224:227], v[66:69]
	v_mfma_f32_16x16x32_bf16 v[66:69], v[196:199], v[228:231], v[66:69]
	s_barrier
; #define PG8_STAGE(bufoff, gbase, voff) do { _Pragma("unroll") for (int _i = 0; _i < 2; ++_i) \
;         __builtin_amdgcn_global_load_lds((const unsigned*)((const char*)(gbase) + (voff)[_i]), (LAS unsigned*)(lds + (bufoff) + ldsw + _i * 8192), 16, 0, 0); } while (0)
; #define PG8_LDA(dst, b, h) do { _Pragma("unroll") for (int m = 0; m < 4; ++m) _Pragma("unroll") for (int k = 0; k < 2; ++k) dst[m][k] = *(const LAS bf16x8*)(lds + PG8_SA(b, h) + aoff + m * 2048 + k * 1024); } while (0)
; #define PG8_MMA(ai, bj, At, Bt) do { __builtin_amdgcn_s_setprio(1); _Pragma("unroll") for (int m = 0; m < 4; ++m) _Pragma("unroll") for (int n = 0; n < 2; ++n) _Pragma("unroll") for (int k = 0; k < 2; ++k) \
;         acc[ai][bj][m][n] = __builtin_amdgcn_mfma_f32_16x16x32_bf16(Bt[n][k], At[m][k], acc[ai][bj][m][n], 0, 0, 0); __builtin_amdgcn_s_setprio(0); } while (0)
; #define PG8_WAIT_V(n) asm volatile("s_waitcnt vmcnt(" #n ")" ::: "memory")
; #define PG8_WAIT_L(n) asm volatile("s_waitcnt lgkmcnt(" #n ")" ::: "memory")
; #define PG8_BAR __builtin_amdgcn_s_barrier()
; #define PG8_SCHED __builtin_amdgcn_sched_barrier(0)
; template <class Epi, bool ALIGN_EPI>
; __device__ __forceinline__ void gemm_phase(LAS unsigned char* lds, const Gemm g, const StaticOrder& S, const Epi& E) {
;     ...
;             PG8_LDA(At, 1, 1); PG8_STAGE(PG8_SB(1, 0), b3, voffB); PG8_STAGE(PG8_SB(1, 1), b3 + hstepB, voffB); PG8_STAGE(PG8_SA(1, 0), a3, voffA);
;             PG8_WAIT_V(8); PG8_WAIT_L(0); PG8_BAR; PG8_MMA(1, 0, At, B0); PG8_MMA(1, 1, At, B1); PG8_BAR; PG8_SCHED;
	s_add_i32 s8, s42, s28
	v_lshl_add_u64 v[144:145], v[144:145], 0, s[94:95]
	s_mov_b32 m0, s8
	ds_read_b128 v[200:203], v147 offset:49152
	ds_read_b128 v[204:207], v147 offset:50176
	ds_read_b128 v[208:211], v147 offset:51200
	ds_read_b128 v[212:215], v147 offset:52224
	ds_read_b128 v[216:219], v147 offset:53248
	ds_read_b128 v[220:223], v147 offset:54272
	ds_read_b128 v[224:227], v147 offset:55296
	ds_read_b128 v[228:231], v147 offset:56320
	global_load_lds_dwordx4 v[144:145], off
	s_add_i32 m0, s8, 0x2000
	s_add_u32 s8, s22, 0x40080
	v_lshl_add_u64 v[144:145], v[152:153], 0, s[94:95]
	s_addc_u32 s9, s23, 0
	s_add_i32 s22, s43, s28
	global_load_lds_dwordx4 v[144:145], off
	v_lshl_add_u64 v[144:145], s[8:9], 0, v[0:1]
	s_mov_b32 m0, s22
	s_nop 0
	global_load_lds_dwordx4 v[144:145], off
	v_lshl_add_u64 v[144:145], s[8:9], 0, v[134:135]
	s_add_i32 m0, s22, 0x2000
	s_nop 0
	global_load_lds_dwordx4 v[144:145], off
	v_lshl_add_u64 v[144:145], v[160:161], 0, s[94:95]
	s_mov_b32 m0, s35
	s_nop 0
	global_load_lds_dwordx4 v[144:145], off
	v_lshl_add_u64 v[144:145], v[162:163], 0, s[94:95]
	s_mov_b32 m0, s36
	s_nop 0
	global_load_lds_dwordx4 v[144:145], off
	s_waitcnt vmcnt(8)
	s_waitcnt lgkmcnt(0)
	s_barrier
	s_waitcnt lgkmcnt(0)
	v_mfma_f32_16x16x32_bf16 v[62:65], v[140:143], v[200:203], v[62:65]
	v_mfma_f32_16x16x32_bf16 v[62:65], v[148:151], v[204:207], v[62:65]
	v_mfma_f32_16x16x32_bf16 v[58:61], v[156:159], v[200:203], v[58:61]
	v_mfma_f32_16x16x32_bf16 v[58:61], v[180:183], v[204:207], v[58:61]
	v_mfma_f32_16x16x32_bf16 v[46:49], v[140:143], v[208:211], v[46:49]
	v_mfma_f32_16x16x32_bf16 v[46:49], v[148:151], v[212:215], v[46:49]
	v_mfma_f32_16x16x32_bf16 v[42:45], v[156:159], v[208:211], v[42:45]
	v_mfma_f32_16x16x32_bf16 v[42:45], v[180:183], v[212:215], v[42:45]
	v_mfma_f32_16x16x32_bf16 v[30:33], v[140:143], v[216:219], v[30:33]
	v_mfma_f32_16x16x32_bf16 v[30:33], v[148:151], v[220:223], v[30:33]
	v_mfma_f32_16x16x32_bf16 v[26:29], v[156:159], v[216:219], v[26:29]
	v_mfma_f32_16x16x32_bf16 v[26:29], v[180:183], v[220:223], v[26:29]
	v_mfma_f32_16x16x32_bf16 v[14:17], v[140:143], v[224:227], v[14:17]
	v_mfma_f32_16x16x32_bf16 v[14:17], v[148:151], v[228:231], v[14:17]
	v_mfma_f32_16x16x32_bf16 v[10:13], v[156:159], v[224:227], v[10:13]
	v_mfma_f32_16x16x32_bf16 v[10:13], v[180:183], v[228:231], v[10:13]
	v_mfma_f32_16x16x32_bf16 v[54:57], v[184:187], v[200:203], v[54:57]
	v_mfma_f32_16x16x32_bf16 v[54:57], v[188:191], v[204:207], v[54:57]
	v_mfma_f32_16x16x32_bf16 v[50:53], v[192:195], v[200:203], v[50:53]
	v_mfma_f32_16x16x32_bf16 v[50:53], v[196:199], v[204:207], v[50:53]
	v_mfma_f32_16x16x32_bf16 v[38:41], v[184:187], v[208:211], v[38:41]
	v_mfma_f32_16x16x32_bf16 v[38:41], v[188:191], v[212:215], v[38:41]
	v_mfma_f32_16x16x32_bf16 v[34:37], v[192:195], v[208:211], v[34:37]
	v_mfma_f32_16x16x32_bf16 v[34:37], v[196:199], v[212:215], v[34:37]
	v_mfma_f32_16x16x32_bf16 v[22:25], v[184:187], v[216:219], v[22:25]
	v_mfma_f32_16x16x32_bf16 v[22:25], v[188:191], v[220:223], v[22:25]
	v_mfma_f32_16x16x32_bf16 v[18:21], v[192:195], v[216:219], v[18:21]
	v_mfma_f32_16x16x32_bf16 v[18:21], v[196:199], v[220:223], v[18:21]
	v_mfma_f32_16x16x32_bf16 v[6:9], v[184:187], v[224:227], v[6:9]
	v_mfma_f32_16x16x32_bf16 v[6:9], v[188:191], v[228:231], v[6:9]
	v_mfma_f32_16x16x32_bf16 v[2:5], v[192:195], v[224:227], v[2:5]
	v_mfma_f32_16x16x32_bf16 v[2:5], v[196:199], v[228:231], v[2:5]
	s_cmp_lg_u32 s41, 12
	s_cbranch_scc1 .Ltail_bar_7
	s_cmp_eq_u64 s[2:3], 0
	s_cbranch_scc1 .Ltail_skip_7

; #define PG8_STAGE(bufoff, gbase, voff) do { _Pragma("unroll") for (int _i = 0; _i < 2; ++_i) \
;         __builtin_amdgcn_global_load_lds((const unsigned*)((const char*)(gbase) + (voff)[_i]), (LAS unsigned*)(lds + (bufoff) + ldsw + _i * 8192), 16, 0, 0); } while (0)
; #define PG8_LDA(dst, b, h) do { _Pragma("unroll") for (int m = 0; m < 4; ++m) _Pragma("unroll") for (int k = 0; k < 2; ++k) dst[m][k] = *(const LAS bf16x8*)(lds + PG8_SA(b, h) + aoff + m * 2048 + k * 1024); } while (0)
; #define PG8_LDB(dst, b, h) do { _Pragma("unroll") for (int n = 0; n < 2; ++n) _Pragma("unroll") for (int k = 0; k < 2; ++k) dst[n][k] = *(const LAS bf16x8*)(lds + PG8_SB(b, h) + boff + n * 2048 + k * 1024); } while (0)
; #define PG8_MMA(ai, bj, At, Bt) do { __builtin_amdgcn_s_setprio(1); _Pragma("unroll") for (int m = 0; m < 4; ++m) _Pragma("unroll") for (int n = 0; n < 2; ++n) _Pragma("unroll") for (int k = 0; k < 2; ++k) \
;         acc[ai][bj][m][n] = __builtin_amdgcn_mfma_f32_16x16x32_bf16(Bt[n][k], At[m][k], acc[ai][bj][m][n], 0, 0, 0); __builtin_amdgcn_s_setprio(0); } while (0)
; #define PG8_WAIT_V(n) asm volatile("s_waitcnt vmcnt(" #n ")" ::: "memory")
; #define PG8_WAIT_L(n) asm volatile("s_waitcnt lgkmcnt(" #n ")" ::: "memory")
; #define PG8_BAR __builtin_amdgcn_s_barrier()
; #define PG8_SCHED __builtin_amdgcn_sched_barrier(0)
; template <class Epi, bool ALIGN_EPI>
; __device__ __forceinline__ void gemm_phase(LAS unsigned char* lds, const Gemm g, const StaticOrder& S, const Epi& E) {
;     ...
;         for (int t = 0; t < nt; t += 2) {
;             const bool last = (t == nt - 2);
;             const char* a1 = cA + (size_t)(t + 1) * kstep;
;             const char* a2 = last ? nA : cA + (size_t)(t + 2) * kstep; const char* b2 = last ? nB : cB + (size_t)(t + 2) * kstep;
;             const char* a3 = a2 + kstep; const char* b3 = b2 + kstep;
;             PG8_LDB(B0, 0, 0); PG8_LDB(B1, 0, 1); PG8_SCHED; PG8_LDA(At, 0, 0); PG8_STAGE(PG8_SA(1, 1), a1 + hstepA, voffA);
;             PG8_WAIT_V(8); PG8_WAIT_L(0); PG8_BAR; PG8_MMA(0, 0, At, B0); PG8_MMA(0, 1, At, B1); PG8_BAR; PG8_SCHED;
;             PG8_LDA(At, 0, 1); PG8_STAGE(PG8_SB(0, 0), b2, voffB); PG8_STAGE(PG8_SB(0, 1), b2 + hstepB, voffB); PG8_STAGE(PG8_SA(0, 0), a2, voffA);
.LBB0_414:
	s_add_u32 s2, s0, 0x100
	s_addc_u32 s3, s1, 0
	s_add_i32 s44, 0, 0x10000
	s_cmp_eq_u32 s43, 12
	s_cselect_b32 s23, s17, s3
	s_cselect_b32 s22, s16, s2
	v_add_u32_e32 v144, s44, v146
	s_cselect_b32 s21, s15, s42
	s_cselect_b32 s20, s40, s41
	s_add_i32 s45, 0, 0x14000
	ds_read_b128 v[140:143], v144
	ds_read_b128 v[148:151], v144 offset:1024
	ds_read_b128 v[156:159], v144 offset:2048
	ds_read_b128 v[180:183], v144 offset:3072
	v_add_u32_e32 v144, s45, v146
	ds_read_b128 v[184:187], v144
	ds_read_b128 v[188:191], v144 offset:1024
	ds_read_b128 v[192:195], v144 offset:2048
	ds_read_b128 v[196:199], v144 offset:3072
	v_lshl_add_u64 v[144:145], s[0:1], 0, v[136:137]
	s_add_i32 m0, s29, 0xc000
	ds_read_b128 v[200:203], v147
	ds_read_b128 v[204:207], v147 offset:1024
	ds_read_b128 v[208:211], v147 offset:2048
	ds_read_b128 v[212:215], v147 offset:3072
	ds_read_b128 v[216:219], v147 offset:4096
	ds_read_b128 v[220:223], v147 offset:5120
	ds_read_b128 v[224:227], v147 offset:6144
	ds_read_b128 v[228:231], v147 offset:7168
	global_load_lds_dwordx4 v[144:145], off
	v_lshl_add_u64 v[144:145], s[0:1], 0, v[138:139]
	s_add_i32 m0, s29, 0xe000
	s_nop 0
	global_load_lds_dwordx4 v[144:145], off
	s_waitcnt vmcnt(8)
	s_waitcnt lgkmcnt(0)
	s_barrier
	s_waitcnt lgkmcnt(0)
	v_mfma_f32_16x16x32_bf16 v[126:129], v[140:143], v[200:203], v[126:129]
	v_mfma_f32_16x16x32_bf16 v[126:129], v[148:151], v[204:207], v[126:129]
	v_mfma_f32_16x16x32_bf16 v[122:125], v[156:159], v[200:203], v[122:125]
	v_mfma_f32_16x16x32_bf16 v[122:125], v[180:183], v[204:207], v[122:125]
	v_mfma_f32_16x16x32_bf16 v[110:113], v[140:143], v[208:211], v[110:113]
	v_mfma_f32_16x16x32_bf16 v[110:113], v[148:151], v[212:215], v[110:113]
	v_mfma_f32_16x16x32_bf16 v[106:109], v[156:159], v[208:211], v[106:109]
	v_mfma_f32_16x16x32_bf16 v[106:109], v[180:183], v[212:215], v[106:109]
	v_mfma_f32_16x16x32_bf16 v[94:97], v[140:143], v[216:219], v[94:97]
	v_mfma_f32_16x16x32_bf16 v[94:97], v[148:151], v[220:223], v[94:97]
	v_mfma_f32_16x16x32_bf16 v[90:93], v[156:159], v[216:219], v[90:93]
	v_mfma_f32_16x16x32_bf16 v[90:93], v[180:183], v[220:223], v[90:93]
	v_mfma_f32_16x16x32_bf16 v[78:81], v[140:143], v[224:227], v[78:81]
	v_mfma_f32_16x16x32_bf16 v[78:81], v[148:151], v[228:231], v[78:81]
	v_mfma_f32_16x16x32_bf16 v[74:77], v[156:159], v[224:227], v[74:77]
	v_mfma_f32_16x16x32_bf16 v[74:77], v[180:183], v[228:231], v[74:77]
	v_mfma_f32_16x16x32_bf16 v[118:121], v[184:187], v[200:203], v[118:121]
	v_mfma_f32_16x16x32_bf16 v[118:121], v[188:191], v[204:207], v[118:121]
	v_mfma_f32_16x16x32_bf16 v[114:117], v[192:195], v[200:203], v[114:117]
	v_mfma_f32_16x16x32_bf16 v[114:117], v[196:199], v[204:207], v[114:117]
	v_mfma_f32_16x16x32_bf16 v[102:105], v[184:187], v[208:211], v[102:105]
	v_mfma_f32_16x16x32_bf16 v[102:105], v[188:191], v[212:215], v[102:105]
	v_mfma_f32_16x16x32_bf16 v[98:101], v[192:195], v[208:211], v[98:101]
	v_mfma_f32_16x16x32_bf16 v[98:101], v[196:199], v[212:215], v[98:101]
	v_mfma_f32_16x16x32_bf16 v[86:89], v[184:187], v[216:219], v[86:89]
	v_mfma_f32_16x16x32_bf16 v[86:89], v[188:191], v[220:223], v[86:89]
	v_mfma_f32_16x16x32_bf16 v[82:85], v[192:195], v[216:219], v[82:85]
	v_mfma_f32_16x16x32_bf16 v[82:85], v[196:199], v[220:223], v[82:85]
	v_mfma_f32_16x16x32_bf16 v[70:73], v[184:187], v[224:227], v[70:73]
	v_mfma_f32_16x16x32_bf16 v[70:73], v[188:191], v[228:231], v[70:73]
	v_mfma_f32_16x16x32_bf16 v[66:69], v[192:195], v[224:227], v[66:69]
	v_mfma_f32_16x16x32_bf16 v[66:69], v[196:199], v[228:231], v[66:69]
	s_barrier
	s_add_i32 s0, s44, s28
	v_lshl_add_u64 v[144:145], s[20:21], 0, v[0:1]
	s_mov_b32 m0, s0
	ds_read_b128 v[200:203], v147 offset:16384
	ds_read_b128 v[204:207], v147 offset:17408
	ds_read_b128 v[208:211], v147 offset:18432
	ds_read_b128 v[212:215], v147 offset:19456
	ds_read_b128 v[216:219], v147 offset:20480
	ds_read_b128 v[220:223], v147 offset:21504
	ds_read_b128 v[224:227], v147 offset:22528
	ds_read_b128 v[228:231], v147 offset:23552
	global_load_lds_dwordx4 v[144:145], off
	s_add_i32 m0, s0, 0x2000
	s_add_u32 s0, s20, 0x40000
	v_lshl_add_u64 v[152:153], s[20:21], 0, v[134:135]
	s_addc_u32 s1, s21, 0
	s_add_i32 s44, s45, s28
	global_load_lds_dwordx4 v[152:153], off
	v_lshl_add_u64 v[160:161], s[0:1], 0, v[0:1]
	s_mov_b32 m0, s44
	v_lshl_add_u64 v[162:163], s[22:23], 0, v[132:133]
	global_load_lds_dwordx4 v[160:161], off
	v_lshl_add_u64 v[160:161], s[0:1], 0, v[134:135]
	s_add_i32 m0, s44, 0x2000
	s_nop 0
	global_load_lds_dwordx4 v[160:161], off
	v_lshl_add_u64 v[160:161], s[22:23], 0, v[130:131]
	s_mov_b32 m0, s29
	s_nop 0
	global_load_lds_dwordx4 v[160:161], off
	s_mov_b32 m0, s30
	s_nop 0
	global_load_lds_dwordx4 v[162:163], off
	s_waitcnt vmcnt(8)
	s_waitcnt lgkmcnt(0)
	s_barrier
; #define PG8_STAGE(bufoff, gbase, voff) do { _Pragma("unroll") for (int _i = 0; _i < 2; ++_i) \
;         __builtin_amdgcn_global_load_lds((const unsigned*)((const char*)(gbase) + (voff)[_i]), (LAS unsigned*)(lds + (bufoff) + ldsw + _i * 8192), 16, 0, 0); } while (0)
; #define PG8_LDA(dst, b, h) do { _Pragma("unroll") for (int m = 0; m < 4; ++m) _Pragma("unroll") for (int k = 0; k < 2; ++k) dst[m][k] = *(const LAS bf16x8*)(lds + PG8_SA(b, h) + aoff + m * 2048 + k * 1024); } while (0)
; #define PG8_LDB(dst, b, h) do { _Pragma("unroll") for (int n = 0; n < 2; ++n) _Pragma("unroll") for (int k = 0; k < 2; ++k) dst[n][k] = *(const LAS bf16x8*)(lds + PG8_SB(b, h) + boff + n * 2048 + k * 1024); } while (0)
; #define PG8_MMA(ai, bj, At, Bt) do { __builtin_amdgcn_s_setprio(1); _Pragma("unroll") for (int m = 0; m < 4; ++m) _Pragma("unroll") for (int n = 0; n < 2; ++n) _Pragma("unroll") for (int k = 0; k < 2; ++k) \
;         acc[ai][bj][m][n] = __builtin_amdgcn_mfma_f32_16x16x32_bf16(Bt[n][k], At[m][k], acc[ai][bj][m][n], 0, 0, 0); __builtin_amdgcn_s_setprio(0); } while (0)
; #define PG8_WAIT_V(n) asm volatile("s_waitcnt vmcnt(" #n ")" ::: "memory")
; #define PG8_WAIT_L(n) asm volatile("s_waitcnt lgkmcnt(" #n ")" ::: "memory")
; #define PG8_BAR __builtin_amdgcn_s_barrier()
; #define PG8_SCHED __builtin_amdgcn_sched_barrier(0)
; template <class Epi, bool ALIGN_EPI>
; __device__ __forceinline__ void gemm_phase(LAS unsigned char* lds, const Gemm g, const StaticOrder& S, const Epi& E) {
;     ...
;             PG8_WAIT_V(8); PG8_WAIT_L(0); PG8_BAR; PG8_MMA(1, 0, At, B0); PG8_MMA(1, 1, At, B1); PG8_BAR; PG8_SCHED;
;             PG8_LDB(B0, 1, 0); PG8_LDB(B1, 1, 1); PG8_SCHED; PG8_LDA(At, 1, 0); PG8_STAGE(PG8_SA(0, 1), a2 + hstepA, voffA);
;             PG8_WAIT_V(8); PG8_WAIT_L(0); PG8_BAR; PG8_MMA(0, 0, At, B0); PG8_MMA(0, 1, At, B1); PG8_BAR; PG8_SCHED;
	s_waitcnt lgkmcnt(0)
	v_mfma_f32_16x16x32_bf16 v[62:65], v[140:143], v[200:203], v[62:65]
	v_mfma_f32_16x16x32_bf16 v[62:65], v[148:151], v[204:207], v[62:65]
	v_mfma_f32_16x16x32_bf16 v[58:61], v[156:159], v[200:203], v[58:61]
	v_mfma_f32_16x16x32_bf16 v[58:61], v[180:183], v[204:207], v[58:61]
	v_mfma_f32_16x16x32_bf16 v[46:49], v[140:143], v[208:211], v[46:49]
	v_mfma_f32_16x16x32_bf16 v[46:49], v[148:151], v[212:215], v[46:49]
	v_mfma_f32_16x16x32_bf16 v[42:45], v[156:159], v[208:211], v[42:45]
	v_mfma_f32_16x16x32_bf16 v[42:45], v[180:183], v[212:215], v[42:45]
	v_mfma_f32_16x16x32_bf16 v[30:33], v[140:143], v[216:219], v[30:33]
	v_mfma_f32_16x16x32_bf16 v[30:33], v[148:151], v[220:223], v[30:33]
	v_mfma_f32_16x16x32_bf16 v[26:29], v[156:159], v[216:219], v[26:29]
	v_mfma_f32_16x16x32_bf16 v[26:29], v[180:183], v[220:223], v[26:29]
	v_mfma_f32_16x16x32_bf16 v[14:17], v[140:143], v[224:227], v[14:17]
	v_mfma_f32_16x16x32_bf16 v[14:17], v[148:151], v[228:231], v[14:17]
	v_mfma_f32_16x16x32_bf16 v[10:13], v[156:159], v[224:227], v[10:13]
	v_mfma_f32_16x16x32_bf16 v[10:13], v[180:183], v[228:231], v[10:13]
	v_mfma_f32_16x16x32_bf16 v[54:57], v[184:187], v[200:203], v[54:57]
	v_mfma_f32_16x16x32_bf16 v[54:57], v[188:191], v[204:207], v[54:57]
	v_mfma_f32_16x16x32_bf16 v[50:53], v[192:195], v[200:203], v[50:53]
	v_mfma_f32_16x16x32_bf16 v[50:53], v[196:199], v[204:207], v[50:53]
	v_mfma_f32_16x16x32_bf16 v[38:41], v[184:187], v[208:211], v[38:41]
	v_mfma_f32_16x16x32_bf16 v[38:41], v[188:191], v[212:215], v[38:41]
	v_mfma_f32_16x16x32_bf16 v[34:37], v[192:195], v[208:211], v[34:37]
	v_mfma_f32_16x16x32_bf16 v[34:37], v[196:199], v[212:215], v[34:37]
	v_mfma_f32_16x16x32_bf16 v[22:25], v[184:187], v[216:219], v[22:25]
	v_mfma_f32_16x16x32_bf16 v[22:25], v[188:191], v[220:223], v[22:25]
	v_mfma_f32_16x16x32_bf16 v[18:21], v[192:195], v[216:219], v[18:21]
	v_mfma_f32_16x16x32_bf16 v[18:21], v[196:199], v[220:223], v[18:21]
	v_mfma_f32_16x16x32_bf16 v[6:9], v[184:187], v[224:227], v[6:9]
	v_mfma_f32_16x16x32_bf16 v[6:9], v[188:191], v[228:231], v[6:9]
	v_mfma_f32_16x16x32_bf16 v[2:5], v[192:195], v[224:227], v[2:5]
	v_mfma_f32_16x16x32_bf16 v[2:5], v[196:199], v[228:231], v[2:5]
	s_barrier
	s_add_i32 s44, 0, 0x18000
	v_add_u32_e32 v164, s44, v146
	s_add_i32 s45, 0, 0x1c000
	ds_read_b128 v[140:143], v164
	ds_read_b128 v[148:151], v164 offset:1024
	ds_read_b128 v[156:159], v164 offset:2048
	ds_read_b128 v[180:183], v164 offset:3072
	v_add_u32_e32 v164, s45, v146
	ds_read_b128 v[184:187], v164
	ds_read_b128 v[188:191], v164 offset:1024
	ds_read_b128 v[192:195], v164 offset:2048
	ds_read_b128 v[196:199], v164 offset:3072
	s_add_u32 s0, s22, 0x160000
	s_addc_u32 s1, s23, 0
	s_mov_b32 m0, s31
	v_lshl_add_u64 v[170:171], s[0:1], 0, v[130:131]
	ds_read_b128 v[200:203], v147 offset:32768
	ds_read_b128 v[204:207], v147 offset:33792
	ds_read_b128 v[208:211], v147 offset:34816
	ds_read_b128 v[212:215], v147 offset:35840
	ds_read_b128 v[216:219], v147 offset:36864
	ds_read_b128 v[220:223], v147 offset:37888
	ds_read_b128 v[224:227], v147 offset:38912
	ds_read_b128 v[228:231], v147 offset:39936
	global_load_lds_dwordx4 v[170:171], off
	v_lshl_add_u64 v[170:171], s[0:1], 0, v[132:133]
	s_mov_b32 m0, s34
	s_nop 0
	global_load_lds_dwordx4 v[170:171], off
	s_waitcnt vmcnt(8)
	s_waitcnt lgkmcnt(0)
	s_barrier
	s_waitcnt lgkmcnt(0)
	v_mfma_f32_16x16x32_bf16 v[126:129], v[140:143], v[200:203], v[126:129]
	v_mfma_f32_16x16x32_bf16 v[126:129], v[148:151], v[204:207], v[126:129]
	v_mfma_f32_16x16x32_bf16 v[122:125], v[156:159], v[200:203], v[122:125]
	v_mfma_f32_16x16x32_bf16 v[122:125], v[180:183], v[204:207], v[122:125]
	v_mfma_f32_16x16x32_bf16 v[110:113], v[140:143], v[208:211], v[110:113]
	v_mfma_f32_16x16x32_bf16 v[110:113], v[148:151], v[212:215], v[110:113]
	v_mfma_f32_16x16x32_bf16 v[106:109], v[156:159], v[208:211], v[106:109]
	v_mfma_f32_16x16x32_bf16 v[106:109], v[180:183], v[212:215], v[106:109]
	v_mfma_f32_16x16x32_bf16 v[94:97], v[140:143], v[216:219], v[94:97]
	v_mfma_f32_16x16x32_bf16 v[94:97], v[148:151], v[220:223], v[94:97]
	v_mfma_f32_16x16x32_bf16 v[90:93], v[156:159], v[216:219], v[90:93]
	v_mfma_f32_16x16x32_bf16 v[90:93], v[180:183], v[220:223], v[90:93]
	v_mfma_f32_16x16x32_bf16 v[78:81], v[140:143], v[224:227], v[78:81]
	v_mfma_f32_16x16x32_bf16 v[78:81], v[148:151], v[228:231], v[78:81]
	v_mfma_f32_16x16x32_bf16 v[74:77], v[156:159], v[224:227], v[74:77]
	v_mfma_f32_16x16x32_bf16 v[74:77], v[180:183], v[228:231], v[74:77]
	v_mfma_f32_16x16x32_bf16 v[118:121], v[184:187], v[200:203], v[118:121]
	v_mfma_f32_16x16x32_bf16 v[118:121], v[188:191], v[204:207], v[118:121]
	v_mfma_f32_16x16x32_bf16 v[114:117], v[192:195], v[200:203], v[114:117]
	v_mfma_f32_16x16x32_bf16 v[114:117], v[196:199], v[204:207], v[114:117]
	v_mfma_f32_16x16x32_bf16 v[102:105], v[184:187], v[208:211], v[102:105]
	v_mfma_f32_16x16x32_bf16 v[102:105], v[188:191], v[212:215], v[102:105]
	v_mfma_f32_16x16x32_bf16 v[98:101], v[192:195], v[208:211], v[98:101]
	v_mfma_f32_16x16x32_bf16 v[98:101], v[196:199], v[212:215], v[98:101]
	v_mfma_f32_16x16x32_bf16 v[86:89], v[184:187], v[216:219], v[86:89]
	v_mfma_f32_16x16x32_bf16 v[86:89], v[188:191], v[220:223], v[86:89]
	v_mfma_f32_16x16x32_bf16 v[82:85], v[192:195], v[216:219], v[82:85]
	v_mfma_f32_16x16x32_bf16 v[82:85], v[196:199], v[220:223], v[82:85]
	v_mfma_f32_16x16x32_bf16 v[70:73], v[184:187], v[224:227], v[70:73]
	v_mfma_f32_16x16x32_bf16 v[70:73], v[188:191], v[228:231], v[70:73]
	v_mfma_f32_16x16x32_bf16 v[66:69], v[192:195], v[224:227], v[66:69]
	v_mfma_f32_16x16x32_bf16 v[66:69], v[196:199], v[228:231], v[66:69]
	s_barrier
; #define PG8_STAGE(bufoff, gbase, voff) do { _Pragma("unroll") for (int _i = 0; _i < 2; ++_i) \
;         __builtin_amdgcn_global_load_lds((const unsigned*)((const char*)(gbase) + (voff)[_i]), (LAS unsigned*)(lds + (bufoff) + ldsw + _i * 8192), 16, 0, 0); } while (0)
; #define PG8_LDA(dst, b, h) do { _Pragma("unroll") for (int m = 0; m < 4; ++m) _Pragma("unroll") for (int k = 0; k < 2; ++k) dst[m][k] = *(const LAS bf16x8*)(lds + PG8_SA(b, h) + aoff + m * 2048 + k * 1024); } while (0)
; #define PG8_MMA(ai, bj, At, Bt) do { __builtin_amdgcn_s_setprio(1); _Pragma("unroll") for (int m = 0; m < 4; ++m) _Pragma("unroll") for (int n = 0; n < 2; ++n) _Pragma("unroll") for (int k = 0; k < 2; ++k) \
;         acc[ai][bj][m][n] = __builtin_amdgcn_mfma_f32_16x16x32_bf16(Bt[n][k], At[m][k], acc[ai][bj][m][n], 0, 0, 0); __builtin_amdgcn_s_setprio(0); } while (0)
; #define PG8_WAIT_V(n) asm volatile("s_waitcnt vmcnt(" #n ")" ::: "memory")
; #define PG8_WAIT_L(n) asm volatile("s_waitcnt lgkmcnt(" #n ")" ::: "memory")
; #define PG8_BAR __builtin_amdgcn_s_barrier()
; #define PG8_SCHED __builtin_amdgcn_sched_barrier(0)
; template <class Epi, bool ALIGN_EPI>
; __device__ __forceinline__ void gemm_phase(LAS unsigned char* lds, const Gemm g, const StaticOrder& S, const Epi& E) {
;     ...
;             PG8_LDA(At, 1, 1); PG8_STAGE(PG8_SB(1, 0), b3, voffB); PG8_STAGE(PG8_SB(1, 1), b3 + hstepB, voffB); PG8_STAGE(PG8_SA(1, 0), a3, voffA);
;             PG8_WAIT_V(8); PG8_WAIT_L(0); PG8_BAR; PG8_MMA(1, 0, At, B0); PG8_MMA(1, 1, At, B1); PG8_BAR; PG8_SCHED;
	s_add_i32 s0, s44, s28
	v_lshl_add_u64 v[144:145], v[144:145], 0, s[94:95]
	s_mov_b32 m0, s0
	ds_read_b128 v[200:203], v147 offset:49152
	ds_read_b128 v[204:207], v147 offset:50176
	ds_read_b128 v[208:211], v147 offset:51200
	ds_read_b128 v[212:215], v147 offset:52224
	ds_read_b128 v[216:219], v147 offset:53248
	ds_read_b128 v[220:223], v147 offset:54272
	ds_read_b128 v[224:227], v147 offset:55296
	ds_read_b128 v[228:231], v147 offset:56320
	global_load_lds_dwordx4 v[144:145], off
	s_add_i32 m0, s0, 0x2000
	s_add_u32 s0, s20, 0x40080
	v_lshl_add_u64 v[144:145], v[152:153], 0, s[94:95]
	s_addc_u32 s1, s21, 0
	s_add_i32 s20, s45, s28
	global_load_lds_dwordx4 v[144:145], off
	v_lshl_add_u64 v[144:145], s[0:1], 0, v[0:1]
	s_mov_b32 m0, s20
	s_nop 0
	global_load_lds_dwordx4 v[144:145], off
	v_lshl_add_u64 v[144:145], s[0:1], 0, v[134:135]
	s_add_i32 m0, s20, 0x2000
	s_nop 0
	global_load_lds_dwordx4 v[144:145], off
	v_lshl_add_u64 v[144:145], v[160:161], 0, s[94:95]
	s_mov_b32 m0, s4
	s_nop 0
	global_load_lds_dwordx4 v[144:145], off
	v_lshl_add_u64 v[144:145], v[162:163], 0, s[94:95]
	s_mov_b32 m0, s35
	s_nop 0
	global_load_lds_dwordx4 v[144:145], off
	s_waitcnt vmcnt(8)
	s_waitcnt lgkmcnt(0)
	s_barrier
	s_waitcnt lgkmcnt(0)
	v_mfma_f32_16x16x32_bf16 v[62:65], v[140:143], v[200:203], v[62:65]
	v_mfma_f32_16x16x32_bf16 v[62:65], v[148:151], v[204:207], v[62:65]
	v_mfma_f32_16x16x32_bf16 v[58:61], v[156:159], v[200:203], v[58:61]
	v_mfma_f32_16x16x32_bf16 v[58:61], v[180:183], v[204:207], v[58:61]
	v_mfma_f32_16x16x32_bf16 v[46:49], v[140:143], v[208:211], v[46:49]
	v_mfma_f32_16x16x32_bf16 v[46:49], v[148:151], v[212:215], v[46:49]
	v_mfma_f32_16x16x32_bf16 v[42:45], v[156:159], v[208:211], v[42:45]
	v_mfma_f32_16x16x32_bf16 v[42:45], v[180:183], v[212:215], v[42:45]
	v_mfma_f32_16x16x32_bf16 v[30:33], v[140:143], v[216:219], v[30:33]
	v_mfma_f32_16x16x32_bf16 v[30:33], v[148:151], v[220:223], v[30:33]
	v_mfma_f32_16x16x32_bf16 v[26:29], v[156:159], v[216:219], v[26:29]
	v_mfma_f32_16x16x32_bf16 v[26:29], v[180:183], v[220:223], v[26:29]
	v_mfma_f32_16x16x32_bf16 v[14:17], v[140:143], v[224:227], v[14:17]
	v_mfma_f32_16x16x32_bf16 v[14:17], v[148:151], v[228:231], v[14:17]
	v_mfma_f32_16x16x32_bf16 v[10:13], v[156:159], v[224:227], v[10:13]
	v_mfma_f32_16x16x32_bf16 v[10:13], v[180:183], v[228:231], v[10:13]
	v_mfma_f32_16x16x32_bf16 v[54:57], v[184:187], v[200:203], v[54:57]
	v_mfma_f32_16x16x32_bf16 v[54:57], v[188:191], v[204:207], v[54:57]
	v_mfma_f32_16x16x32_bf16 v[50:53], v[192:195], v[200:203], v[50:53]
	v_mfma_f32_16x16x32_bf16 v[50:53], v[196:199], v[204:207], v[50:53]
	v_mfma_f32_16x16x32_bf16 v[38:41], v[184:187], v[208:211], v[38:41]
	v_mfma_f32_16x16x32_bf16 v[38:41], v[188:191], v[212:215], v[38:41]
	v_mfma_f32_16x16x32_bf16 v[34:37], v[192:195], v[208:211], v[34:37]
	v_mfma_f32_16x16x32_bf16 v[34:37], v[196:199], v[212:215], v[34:37]
	v_mfma_f32_16x16x32_bf16 v[22:25], v[184:187], v[216:219], v[22:25]
	v_mfma_f32_16x16x32_bf16 v[22:25], v[188:191], v[220:223], v[22:25]
	v_mfma_f32_16x16x32_bf16 v[18:21], v[192:195], v[216:219], v[18:21]
	v_mfma_f32_16x16x32_bf16 v[18:21], v[196:199], v[220:223], v[18:21]
	v_mfma_f32_16x16x32_bf16 v[6:9], v[184:187], v[224:227], v[6:9]
	v_mfma_f32_16x16x32_bf16 v[6:9], v[188:191], v[228:231], v[6:9]
	v_mfma_f32_16x16x32_bf16 v[2:5], v[192:195], v[224:227], v[2:5]
	v_mfma_f32_16x16x32_bf16 v[2:5], v[196:199], v[228:231], v[2:5]
	s_cmp_lg_u32 s43, 12
	s_cbranch_scc1 .Ltail_bar_6
	s_cmp_eq_u64 s[12:13], 0
	s_cbranch_scc1 .Ltail_skip_6

; #define PG8_STAGE(bufoff, gbase, voff) do { _Pragma("unroll") for (int _i = 0; _i < 2; ++_i) \
;         __builtin_amdgcn_global_load_lds((const unsigned*)((const char*)(gbase) + (voff)[_i]), (LAS unsigned*)(lds + (bufoff) + ldsw + _i * 8192), 16, 0, 0); } while (0)
; #define PG8_LDA(dst, b, h) do { _Pragma("unroll") for (int m = 0; m < 4; ++m) _Pragma("unroll") for (int k = 0; k < 2; ++k) dst[m][k] = *(const LAS bf16x8*)(lds + PG8_SA(b, h) + aoff + m * 2048 + k * 1024); } while (0)
; #define PG8_LDB(dst, b, h) do { _Pragma("unroll") for (int n = 0; n < 2; ++n) _Pragma("unroll") for (int k = 0; k < 2; ++k) dst[n][k] = *(const LAS bf16x8*)(lds + PG8_SB(b, h) + boff + n * 2048 + k * 1024); } while (0)
; #define PG8_MMA(ai, bj, At, Bt) do { __builtin_amdgcn_s_setprio(1); _Pragma("unroll") for (int m = 0; m < 4; ++m) _Pragma("unroll") for (int n = 0; n < 2; ++n) _Pragma("unroll") for (int k = 0; k < 2; ++k) \
;         acc[ai][bj][m][n] = __builtin_amdgcn_mfma_f32_16x16x32_bf16(Bt[n][k], At[m][k], acc[ai][bj][m][n], 0, 0, 0); __builtin_amdgcn_s_setprio(0); } while (0)
; #define PG8_WAIT_V(n) asm volatile("s_waitcnt vmcnt(" #n ")" ::: "memory")
; #define PG8_WAIT_L(n) asm volatile("s_waitcnt lgkmcnt(" #n ")" ::: "memory")
; #define PG8_BAR __builtin_amdgcn_s_barrier()
; #define PG8_SCHED __builtin_amdgcn_sched_barrier(0)
; template <class Epi, bool ALIGN_EPI>
; __device__ __forceinline__ void gemm_phase(LAS unsigned char* lds, const Gemm g, const StaticOrder& S, const Epi& E) {
;     ...
;         for (int t = 0; t < nt; t += 2) {
;             const bool last = (t == nt - 2);
;             const char* a1 = cA + (size_t)(t + 1) * kstep;
;             const char* a2 = last ? nA : cA + (size_t)(t + 2) * kstep; const char* b2 = last ? nB : cB + (size_t)(t + 2) * kstep;
;             const char* a3 = a2 + kstep; const char* b3 = b2 + kstep;
;             PG8_LDB(B0, 0, 0); PG8_LDB(B1, 0, 1); PG8_SCHED; PG8_LDA(At, 0, 0); PG8_STAGE(PG8_SA(1, 1), a1 + hstepA, voffA);
;             PG8_WAIT_V(8); PG8_WAIT_L(0); PG8_BAR; PG8_MMA(0, 0, At, B0); PG8_MMA(0, 1, At, B1); PG8_BAR; PG8_SCHED;
;             PG8_LDA(At, 0, 1); PG8_STAGE(PG8_SB(0, 0), b2, voffB); PG8_STAGE(PG8_SB(0, 1), b2 + hstepB, voffB); PG8_STAGE(PG8_SA(0, 0), a2, voffA);
.LBB0_483:
	s_add_u32 s18, s6, 0xfffc0080
	s_addc_u32 s19, s7, -1
	s_add_i32 s41, 0, 0x10000
	s_cmp_eq_u32 s40, 12
	s_cselect_b32 s21, s1, s19
	s_cselect_b32 s20, s36, s18
	v_add_u32_e32 v152, s41, v140
	s_cselect_b32 s19, s11, s39
	s_cselect_b32 s18, s37, s38
	s_add_i32 s44, 0, 0x14000
	ds_read_b128 v[144:147], v152
	ds_read_b128 v[148:151], v152 offset:1024
	ds_read_b128 v[156:159], v152 offset:2048
	ds_read_b128 v[180:183], v152 offset:3072
	v_add_u32_e32 v152, s44, v140
	ds_read_b128 v[184:187], v152
	ds_read_b128 v[188:191], v152 offset:1024
	ds_read_b128 v[192:195], v152 offset:2048
	ds_read_b128 v[196:199], v152 offset:3072
	v_lshl_add_u64 v[152:153], s[6:7], 0, v[136:137]
	s_add_i32 m0, s25, 0xc000
	ds_read_b128 v[200:203], v142
	ds_read_b128 v[204:207], v142 offset:1024
	ds_read_b128 v[208:211], v142 offset:2048
	ds_read_b128 v[212:215], v142 offset:3072
	ds_read_b128 v[216:219], v142 offset:4096
	ds_read_b128 v[220:223], v142 offset:5120
	ds_read_b128 v[224:227], v142 offset:6144
	ds_read_b128 v[228:231], v142 offset:7168
	global_load_lds_dwordx4 v[152:153], off
	v_lshl_add_u64 v[152:153], s[6:7], 0, v[138:139]
	s_add_i32 m0, s25, 0xe000
	s_nop 0
	global_load_lds_dwordx4 v[152:153], off
	s_waitcnt vmcnt(8)
	s_waitcnt lgkmcnt(0)
	s_barrier
	s_waitcnt lgkmcnt(0)
	v_mfma_f32_16x16x32_bf16 v[126:129], v[144:147], v[200:203], v[126:129]
	v_mfma_f32_16x16x32_bf16 v[126:129], v[148:151], v[204:207], v[126:129]
	v_mfma_f32_16x16x32_bf16 v[122:125], v[156:159], v[200:203], v[122:125]
	v_mfma_f32_16x16x32_bf16 v[122:125], v[180:183], v[204:207], v[122:125]
	v_mfma_f32_16x16x32_bf16 v[110:113], v[144:147], v[208:211], v[110:113]
	v_mfma_f32_16x16x32_bf16 v[110:113], v[148:151], v[212:215], v[110:113]
	v_mfma_f32_16x16x32_bf16 v[106:109], v[156:159], v[208:211], v[106:109]
	v_mfma_f32_16x16x32_bf16 v[106:109], v[180:183], v[212:215], v[106:109]
	v_mfma_f32_16x16x32_bf16 v[94:97], v[144:147], v[216:219], v[94:97]
	v_mfma_f32_16x16x32_bf16 v[94:97], v[148:151], v[220:223], v[94:97]
	v_mfma_f32_16x16x32_bf16 v[90:93], v[156:159], v[216:219], v[90:93]
	v_mfma_f32_16x16x32_bf16 v[90:93], v[180:183], v[220:223], v[90:93]
	v_mfma_f32_16x16x32_bf16 v[78:81], v[144:147], v[224:227], v[78:81]
	v_mfma_f32_16x16x32_bf16 v[78:81], v[148:151], v[228:231], v[78:81]
	v_mfma_f32_16x16x32_bf16 v[74:77], v[156:159], v[224:227], v[74:77]
	v_mfma_f32_16x16x32_bf16 v[74:77], v[180:183], v[228:231], v[74:77]
	v_mfma_f32_16x16x32_bf16 v[118:121], v[184:187], v[200:203], v[118:121]
	v_mfma_f32_16x16x32_bf16 v[118:121], v[188:191], v[204:207], v[118:121]
	v_mfma_f32_16x16x32_bf16 v[114:117], v[192:195], v[200:203], v[114:117]
	v_mfma_f32_16x16x32_bf16 v[114:117], v[196:199], v[204:207], v[114:117]
	v_mfma_f32_16x16x32_bf16 v[102:105], v[184:187], v[208:211], v[102:105]
	v_mfma_f32_16x16x32_bf16 v[102:105], v[188:191], v[212:215], v[102:105]
	v_mfma_f32_16x16x32_bf16 v[98:101], v[192:195], v[208:211], v[98:101]
	v_mfma_f32_16x16x32_bf16 v[98:101], v[196:199], v[212:215], v[98:101]
	v_mfma_f32_16x16x32_bf16 v[86:89], v[184:187], v[216:219], v[86:89]
	v_mfma_f32_16x16x32_bf16 v[86:89], v[188:191], v[220:223], v[86:89]
	v_mfma_f32_16x16x32_bf16 v[82:85], v[192:195], v[216:219], v[82:85]
	v_mfma_f32_16x16x32_bf16 v[82:85], v[196:199], v[220:223], v[82:85]
	v_mfma_f32_16x16x32_bf16 v[70:73], v[184:187], v[224:227], v[70:73]
	v_mfma_f32_16x16x32_bf16 v[70:73], v[188:191], v[228:231], v[70:73]
	v_mfma_f32_16x16x32_bf16 v[66:69], v[192:195], v[224:227], v[66:69]
	v_mfma_f32_16x16x32_bf16 v[66:69], v[196:199], v[228:231], v[66:69]
	s_barrier
	s_add_i32 s41, s41, s24
	v_lshl_add_u64 v[152:153], s[18:19], 0, v[0:1]
	s_mov_b32 m0, s41
	ds_read_b128 v[200:203], v142 offset:16384
	ds_read_b128 v[204:207], v142 offset:17408
	ds_read_b128 v[208:211], v142 offset:18432
	ds_read_b128 v[212:215], v142 offset:19456
	ds_read_b128 v[216:219], v142 offset:20480
	ds_read_b128 v[220:223], v142 offset:21504
	ds_read_b128 v[224:227], v142 offset:22528
	ds_read_b128 v[228:231], v142 offset:23552
	global_load_lds_dwordx4 v[152:153], off
	s_add_i32 m0, s41, 0x2000
	s_add_u32 s42, s18, 0x40000
	v_lshl_add_u64 v[160:161], s[18:19], 0, v[134:135]
	s_addc_u32 s43, s19, 0
	s_add_i32 s41, s44, s24
	global_load_lds_dwordx4 v[160:161], off
	v_lshl_add_u64 v[162:163], s[42:43], 0, v[0:1]
	s_mov_b32 m0, s41
	v_lshl_add_u64 v[170:171], s[20:21], 0, v[132:133]
	global_load_lds_dwordx4 v[162:163], off
	v_lshl_add_u64 v[162:163], s[42:43], 0, v[134:135]
	s_add_i32 m0, s41, 0x2000
	s_nop 0
	global_load_lds_dwordx4 v[162:163], off
	v_lshl_add_u64 v[162:163], s[20:21], 0, v[130:131]
	s_mov_b32 m0, s25
	s_nop 0
	global_load_lds_dwordx4 v[162:163], off
	s_mov_b32 m0, s26
	s_nop 0
	global_load_lds_dwordx4 v[170:171], off
	s_waitcnt vmcnt(8)
	s_waitcnt lgkmcnt(0)
	s_barrier
; #define PG8_STAGE(bufoff, gbase, voff) do { _Pragma("unroll") for (int _i = 0; _i < 2; ++_i) \
;         __builtin_amdgcn_global_load_lds((const unsigned*)((const char*)(gbase) + (voff)[_i]), (LAS unsigned*)(lds + (bufoff) + ldsw + _i * 8192), 16, 0, 0); } while (0)
; #define PG8_LDA(dst, b, h) do { _Pragma("unroll") for (int m = 0; m < 4; ++m) _Pragma("unroll") for (int k = 0; k < 2; ++k) dst[m][k] = *(const LAS bf16x8*)(lds + PG8_SA(b, h) + aoff + m * 2048 + k * 1024); } while (0)
; #define PG8_LDB(dst, b, h) do { _Pragma("unroll") for (int n = 0; n < 2; ++n) _Pragma("unroll") for (int k = 0; k < 2; ++k) dst[n][k] = *(const LAS bf16x8*)(lds + PG8_SB(b, h) + boff + n * 2048 + k * 1024); } while (0)
; #define PG8_MMA(ai, bj, At, Bt) do { __builtin_amdgcn_s_setprio(1); _Pragma("unroll") for (int m = 0; m < 4; ++m) _Pragma("unroll") for (int n = 0; n < 2; ++n) _Pragma("unroll") for (int k = 0; k < 2; ++k) \
;         acc[ai][bj][m][n] = __builtin_amdgcn_mfma_f32_16x16x32_bf16(Bt[n][k], At[m][k], acc[ai][bj][m][n], 0, 0, 0); __builtin_amdgcn_s_setprio(0); } while (0)
; #define PG8_WAIT_V(n) asm volatile("s_waitcnt vmcnt(" #n ")" ::: "memory")
; #define PG8_WAIT_L(n) asm volatile("s_waitcnt lgkmcnt(" #n ")" ::: "memory")
; #define PG8_BAR __builtin_amdgcn_s_barrier()
; #define PG8_SCHED __builtin_amdgcn_sched_barrier(0)
; template <class Epi, bool ALIGN_EPI>
; __device__ __forceinline__ void gemm_phase(LAS unsigned char* lds, const Gemm g, const StaticOrder& S, const Epi& E) {
;     ...
;             PG8_WAIT_V(8); PG8_WAIT_L(0); PG8_BAR; PG8_MMA(1, 0, At, B0); PG8_MMA(1, 1, At, B1); PG8_BAR; PG8_SCHED;
;             PG8_LDB(B0, 1, 0); PG8_LDB(B1, 1, 1); PG8_SCHED; PG8_LDA(At, 1, 0); PG8_STAGE(PG8_SA(0, 1), a2 + hstepA, voffA);
;             PG8_WAIT_V(8); PG8_WAIT_L(0); PG8_BAR; PG8_MMA(0, 0, At, B0); PG8_MMA(0, 1, At, B1); PG8_BAR; PG8_SCHED;
	s_waitcnt lgkmcnt(0)
	v_mfma_f32_16x16x32_bf16 v[62:65], v[144:147], v[200:203], v[62:65]
	v_mfma_f32_16x16x32_bf16 v[62:65], v[148:151], v[204:207], v[62:65]
	v_mfma_f32_16x16x32_bf16 v[58:61], v[156:159], v[200:203], v[58:61]
	v_mfma_f32_16x16x32_bf16 v[58:61], v[180:183], v[204:207], v[58:61]
	v_mfma_f32_16x16x32_bf16 v[46:49], v[144:147], v[208:211], v[46:49]
	v_mfma_f32_16x16x32_bf16 v[46:49], v[148:151], v[212:215], v[46:49]
	v_mfma_f32_16x16x32_bf16 v[42:45], v[156:159], v[208:211], v[42:45]
	v_mfma_f32_16x16x32_bf16 v[42:45], v[180:183], v[212:215], v[42:45]
	v_mfma_f32_16x16x32_bf16 v[30:33], v[144:147], v[216:219], v[30:33]
	v_mfma_f32_16x16x32_bf16 v[30:33], v[148:151], v[220:223], v[30:33]
	v_mfma_f32_16x16x32_bf16 v[26:29], v[156:159], v[216:219], v[26:29]
	v_mfma_f32_16x16x32_bf16 v[26:29], v[180:183], v[220:223], v[26:29]
	v_mfma_f32_16x16x32_bf16 v[14:17], v[144:147], v[224:227], v[14:17]
	v_mfma_f32_16x16x32_bf16 v[14:17], v[148:151], v[228:231], v[14:17]
	v_mfma_f32_16x16x32_bf16 v[10:13], v[156:159], v[224:227], v[10:13]
	v_mfma_f32_16x16x32_bf16 v[10:13], v[180:183], v[228:231], v[10:13]
	v_mfma_f32_16x16x32_bf16 v[54:57], v[184:187], v[200:203], v[54:57]
	v_mfma_f32_16x16x32_bf16 v[54:57], v[188:191], v[204:207], v[54:57]
	v_mfma_f32_16x16x32_bf16 v[50:53], v[192:195], v[200:203], v[50:53]
	v_mfma_f32_16x16x32_bf16 v[50:53], v[196:199], v[204:207], v[50:53]
	v_mfma_f32_16x16x32_bf16 v[38:41], v[184:187], v[208:211], v[38:41]
	v_mfma_f32_16x16x32_bf16 v[38:41], v[188:191], v[212:215], v[38:41]
	v_mfma_f32_16x16x32_bf16 v[34:37], v[192:195], v[208:211], v[34:37]
	v_mfma_f32_16x16x32_bf16 v[34:37], v[196:199], v[212:215], v[34:37]
	v_mfma_f32_16x16x32_bf16 v[22:25], v[184:187], v[216:219], v[22:25]
	v_mfma_f32_16x16x32_bf16 v[22:25], v[188:191], v[220:223], v[22:25]
	v_mfma_f32_16x16x32_bf16 v[18:21], v[192:195], v[216:219], v[18:21]
	v_mfma_f32_16x16x32_bf16 v[18:21], v[196:199], v[220:223], v[18:21]
	v_mfma_f32_16x16x32_bf16 v[6:9], v[184:187], v[224:227], v[6:9]
	v_mfma_f32_16x16x32_bf16 v[6:9], v[188:191], v[228:231], v[6:9]
	v_mfma_f32_16x16x32_bf16 v[2:5], v[192:195], v[224:227], v[2:5]
	v_mfma_f32_16x16x32_bf16 v[2:5], v[196:199], v[228:231], v[2:5]
	s_barrier
	s_add_i32 s41, 0, 0x18000
	v_add_u32_e32 v164, s41, v140
	s_add_i32 s42, 0, 0x1c000
	ds_read_b128 v[144:147], v164
	ds_read_b128 v[148:151], v164 offset:1024
	ds_read_b128 v[156:159], v164 offset:2048
	ds_read_b128 v[180:183], v164 offset:3072
	v_add_u32_e32 v164, s42, v140
	ds_read_b128 v[184:187], v164
	ds_read_b128 v[188:191], v164 offset:1024
	ds_read_b128 v[192:195], v164 offset:2048
	ds_read_b128 v[196:199], v164 offset:3072
	s_add_u32 s20, s20, 0x40000
	s_addc_u32 s21, s21, 0
	s_mov_b32 m0, s27
	v_lshl_add_u64 v[172:173], s[20:21], 0, v[130:131]
	ds_read_b128 v[200:203], v142 offset:32768
	ds_read_b128 v[204:207], v142 offset:33792
	ds_read_b128 v[208:211], v142 offset:34816
	ds_read_b128 v[212:215], v142 offset:35840
	ds_read_b128 v[216:219], v142 offset:36864
	ds_read_b128 v[220:223], v142 offset:37888
	ds_read_b128 v[224:227], v142 offset:38912
	ds_read_b128 v[228:231], v142 offset:39936
	global_load_lds_dwordx4 v[172:173], off
	v_lshl_add_u64 v[172:173], s[20:21], 0, v[132:133]
	s_mov_b32 m0, s28
	s_nop 0
	global_load_lds_dwordx4 v[172:173], off
	s_waitcnt vmcnt(8)
	s_waitcnt lgkmcnt(0)
	s_barrier
	s_waitcnt lgkmcnt(0)
	v_mfma_f32_16x16x32_bf16 v[126:129], v[144:147], v[200:203], v[126:129]
	v_mfma_f32_16x16x32_bf16 v[126:129], v[148:151], v[204:207], v[126:129]
	v_mfma_f32_16x16x32_bf16 v[122:125], v[156:159], v[200:203], v[122:125]
	v_mfma_f32_16x16x32_bf16 v[122:125], v[180:183], v[204:207], v[122:125]
	v_mfma_f32_16x16x32_bf16 v[110:113], v[144:147], v[208:211], v[110:113]
	v_mfma_f32_16x16x32_bf16 v[110:113], v[148:151], v[212:215], v[110:113]
	v_mfma_f32_16x16x32_bf16 v[106:109], v[156:159], v[208:211], v[106:109]
	v_mfma_f32_16x16x32_bf16 v[106:109], v[180:183], v[212:215], v[106:109]
	v_mfma_f32_16x16x32_bf16 v[94:97], v[144:147], v[216:219], v[94:97]
	v_mfma_f32_16x16x32_bf16 v[94:97], v[148:151], v[220:223], v[94:97]
	v_mfma_f32_16x16x32_bf16 v[90:93], v[156:159], v[216:219], v[90:93]
	v_mfma_f32_16x16x32_bf16 v[90:93], v[180:183], v[220:223], v[90:93]
	v_mfma_f32_16x16x32_bf16 v[78:81], v[144:147], v[224:227], v[78:81]
	v_mfma_f32_16x16x32_bf16 v[78:81], v[148:151], v[228:231], v[78:81]
	v_mfma_f32_16x16x32_bf16 v[74:77], v[156:159], v[224:227], v[74:77]
	v_mfma_f32_16x16x32_bf16 v[74:77], v[180:183], v[228:231], v[74:77]
	v_mfma_f32_16x16x32_bf16 v[118:121], v[184:187], v[200:203], v[118:121]
	v_mfma_f32_16x16x32_bf16 v[118:121], v[188:191], v[204:207], v[118:121]
	v_mfma_f32_16x16x32_bf16 v[114:117], v[192:195], v[200:203], v[114:117]
	v_mfma_f32_16x16x32_bf16 v[114:117], v[196:199], v[204:207], v[114:117]
	v_mfma_f32_16x16x32_bf16 v[102:105], v[184:187], v[208:211], v[102:105]
	v_mfma_f32_16x16x32_bf16 v[102:105], v[188:191], v[212:215], v[102:105]
	v_mfma_f32_16x16x32_bf16 v[98:101], v[192:195], v[208:211], v[98:101]
	v_mfma_f32_16x16x32_bf16 v[98:101], v[196:199], v[212:215], v[98:101]
	v_mfma_f32_16x16x32_bf16 v[86:89], v[184:187], v[216:219], v[86:89]
	v_mfma_f32_16x16x32_bf16 v[86:89], v[188:191], v[220:223], v[86:89]
	v_mfma_f32_16x16x32_bf16 v[82:85], v[192:195], v[216:219], v[82:85]
	v_mfma_f32_16x16x32_bf16 v[82:85], v[196:199], v[220:223], v[82:85]
	v_mfma_f32_16x16x32_bf16 v[70:73], v[184:187], v[224:227], v[70:73]
	v_mfma_f32_16x16x32_bf16 v[70:73], v[188:191], v[228:231], v[70:73]
	v_mfma_f32_16x16x32_bf16 v[66:69], v[192:195], v[224:227], v[66:69]
	v_mfma_f32_16x16x32_bf16 v[66:69], v[196:199], v[228:231], v[66:69]
	s_barrier
; #define PG8_STAGE(bufoff, gbase, voff) do { _Pragma("unroll") for (int _i = 0; _i < 2; ++_i) \
;         __builtin_amdgcn_global_load_lds((const unsigned*)((const char*)(gbase) + (voff)[_i]), (LAS unsigned*)(lds + (bufoff) + ldsw + _i * 8192), 16, 0, 0); } while (0)
; #define PG8_LDA(dst, b, h) do { _Pragma("unroll") for (int m = 0; m < 4; ++m) _Pragma("unroll") for (int k = 0; k < 2; ++k) dst[m][k] = *(const LAS bf16x8*)(lds + PG8_SA(b, h) + aoff + m * 2048 + k * 1024); } while (0)
; #define PG8_MMA(ai, bj, At, Bt) do { __builtin_amdgcn_s_setprio(1); _Pragma("unroll") for (int m = 0; m < 4; ++m) _Pragma("unroll") for (int n = 0; n < 2; ++n) _Pragma("unroll") for (int k = 0; k < 2; ++k) \
;         acc[ai][bj][m][n] = __builtin_amdgcn_mfma_f32_16x16x32_bf16(Bt[n][k], At[m][k], acc[ai][bj][m][n], 0, 0, 0); __builtin_amdgcn_s_setprio(0); } while (0)
; #define PG8_WAIT_V(n) asm volatile("s_waitcnt vmcnt(" #n ")" ::: "memory")
; #define PG8_WAIT_L(n) asm volatile("s_waitcnt lgkmcnt(" #n ")" ::: "memory")
; #define PG8_BAR __builtin_amdgcn_s_barrier()
; #define PG8_SCHED __builtin_amdgcn_sched_barrier(0)
; template <class Epi, bool ALIGN_EPI>
; __device__ __forceinline__ void gemm_phase(LAS unsigned char* lds, const Gemm g, const StaticOrder& S, const Epi& E) {
;     ...
;             PG8_LDA(At, 1, 1); PG8_STAGE(PG8_SB(1, 0), b3, voffB); PG8_STAGE(PG8_SB(1, 1), b3 + hstepB, voffB); PG8_STAGE(PG8_SA(1, 0), a3, voffA);
;             PG8_WAIT_V(8); PG8_WAIT_L(0); PG8_BAR; PG8_MMA(1, 0, At, B0); PG8_MMA(1, 1, At, B1); PG8_BAR; PG8_SCHED;
	s_add_i32 s20, s41, s24
	v_lshl_add_u64 v[152:153], v[152:153], 0, s[94:95]
	s_mov_b32 m0, s20
	ds_read_b128 v[200:203], v142 offset:49152
	ds_read_b128 v[204:207], v142 offset:50176
	ds_read_b128 v[208:211], v142 offset:51200
	ds_read_b128 v[212:215], v142 offset:52224
	ds_read_b128 v[216:219], v142 offset:53248
	ds_read_b128 v[220:223], v142 offset:54272
	ds_read_b128 v[224:227], v142 offset:55296
	ds_read_b128 v[228:231], v142 offset:56320
	global_load_lds_dwordx4 v[152:153], off
	s_add_i32 m0, s20, 0x2000
	s_add_u32 s18, s18, 0x40080
	v_lshl_add_u64 v[152:153], v[160:161], 0, s[94:95]
	s_addc_u32 s19, s19, 0
	s_add_i32 s20, s42, s24
	global_load_lds_dwordx4 v[152:153], off
	v_lshl_add_u64 v[152:153], s[18:19], 0, v[0:1]
	s_mov_b32 m0, s20
	s_nop 0
	global_load_lds_dwordx4 v[152:153], off
	v_lshl_add_u64 v[152:153], s[18:19], 0, v[134:135]
	s_add_i32 m0, s20, 0x2000
	s_nop 0
	global_load_lds_dwordx4 v[152:153], off
	v_lshl_add_u64 v[152:153], v[162:163], 0, s[94:95]
	s_mov_b32 m0, s4
	s_nop 0
	global_load_lds_dwordx4 v[152:153], off
	v_lshl_add_u64 v[152:153], v[170:171], 0, s[94:95]
	s_mov_b32 m0, s29
	s_nop 0
	global_load_lds_dwordx4 v[152:153], off
	s_waitcnt vmcnt(8)
	s_waitcnt lgkmcnt(0)
	s_barrier
	s_waitcnt lgkmcnt(0)
	v_mfma_f32_16x16x32_bf16 v[62:65], v[144:147], v[200:203], v[62:65]
	v_mfma_f32_16x16x32_bf16 v[62:65], v[148:151], v[204:207], v[62:65]
	v_mfma_f32_16x16x32_bf16 v[58:61], v[156:159], v[200:203], v[58:61]
	v_mfma_f32_16x16x32_bf16 v[58:61], v[180:183], v[204:207], v[58:61]
	v_mfma_f32_16x16x32_bf16 v[46:49], v[144:147], v[208:211], v[46:49]
	v_mfma_f32_16x16x32_bf16 v[46:49], v[148:151], v[212:215], v[46:49]
	v_mfma_f32_16x16x32_bf16 v[42:45], v[156:159], v[208:211], v[42:45]
	v_mfma_f32_16x16x32_bf16 v[42:45], v[180:183], v[212:215], v[42:45]
	v_mfma_f32_16x16x32_bf16 v[30:33], v[144:147], v[216:219], v[30:33]
	v_mfma_f32_16x16x32_bf16 v[30:33], v[148:151], v[220:223], v[30:33]
	v_mfma_f32_16x16x32_bf16 v[26:29], v[156:159], v[216:219], v[26:29]
	v_mfma_f32_16x16x32_bf16 v[26:29], v[180:183], v[220:223], v[26:29]
	v_mfma_f32_16x16x32_bf16 v[14:17], v[144:147], v[224:227], v[14:17]
	v_mfma_f32_16x16x32_bf16 v[14:17], v[148:151], v[228:231], v[14:17]
	v_mfma_f32_16x16x32_bf16 v[10:13], v[156:159], v[224:227], v[10:13]
	v_mfma_f32_16x16x32_bf16 v[10:13], v[180:183], v[228:231], v[10:13]
	v_mfma_f32_16x16x32_bf16 v[54:57], v[184:187], v[200:203], v[54:57]
	v_mfma_f32_16x16x32_bf16 v[54:57], v[188:191], v[204:207], v[54:57]
	v_mfma_f32_16x16x32_bf16 v[50:53], v[192:195], v[200:203], v[50:53]
	v_mfma_f32_16x16x32_bf16 v[50:53], v[196:199], v[204:207], v[50:53]
	v_mfma_f32_16x16x32_bf16 v[38:41], v[184:187], v[208:211], v[38:41]
	v_mfma_f32_16x16x32_bf16 v[38:41], v[188:191], v[212:215], v[38:41]
	v_mfma_f32_16x16x32_bf16 v[34:37], v[192:195], v[208:211], v[34:37]
	v_mfma_f32_16x16x32_bf16 v[34:37], v[196:199], v[212:215], v[34:37]
	v_mfma_f32_16x16x32_bf16 v[22:25], v[184:187], v[216:219], v[22:25]
	v_mfma_f32_16x16x32_bf16 v[22:25], v[188:191], v[220:223], v[22:25]
	v_mfma_f32_16x16x32_bf16 v[18:21], v[192:195], v[216:219], v[18:21]
	v_mfma_f32_16x16x32_bf16 v[18:21], v[196:199], v[220:223], v[18:21]
	v_mfma_f32_16x16x32_bf16 v[6:9], v[184:187], v[224:227], v[6:9]
	v_mfma_f32_16x16x32_bf16 v[6:9], v[188:191], v[228:231], v[6:9]
	v_mfma_f32_16x16x32_bf16 v[2:5], v[192:195], v[224:227], v[2:5]
	v_mfma_f32_16x16x32_bf16 v[2:5], v[196:199], v[228:231], v[2:5]
	s_cmp_lg_u32 s40, 12
	s_cbranch_scc1 .Ltail_bar_4
	s_cmp_eq_u64 s[8:9], 0
	s_cbranch_scc1 .Ltail_skip_4

; #define PG8_STAGE(bufoff, gbase, voff) do { _Pragma("unroll") for (int _i = 0; _i < 2; ++_i) \
;         __builtin_amdgcn_global_load_lds((const unsigned*)((const char*)(gbase) + (voff)[_i]), (LAS unsigned*)(lds + (bufoff) + ldsw + _i * 8192), 16, 0, 0); } while (0)
; #define PG8_LDA(dst, b, h) do { _Pragma("unroll") for (int m = 0; m < 4; ++m) _Pragma("unroll") for (int k = 0; k < 2; ++k) dst[m][k] = *(const LAS bf16x8*)(lds + PG8_SA(b, h) + aoff + m * 2048 + k * 1024); } while (0)
; #define PG8_LDB(dst, b, h) do { _Pragma("unroll") for (int n = 0; n < 2; ++n) _Pragma("unroll") for (int k = 0; k < 2; ++k) dst[n][k] = *(const LAS bf16x8*)(lds + PG8_SB(b, h) + boff + n * 2048 + k * 1024); } while (0)
; #define PG8_MMA(ai, bj, At, Bt) do { __builtin_amdgcn_s_setprio(1); _Pragma("unroll") for (int m = 0; m < 4; ++m) _Pragma("unroll") for (int n = 0; n < 2; ++n) _Pragma("unroll") for (int k = 0; k < 2; ++k) \
;         acc[ai][bj][m][n] = __builtin_amdgcn_mfma_f32_16x16x32_bf16(Bt[n][k], At[m][k], acc[ai][bj][m][n], 0, 0, 0); __builtin_amdgcn_s_setprio(0); } while (0)
; #define PG8_WAIT_V(n) asm volatile("s_waitcnt vmcnt(" #n ")" ::: "memory")
; #define PG8_WAIT_L(n) asm volatile("s_waitcnt lgkmcnt(" #n ")" ::: "memory")
; #define PG8_BAR __builtin_amdgcn_s_barrier()
; #define PG8_SCHED __builtin_amdgcn_sched_barrier(0)
; template <class Epi, bool ALIGN_EPI>
; __device__ __forceinline__ void gemm_phase(LAS unsigned char* lds, const Gemm g, const StaticOrder& S, const Epi& E) {
;     ...
;             const bool last = (t == nt - 2);
;             const char* a1 = cA + (size_t)(t + 1) * kstep;
;             const char* a2 = last ? nA : cA + (size_t)(t + 2) * kstep; const char* b2 = last ? nB : cB + (size_t)(t + 2) * kstep;
;             const char* a3 = a2 + kstep; const char* b3 = b2 + kstep;
;             PG8_LDB(B0, 0, 0); PG8_LDB(B1, 0, 1); PG8_SCHED; PG8_LDA(At, 0, 0); PG8_STAGE(PG8_SA(1, 1), a1 + hstepA, voffA);
;             PG8_WAIT_V(8); PG8_WAIT_L(0); PG8_BAR; PG8_MMA(0, 0, At, B0); PG8_MMA(0, 1, At, B1); PG8_BAR; PG8_SCHED;
;             PG8_LDA(At, 0, 1); PG8_STAGE(PG8_SB(0, 0), b2, voffB); PG8_STAGE(PG8_SB(0, 1), b2 + hstepB, voffB); PG8_STAGE(PG8_SA(0, 0), a2, voffA);
;             PG8_WAIT_V(8); PG8_WAIT_L(0); PG8_BAR; PG8_MMA(1, 0, At, B0); PG8_MMA(1, 1, At, B1); PG8_BAR; PG8_SCHED;
.LBB0_603:
	s_add_u32 s24, s6, 0xfffc0080
	s_addc_u32 s25, s7, -1
	s_add_i32 s45, 0, 0x10000
	s_cmp_eq_u32 s44, 12
	s_cselect_b32 s27, s9, s25
	s_cselect_b32 s26, s40, s24
	v_add_u32_e32 v0, s45, v158
	s_cselect_b32 s25, s15, s43
	s_cselect_b32 s24, s41, s42
	s_add_i32 s48, 0, 0x14000
	ds_read_b128 v[142:145], v0
	ds_read_b128 v[146:149], v0 offset:1024
	ds_read_b128 v[150:153], v0 offset:2048
	ds_read_b128 v[180:183], v0 offset:3072
	v_add_u32_e32 v0, s48, v158
	ds_read_b128 v[184:187], v0
	ds_read_b128 v[188:191], v0 offset:1024
	ds_read_b128 v[192:195], v0 offset:2048
	ds_read_b128 v[196:199], v0 offset:3072
	v_lshl_add_u64 v[156:157], s[6:7], 0, v[138:139]
	s_add_i32 m0, s30, 0xc000
	ds_read_b128 v[200:203], v160
	ds_read_b128 v[204:207], v160 offset:1024
	ds_read_b128 v[208:211], v160 offset:2048
	ds_read_b128 v[212:215], v160 offset:3072
	ds_read_b128 v[216:219], v160 offset:4096
	ds_read_b128 v[220:223], v160 offset:5120
	ds_read_b128 v[224:227], v160 offset:6144
	ds_read_b128 v[228:231], v160 offset:7168
	global_load_lds_dwordx4 v[156:157], off
	v_lshl_add_u64 v[156:157], s[6:7], 0, v[140:141]
	s_add_i32 m0, s30, 0xe000
	s_nop 0
	global_load_lds_dwordx4 v[156:157], off
	s_waitcnt vmcnt(8)
	s_waitcnt lgkmcnt(0)
	s_barrier
	s_waitcnt lgkmcnt(0)
	v_mfma_f32_16x16x32_bf16 v[66:69], v[142:145], v[200:203], v[66:69]
	v_mfma_f32_16x16x32_bf16 v[66:69], v[146:149], v[204:207], v[66:69]
	v_mfma_f32_16x16x32_bf16 v[58:61], v[150:153], v[200:203], v[58:61]
	v_mfma_f32_16x16x32_bf16 v[58:61], v[180:183], v[204:207], v[58:61]
	v_mfma_f32_16x16x32_bf16 v[54:57], v[142:145], v[208:211], v[54:57]
	v_mfma_f32_16x16x32_bf16 v[54:57], v[146:149], v[212:215], v[54:57]
	v_mfma_f32_16x16x32_bf16 v[50:53], v[150:153], v[208:211], v[50:53]
	v_mfma_f32_16x16x32_bf16 v[50:53], v[180:183], v[212:215], v[50:53]
	v_mfma_f32_16x16x32_bf16 v[46:49], v[142:145], v[216:219], v[46:49]
	v_mfma_f32_16x16x32_bf16 v[46:49], v[146:149], v[220:223], v[46:49]
	v_mfma_f32_16x16x32_bf16 v[42:45], v[150:153], v[216:219], v[42:45]
	v_mfma_f32_16x16x32_bf16 v[42:45], v[180:183], v[220:223], v[42:45]
	v_mfma_f32_16x16x32_bf16 v[38:41], v[142:145], v[224:227], v[38:41]
	v_mfma_f32_16x16x32_bf16 v[38:41], v[146:149], v[228:231], v[38:41]
	v_mfma_f32_16x16x32_bf16 v[34:37], v[150:153], v[224:227], v[34:37]
	v_mfma_f32_16x16x32_bf16 v[34:37], v[180:183], v[228:231], v[34:37]
	v_mfma_f32_16x16x32_bf16 v[126:129], v[184:187], v[200:203], v[126:129]
	v_mfma_f32_16x16x32_bf16 v[126:129], v[188:191], v[204:207], v[126:129]
	v_mfma_f32_16x16x32_bf16 v[122:125], v[192:195], v[200:203], v[122:125]
	v_mfma_f32_16x16x32_bf16 v[122:125], v[196:199], v[204:207], v[122:125]
	v_mfma_f32_16x16x32_bf16 v[118:121], v[184:187], v[208:211], v[118:121]
	v_mfma_f32_16x16x32_bf16 v[118:121], v[188:191], v[212:215], v[118:121]
	v_mfma_f32_16x16x32_bf16 v[114:117], v[192:195], v[208:211], v[114:117]
	v_mfma_f32_16x16x32_bf16 v[114:117], v[196:199], v[212:215], v[114:117]
	v_mfma_f32_16x16x32_bf16 v[110:113], v[184:187], v[216:219], v[110:113]
	v_mfma_f32_16x16x32_bf16 v[110:113], v[188:191], v[220:223], v[110:113]
	v_mfma_f32_16x16x32_bf16 v[106:109], v[192:195], v[216:219], v[106:109]
	v_mfma_f32_16x16x32_bf16 v[106:109], v[196:199], v[220:223], v[106:109]
	v_mfma_f32_16x16x32_bf16 v[102:105], v[184:187], v[224:227], v[102:105]
	v_mfma_f32_16x16x32_bf16 v[102:105], v[188:191], v[228:231], v[102:105]
	v_mfma_f32_16x16x32_bf16 v[98:101], v[192:195], v[224:227], v[98:101]
	v_mfma_f32_16x16x32_bf16 v[98:101], v[196:199], v[228:231], v[98:101]
	s_barrier
	s_add_i32 s45, s45, s29
	v_lshl_add_u64 v[156:157], s[24:25], 0, v[132:133]
	s_mov_b32 m0, s45
	ds_read_b128 v[200:203], v160 offset:16384
	ds_read_b128 v[204:207], v160 offset:17408
	ds_read_b128 v[208:211], v160 offset:18432
	ds_read_b128 v[212:215], v160 offset:19456
	ds_read_b128 v[216:219], v160 offset:20480
	ds_read_b128 v[220:223], v160 offset:21504
	ds_read_b128 v[224:227], v160 offset:22528
	ds_read_b128 v[228:231], v160 offset:23552
	global_load_lds_dwordx4 v[156:157], off
	s_add_i32 m0, s45, 0x2000
	s_add_u32 s46, s24, 0x40000
	v_lshl_add_u64 v[162:163], s[24:25], 0, v[136:137]
	s_addc_u32 s47, s25, 0
	s_add_i32 s45, s48, s29
	global_load_lds_dwordx4 v[162:163], off
	v_lshl_add_u64 v[170:171], s[46:47], 0, v[132:133]
	s_mov_b32 m0, s45
	v_lshl_add_u64 v[172:173], s[26:27], 0, v[134:135]
	global_load_lds_dwordx4 v[170:171], off
	v_lshl_add_u64 v[170:171], s[46:47], 0, v[136:137]
	s_add_i32 m0, s45, 0x2000
	s_nop 0
	global_load_lds_dwordx4 v[170:171], off
	v_lshl_add_u64 v[170:171], s[26:27], 0, v[130:131]
	s_mov_b32 m0, s30
	s_nop 0
	global_load_lds_dwordx4 v[170:171], off
	s_mov_b32 m0, s31
	s_nop 0
	global_load_lds_dwordx4 v[172:173], off
	s_waitcnt vmcnt(8)
	s_waitcnt lgkmcnt(0)
	s_barrier
; #define PG8_STAGE(bufoff, gbase, voff) do { _Pragma("unroll") for (int _i = 0; _i < 2; ++_i) \
;         __builtin_amdgcn_global_load_lds((const unsigned*)((const char*)(gbase) + (voff)[_i]), (LAS unsigned*)(lds + (bufoff) + ldsw + _i * 8192), 16, 0, 0); } while (0)
; #define PG8_LDA(dst, b, h) do { _Pragma("unroll") for (int m = 0; m < 4; ++m) _Pragma("unroll") for (int k = 0; k < 2; ++k) dst[m][k] = *(const LAS bf16x8*)(lds + PG8_SA(b, h) + aoff + m * 2048 + k * 1024); } while (0)
; #define PG8_LDB(dst, b, h) do { _Pragma("unroll") for (int n = 0; n < 2; ++n) _Pragma("unroll") for (int k = 0; k < 2; ++k) dst[n][k] = *(const LAS bf16x8*)(lds + PG8_SB(b, h) + boff + n * 2048 + k * 1024); } while (0)
; #define PG8_MMA(ai, bj, At, Bt) do { __builtin_amdgcn_s_setprio(1); _Pragma("unroll") for (int m = 0; m < 4; ++m) _Pragma("unroll") for (int n = 0; n < 2; ++n) _Pragma("unroll") for (int k = 0; k < 2; ++k) \
;         acc[ai][bj][m][n] = __builtin_amdgcn_mfma_f32_16x16x32_bf16(Bt[n][k], At[m][k], acc[ai][bj][m][n], 0, 0, 0); __builtin_amdgcn_s_setprio(0); } while (0)
; #define PG8_WAIT_V(n) asm volatile("s_waitcnt vmcnt(" #n ")" ::: "memory")
; #define PG8_WAIT_L(n) asm volatile("s_waitcnt lgkmcnt(" #n ")" ::: "memory")
; #define PG8_BAR __builtin_amdgcn_s_barrier()
; #define PG8_SCHED __builtin_amdgcn_sched_barrier(0)
; template <class Epi, bool ALIGN_EPI>
; __device__ __forceinline__ void gemm_phase(LAS unsigned char* lds, const Gemm g, const StaticOrder& S, const Epi& E) {
;     ...
;             PG8_WAIT_V(8); PG8_WAIT_L(0); PG8_BAR; PG8_MMA(1, 0, At, B0); PG8_MMA(1, 1, At, B1); PG8_BAR; PG8_SCHED;
;             PG8_LDB(B0, 1, 0); PG8_LDB(B1, 1, 1); PG8_SCHED; PG8_LDA(At, 1, 0); PG8_STAGE(PG8_SA(0, 1), a2 + hstepA, voffA);
;             PG8_WAIT_V(8); PG8_WAIT_L(0); PG8_BAR; PG8_MMA(0, 0, At, B0); PG8_MMA(0, 1, At, B1); PG8_BAR; PG8_SCHED;
	s_waitcnt lgkmcnt(0)
	v_mfma_f32_16x16x32_bf16 v[30:33], v[142:145], v[200:203], v[30:33]
	v_mfma_f32_16x16x32_bf16 v[30:33], v[146:149], v[204:207], v[30:33]
	v_mfma_f32_16x16x32_bf16 v[26:29], v[150:153], v[200:203], v[26:29]
	v_mfma_f32_16x16x32_bf16 v[26:29], v[180:183], v[204:207], v[26:29]
	v_mfma_f32_16x16x32_bf16 v[22:25], v[142:145], v[208:211], v[22:25]
	v_mfma_f32_16x16x32_bf16 v[22:25], v[146:149], v[212:215], v[22:25]
	v_mfma_f32_16x16x32_bf16 v[18:21], v[150:153], v[208:211], v[18:21]
	v_mfma_f32_16x16x32_bf16 v[18:21], v[180:183], v[212:215], v[18:21]
	v_mfma_f32_16x16x32_bf16 v[14:17], v[142:145], v[216:219], v[14:17]
	v_mfma_f32_16x16x32_bf16 v[14:17], v[146:149], v[220:223], v[14:17]
	v_mfma_f32_16x16x32_bf16 v[10:13], v[150:153], v[216:219], v[10:13]
	v_mfma_f32_16x16x32_bf16 v[10:13], v[180:183], v[220:223], v[10:13]
	v_mfma_f32_16x16x32_bf16 v[6:9], v[142:145], v[224:227], v[6:9]
	v_mfma_f32_16x16x32_bf16 v[6:9], v[146:149], v[228:231], v[6:9]
	v_mfma_f32_16x16x32_bf16 v[2:5], v[150:153], v[224:227], v[2:5]
	v_mfma_f32_16x16x32_bf16 v[2:5], v[180:183], v[228:231], v[2:5]
	v_mfma_f32_16x16x32_bf16 v[94:97], v[184:187], v[200:203], v[94:97]
	v_mfma_f32_16x16x32_bf16 v[94:97], v[188:191], v[204:207], v[94:97]
	v_mfma_f32_16x16x32_bf16 v[90:93], v[192:195], v[200:203], v[90:93]
	v_mfma_f32_16x16x32_bf16 v[90:93], v[196:199], v[204:207], v[90:93]
	v_mfma_f32_16x16x32_bf16 v[86:89], v[184:187], v[208:211], v[86:89]
	v_mfma_f32_16x16x32_bf16 v[86:89], v[188:191], v[212:215], v[86:89]
	v_mfma_f32_16x16x32_bf16 v[82:85], v[192:195], v[208:211], v[82:85]
	v_mfma_f32_16x16x32_bf16 v[82:85], v[196:199], v[212:215], v[82:85]
	v_mfma_f32_16x16x32_bf16 v[78:81], v[184:187], v[216:219], v[78:81]
	v_mfma_f32_16x16x32_bf16 v[78:81], v[188:191], v[220:223], v[78:81]
	v_mfma_f32_16x16x32_bf16 v[74:77], v[192:195], v[216:219], v[74:77]
	v_mfma_f32_16x16x32_bf16 v[74:77], v[196:199], v[220:223], v[74:77]
	v_mfma_f32_16x16x32_bf16 v[70:73], v[184:187], v[224:227], v[70:73]
	v_mfma_f32_16x16x32_bf16 v[70:73], v[188:191], v[228:231], v[70:73]
	v_mfma_f32_16x16x32_bf16 v[62:65], v[192:195], v[224:227], v[62:65]
	v_mfma_f32_16x16x32_bf16 v[62:65], v[196:199], v[228:231], v[62:65]
	s_barrier
	s_add_i32 s45, 0, 0x18000
	v_add_u32_e32 v0, s45, v158
	s_add_i32 s46, 0, 0x1c000
	ds_read_b128 v[142:145], v0
	ds_read_b128 v[146:149], v0 offset:1024
	ds_read_b128 v[150:153], v0 offset:2048
	ds_read_b128 v[180:183], v0 offset:3072
	v_add_u32_e32 v0, s46, v158
	ds_read_b128 v[184:187], v0
	ds_read_b128 v[188:191], v0 offset:1024
	ds_read_b128 v[192:195], v0 offset:2048
	ds_read_b128 v[196:199], v0 offset:3072
	s_add_u32 s26, s26, 0x40000
	s_addc_u32 s27, s27, 0
	s_mov_b32 m0, s34
	v_lshl_add_u64 v[232:233], s[26:27], 0, v[130:131]
	ds_read_b128 v[200:203], v160 offset:32768
	ds_read_b128 v[204:207], v160 offset:33792
	ds_read_b128 v[208:211], v160 offset:34816
	ds_read_b128 v[212:215], v160 offset:35840
	ds_read_b128 v[216:219], v160 offset:36864
	ds_read_b128 v[220:223], v160 offset:37888
	ds_read_b128 v[224:227], v160 offset:38912
	ds_read_b128 v[228:231], v160 offset:39936
	global_load_lds_dwordx4 v[232:233], off
	v_lshl_add_u64 v[232:233], s[26:27], 0, v[134:135]
	s_mov_b32 m0, s35
	s_nop 0
	global_load_lds_dwordx4 v[232:233], off
	s_waitcnt vmcnt(8)
	s_waitcnt lgkmcnt(0)
	s_barrier
	s_waitcnt lgkmcnt(0)
	v_mfma_f32_16x16x32_bf16 v[66:69], v[142:145], v[200:203], v[66:69]
	v_mfma_f32_16x16x32_bf16 v[66:69], v[146:149], v[204:207], v[66:69]
	v_mfma_f32_16x16x32_bf16 v[58:61], v[150:153], v[200:203], v[58:61]
	v_mfma_f32_16x16x32_bf16 v[58:61], v[180:183], v[204:207], v[58:61]
	v_mfma_f32_16x16x32_bf16 v[54:57], v[142:145], v[208:211], v[54:57]
	v_mfma_f32_16x16x32_bf16 v[54:57], v[146:149], v[212:215], v[54:57]
	v_mfma_f32_16x16x32_bf16 v[50:53], v[150:153], v[208:211], v[50:53]
	v_mfma_f32_16x16x32_bf16 v[50:53], v[180:183], v[212:215], v[50:53]
	v_mfma_f32_16x16x32_bf16 v[46:49], v[142:145], v[216:219], v[46:49]
	v_mfma_f32_16x16x32_bf16 v[46:49], v[146:149], v[220:223], v[46:49]
	v_mfma_f32_16x16x32_bf16 v[42:45], v[150:153], v[216:219], v[42:45]
	v_mfma_f32_16x16x32_bf16 v[42:45], v[180:183], v[220:223], v[42:45]
	v_mfma_f32_16x16x32_bf16 v[38:41], v[142:145], v[224:227], v[38:41]
	v_mfma_f32_16x16x32_bf16 v[38:41], v[146:149], v[228:231], v[38:41]
	v_mfma_f32_16x16x32_bf16 v[34:37], v[150:153], v[224:227], v[34:37]
	v_mfma_f32_16x16x32_bf16 v[34:37], v[180:183], v[228:231], v[34:37]
	v_mfma_f32_16x16x32_bf16 v[126:129], v[184:187], v[200:203], v[126:129]
	v_mfma_f32_16x16x32_bf16 v[126:129], v[188:191], v[204:207], v[126:129]
	v_mfma_f32_16x16x32_bf16 v[122:125], v[192:195], v[200:203], v[122:125]
	v_mfma_f32_16x16x32_bf16 v[122:125], v[196:199], v[204:207], v[122:125]
	v_mfma_f32_16x16x32_bf16 v[118:121], v[184:187], v[208:211], v[118:121]
	v_mfma_f32_16x16x32_bf16 v[118:121], v[188:191], v[212:215], v[118:121]
	v_mfma_f32_16x16x32_bf16 v[114:117], v[192:195], v[208:211], v[114:117]
	v_mfma_f32_16x16x32_bf16 v[114:117], v[196:199], v[212:215], v[114:117]
	v_mfma_f32_16x16x32_bf16 v[110:113], v[184:187], v[216:219], v[110:113]
	v_mfma_f32_16x16x32_bf16 v[110:113], v[188:191], v[220:223], v[110:113]
	v_mfma_f32_16x16x32_bf16 v[106:109], v[192:195], v[216:219], v[106:109]
	v_mfma_f32_16x16x32_bf16 v[106:109], v[196:199], v[220:223], v[106:109]
	v_mfma_f32_16x16x32_bf16 v[102:105], v[184:187], v[224:227], v[102:105]
	v_mfma_f32_16x16x32_bf16 v[102:105], v[188:191], v[228:231], v[102:105]
	v_mfma_f32_16x16x32_bf16 v[98:101], v[192:195], v[224:227], v[98:101]
	v_mfma_f32_16x16x32_bf16 v[98:101], v[196:199], v[228:231], v[98:101]
	s_barrier
; #define PG8_STAGE(bufoff, gbase, voff) do { _Pragma("unroll") for (int _i = 0; _i < 2; ++_i) \
;         __builtin_amdgcn_global_load_lds((const unsigned*)((const char*)(gbase) + (voff)[_i]), (LAS unsigned*)(lds + (bufoff) + ldsw + _i * 8192), 16, 0, 0); } while (0)
; #define PG8_LDA(dst, b, h) do { _Pragma("unroll") for (int m = 0; m < 4; ++m) _Pragma("unroll") for (int k = 0; k < 2; ++k) dst[m][k] = *(const LAS bf16x8*)(lds + PG8_SA(b, h) + aoff + m * 2048 + k * 1024); } while (0)
; #define PG8_MMA(ai, bj, At, Bt) do { __builtin_amdgcn_s_setprio(1); _Pragma("unroll") for (int m = 0; m < 4; ++m) _Pragma("unroll") for (int n = 0; n < 2; ++n) _Pragma("unroll") for (int k = 0; k < 2; ++k) \
;         acc[ai][bj][m][n] = __builtin_amdgcn_mfma_f32_16x16x32_bf16(Bt[n][k], At[m][k], acc[ai][bj][m][n], 0, 0, 0); __builtin_amdgcn_s_setprio(0); } while (0)
; #define PG8_WAIT_V(n) asm volatile("s_waitcnt vmcnt(" #n ")" ::: "memory")
; #define PG8_WAIT_L(n) asm volatile("s_waitcnt lgkmcnt(" #n ")" ::: "memory")
; #define PG8_BAR __builtin_amdgcn_s_barrier()
; #define PG8_SCHED __builtin_amdgcn_sched_barrier(0)
; template <class Epi, bool ALIGN_EPI>
; __device__ __forceinline__ void gemm_phase(LAS unsigned char* lds, const Gemm g, const StaticOrder& S, const Epi& E) {
;     ...
;             PG8_LDA(At, 1, 1); PG8_STAGE(PG8_SB(1, 0), b3, voffB); PG8_STAGE(PG8_SB(1, 1), b3 + hstepB, voffB); PG8_STAGE(PG8_SA(1, 0), a3, voffA);
;             PG8_WAIT_V(8); PG8_WAIT_L(0); PG8_BAR; PG8_MMA(1, 0, At, B0); PG8_MMA(1, 1, At, B1); PG8_BAR; PG8_SCHED;
	s_add_i32 s26, s45, s29
	v_lshl_add_u64 v[156:157], v[156:157], 0, s[94:95]
	s_mov_b32 m0, s26
	ds_read_b128 v[200:203], v160 offset:49152
	ds_read_b128 v[204:207], v160 offset:50176
	ds_read_b128 v[208:211], v160 offset:51200
	ds_read_b128 v[212:215], v160 offset:52224
	ds_read_b128 v[216:219], v160 offset:53248
	ds_read_b128 v[220:223], v160 offset:54272
	ds_read_b128 v[224:227], v160 offset:55296
	ds_read_b128 v[228:231], v160 offset:56320
	global_load_lds_dwordx4 v[156:157], off
	s_add_i32 m0, s26, 0x2000
	s_add_u32 s24, s24, 0x40080
	v_lshl_add_u64 v[156:157], v[162:163], 0, s[94:95]
	s_addc_u32 s25, s25, 0
	s_add_i32 s26, s46, s29
	global_load_lds_dwordx4 v[156:157], off
	v_lshl_add_u64 v[156:157], s[24:25], 0, v[132:133]
	s_mov_b32 m0, s26
	s_nop 0
	global_load_lds_dwordx4 v[156:157], off
	v_lshl_add_u64 v[156:157], s[24:25], 0, v[136:137]
	s_add_i32 m0, s26, 0x2000
	s_nop 0
	global_load_lds_dwordx4 v[156:157], off
	v_lshl_add_u64 v[156:157], v[170:171], 0, s[94:95]
	s_mov_b32 m0, s36
	s_nop 0
	global_load_lds_dwordx4 v[156:157], off
	v_lshl_add_u64 v[156:157], v[172:173], 0, s[94:95]
	s_mov_b32 m0, s37
	s_nop 0
	global_load_lds_dwordx4 v[156:157], off
	s_waitcnt vmcnt(8)
	s_waitcnt lgkmcnt(0)
	s_barrier
	s_waitcnt lgkmcnt(0)
	v_mfma_f32_16x16x32_bf16 v[30:33], v[142:145], v[200:203], v[30:33]
	v_mfma_f32_16x16x32_bf16 v[30:33], v[146:149], v[204:207], v[30:33]
	v_mfma_f32_16x16x32_bf16 v[26:29], v[150:153], v[200:203], v[26:29]
	v_mfma_f32_16x16x32_bf16 v[26:29], v[180:183], v[204:207], v[26:29]
	v_mfma_f32_16x16x32_bf16 v[22:25], v[142:145], v[208:211], v[22:25]
	v_mfma_f32_16x16x32_bf16 v[22:25], v[146:149], v[212:215], v[22:25]
	v_mfma_f32_16x16x32_bf16 v[18:21], v[150:153], v[208:211], v[18:21]
	v_mfma_f32_16x16x32_bf16 v[18:21], v[180:183], v[212:215], v[18:21]
	v_mfma_f32_16x16x32_bf16 v[14:17], v[142:145], v[216:219], v[14:17]
	v_mfma_f32_16x16x32_bf16 v[14:17], v[146:149], v[220:223], v[14:17]
	v_mfma_f32_16x16x32_bf16 v[10:13], v[150:153], v[216:219], v[10:13]
	v_mfma_f32_16x16x32_bf16 v[10:13], v[180:183], v[220:223], v[10:13]
	v_mfma_f32_16x16x32_bf16 v[6:9], v[142:145], v[224:227], v[6:9]
	v_mfma_f32_16x16x32_bf16 v[6:9], v[146:149], v[228:231], v[6:9]
	v_mfma_f32_16x16x32_bf16 v[2:5], v[150:153], v[224:227], v[2:5]
	v_mfma_f32_16x16x32_bf16 v[2:5], v[180:183], v[228:231], v[2:5]
	v_mfma_f32_16x16x32_bf16 v[94:97], v[184:187], v[200:203], v[94:97]
	v_mfma_f32_16x16x32_bf16 v[94:97], v[188:191], v[204:207], v[94:97]
	v_mfma_f32_16x16x32_bf16 v[90:93], v[192:195], v[200:203], v[90:93]
	v_mfma_f32_16x16x32_bf16 v[90:93], v[196:199], v[204:207], v[90:93]
	v_mfma_f32_16x16x32_bf16 v[86:89], v[184:187], v[208:211], v[86:89]
	v_mfma_f32_16x16x32_bf16 v[86:89], v[188:191], v[212:215], v[86:89]
	v_mfma_f32_16x16x32_bf16 v[82:85], v[192:195], v[208:211], v[82:85]
	v_mfma_f32_16x16x32_bf16 v[82:85], v[196:199], v[212:215], v[82:85]
	v_mfma_f32_16x16x32_bf16 v[78:81], v[184:187], v[216:219], v[78:81]
	v_mfma_f32_16x16x32_bf16 v[78:81], v[188:191], v[220:223], v[78:81]
	v_mfma_f32_16x16x32_bf16 v[74:77], v[192:195], v[216:219], v[74:77]
	v_mfma_f32_16x16x32_bf16 v[74:77], v[196:199], v[220:223], v[74:77]
	v_mfma_f32_16x16x32_bf16 v[70:73], v[184:187], v[224:227], v[70:73]
	v_mfma_f32_16x16x32_bf16 v[70:73], v[188:191], v[228:231], v[70:73]
	v_mfma_f32_16x16x32_bf16 v[62:65], v[192:195], v[224:227], v[62:65]
	v_mfma_f32_16x16x32_bf16 v[62:65], v[196:199], v[228:231], v[62:65]
	s_cmp_lg_u32 s44, 12
	s_cbranch_scc1 .Ltail_bar_3
	s_cmp_eq_u64 s[12:13], 0
	s_cbranch_scc1 .Ltail_skip_3

; #define PG8_STAGE(bufoff, gbase, voff) do { _Pragma("unroll") for (int _i = 0; _i < 2; ++_i) \
;         __builtin_amdgcn_global_load_lds((const unsigned*)((const char*)(gbase) + (voff)[_i]), (LAS unsigned*)(lds + (bufoff) + ldsw + _i * 8192), 16, 0, 0); } while (0)
; #define PG8_LDA(dst, b, h) do { _Pragma("unroll") for (int m = 0; m < 4; ++m) _Pragma("unroll") for (int k = 0; k < 2; ++k) dst[m][k] = *(const LAS bf16x8*)(lds + PG8_SA(b, h) + aoff + m * 2048 + k * 1024); } while (0)
; #define PG8_LDB(dst, b, h) do { _Pragma("unroll") for (int n = 0; n < 2; ++n) _Pragma("unroll") for (int k = 0; k < 2; ++k) dst[n][k] = *(const LAS bf16x8*)(lds + PG8_SB(b, h) + boff + n * 2048 + k * 1024); } while (0)
; #define PG8_MMA(ai, bj, At, Bt) do { __builtin_amdgcn_s_setprio(1); _Pragma("unroll") for (int m = 0; m < 4; ++m) _Pragma("unroll") for (int n = 0; n < 2; ++n) _Pragma("unroll") for (int k = 0; k < 2; ++k) \
;         acc[ai][bj][m][n] = __builtin_amdgcn_mfma_f32_16x16x32_bf16(Bt[n][k], At[m][k], acc[ai][bj][m][n], 0, 0, 0); __builtin_amdgcn_s_setprio(0); } while (0)
; #define PG8_WAIT_V(n) asm volatile("s_waitcnt vmcnt(" #n ")" ::: "memory")
; #define PG8_WAIT_L(n) asm volatile("s_waitcnt lgkmcnt(" #n ")" ::: "memory")
; #define PG8_BAR __builtin_amdgcn_s_barrier()
; #define PG8_SCHED __builtin_amdgcn_sched_barrier(0)
; template <class Epi, bool ALIGN_EPI>
; __device__ __forceinline__ void gemm_phase(LAS unsigned char* lds, const Gemm g, const StaticOrder& S, const Epi& E) {
;     ...
;             const bool last = (t == nt - 2);
;             const char* a1 = cA + (size_t)(t + 1) * kstep;
;             const char* a2 = last ? nA : cA + (size_t)(t + 2) * kstep; const char* b2 = last ? nB : cB + (size_t)(t + 2) * kstep;
;             const char* a3 = a2 + kstep; const char* b3 = b2 + kstep;
;             PG8_LDB(B0, 0, 0); PG8_LDB(B1, 0, 1); PG8_SCHED; PG8_LDA(At, 0, 0); PG8_STAGE(PG8_SA(1, 1), a1 + hstepA, voffA);
;             PG8_WAIT_V(8); PG8_WAIT_L(0); PG8_BAR; PG8_MMA(0, 0, At, B0); PG8_MMA(0, 1, At, B1); PG8_BAR; PG8_SCHED;
;             PG8_LDA(At, 0, 1); PG8_STAGE(PG8_SB(0, 0), b2, voffB); PG8_STAGE(PG8_SB(0, 1), b2 + hstepB, voffB); PG8_STAGE(PG8_SA(0, 0), a2, voffA);
;             PG8_WAIT_V(8); PG8_WAIT_L(0); PG8_BAR; PG8_MMA(1, 0, At, B0); PG8_MMA(1, 1, At, B1); PG8_BAR; PG8_SCHED;
.LBB0_719:
	s_add_u32 s10, s8, 0x100
	s_addc_u32 s11, s9, 0
	s_add_i32 s46, 0, 0x10000
	s_cmp_eq_u32 s45, 40
	s_cselect_b32 s27, s23, s11
	s_cselect_b32 s26, s22, s10
	v_add_u32_e32 v152, s46, v160
	s_cselect_b32 s13, s25, s44
	s_cselect_b32 s12, s24, s29
	s_add_i32 s47, 0, 0x14000
	ds_read_b128 v[130:133], v152
	ds_read_b128 v[134:137], v152 offset:1024
	ds_read_b128 v[148:151], v152 offset:2048
	ds_read_b128 v[156:159], v152 offset:3072
	v_add_u32_e32 v152, s47, v160
	ds_read_b128 v[180:183], v152
	ds_read_b128 v[184:187], v152 offset:1024
	ds_read_b128 v[188:191], v152 offset:2048
	ds_read_b128 v[192:195], v152 offset:3072
	v_lshl_add_u64 v[152:153], s[8:9], 0, v[144:145]
	s_add_i32 m0, s35, 0xc000
	ds_read_b128 v[196:199], v161
	ds_read_b128 v[200:203], v161 offset:1024
	ds_read_b128 v[204:207], v161 offset:2048
	ds_read_b128 v[208:211], v161 offset:3072
	ds_read_b128 v[212:215], v161 offset:4096
	ds_read_b128 v[216:219], v161 offset:5120
	ds_read_b128 v[220:223], v161 offset:6144
	ds_read_b128 v[224:227], v161 offset:7168
	global_load_lds_dwordx4 v[152:153], off
	v_lshl_add_u64 v[152:153], s[8:9], 0, v[146:147]
	s_add_i32 m0, s35, 0xe000
	s_nop 0
	global_load_lds_dwordx4 v[152:153], off
	s_waitcnt vmcnt(8)
	s_waitcnt lgkmcnt(0)
	s_barrier
	s_waitcnt lgkmcnt(0)
	v_mfma_f32_16x16x32_bf16 v[126:129], v[130:133], v[196:199], v[126:129]
	v_mfma_f32_16x16x32_bf16 v[126:129], v[134:137], v[200:203], v[126:129]
	v_mfma_f32_16x16x32_bf16 v[122:125], v[148:151], v[196:199], v[122:125]
	v_mfma_f32_16x16x32_bf16 v[122:125], v[156:159], v[200:203], v[122:125]
	v_mfma_f32_16x16x32_bf16 v[110:113], v[130:133], v[204:207], v[110:113]
	v_mfma_f32_16x16x32_bf16 v[110:113], v[134:137], v[208:211], v[110:113]
	v_mfma_f32_16x16x32_bf16 v[106:109], v[148:151], v[204:207], v[106:109]
	v_mfma_f32_16x16x32_bf16 v[106:109], v[156:159], v[208:211], v[106:109]
	v_mfma_f32_16x16x32_bf16 v[94:97], v[130:133], v[212:215], v[94:97]
	v_mfma_f32_16x16x32_bf16 v[94:97], v[134:137], v[216:219], v[94:97]
	v_mfma_f32_16x16x32_bf16 v[90:93], v[148:151], v[212:215], v[90:93]
	v_mfma_f32_16x16x32_bf16 v[90:93], v[156:159], v[216:219], v[90:93]
	v_mfma_f32_16x16x32_bf16 v[78:81], v[130:133], v[220:223], v[78:81]
	v_mfma_f32_16x16x32_bf16 v[78:81], v[134:137], v[224:227], v[78:81]
	v_mfma_f32_16x16x32_bf16 v[74:77], v[148:151], v[220:223], v[74:77]
	v_mfma_f32_16x16x32_bf16 v[74:77], v[156:159], v[224:227], v[74:77]
	v_mfma_f32_16x16x32_bf16 v[118:121], v[180:183], v[196:199], v[118:121]
	v_mfma_f32_16x16x32_bf16 v[118:121], v[184:187], v[200:203], v[118:121]
	v_mfma_f32_16x16x32_bf16 v[114:117], v[188:191], v[196:199], v[114:117]
	v_mfma_f32_16x16x32_bf16 v[114:117], v[192:195], v[200:203], v[114:117]
	v_mfma_f32_16x16x32_bf16 v[102:105], v[180:183], v[204:207], v[102:105]
	v_mfma_f32_16x16x32_bf16 v[102:105], v[184:187], v[208:211], v[102:105]
	v_mfma_f32_16x16x32_bf16 v[98:101], v[188:191], v[204:207], v[98:101]
	v_mfma_f32_16x16x32_bf16 v[98:101], v[192:195], v[208:211], v[98:101]
	v_mfma_f32_16x16x32_bf16 v[86:89], v[180:183], v[212:215], v[86:89]
	v_mfma_f32_16x16x32_bf16 v[86:89], v[184:187], v[216:219], v[86:89]
	v_mfma_f32_16x16x32_bf16 v[82:85], v[188:191], v[212:215], v[82:85]
	v_mfma_f32_16x16x32_bf16 v[82:85], v[192:195], v[216:219], v[82:85]
	v_mfma_f32_16x16x32_bf16 v[70:73], v[180:183], v[220:223], v[70:73]
	v_mfma_f32_16x16x32_bf16 v[70:73], v[184:187], v[224:227], v[70:73]
	v_mfma_f32_16x16x32_bf16 v[66:69], v[188:191], v[220:223], v[66:69]
	v_mfma_f32_16x16x32_bf16 v[66:69], v[192:195], v[224:227], v[66:69]
	s_barrier
	s_add_i32 s8, s46, s30
	v_lshl_add_u64 v[152:153], s[12:13], 0, v[0:1]
	s_mov_b32 m0, s8
	ds_read_b128 v[196:199], v161 offset:16384
	ds_read_b128 v[200:203], v161 offset:17408
	ds_read_b128 v[204:207], v161 offset:18432
	ds_read_b128 v[208:211], v161 offset:19456
	ds_read_b128 v[212:215], v161 offset:20480
	ds_read_b128 v[216:219], v161 offset:21504
	ds_read_b128 v[220:223], v161 offset:22528
	ds_read_b128 v[224:227], v161 offset:23552
	global_load_lds_dwordx4 v[152:153], off
	s_add_i32 m0, s8, 0x2000
	s_add_u32 s8, s12, 0xb0000
	v_lshl_add_u64 v[162:163], s[12:13], 0, v[142:143]
	s_addc_u32 s9, s13, 0
	s_add_i32 s46, s47, s30
	global_load_lds_dwordx4 v[162:163], off
	v_lshl_add_u64 v[170:171], s[8:9], 0, v[0:1]
	s_mov_b32 m0, s46
	v_lshl_add_u64 v[172:173], s[26:27], 0, v[140:141]
	global_load_lds_dwordx4 v[170:171], off
	v_lshl_add_u64 v[170:171], s[8:9], 0, v[142:143]
	s_add_i32 m0, s46, 0x2000
	s_nop 0
	global_load_lds_dwordx4 v[170:171], off
	v_lshl_add_u64 v[170:171], s[26:27], 0, v[138:139]
	s_mov_b32 m0, s35
	s_nop 0
	global_load_lds_dwordx4 v[170:171], off
	s_mov_b32 m0, s36
	s_nop 0
	global_load_lds_dwordx4 v[172:173], off
	s_waitcnt vmcnt(8)
	s_waitcnt lgkmcnt(0)
	s_barrier
; #define PG8_STAGE(bufoff, gbase, voff) do { _Pragma("unroll") for (int _i = 0; _i < 2; ++_i) \
;         __builtin_amdgcn_global_load_lds((const unsigned*)((const char*)(gbase) + (voff)[_i]), (LAS unsigned*)(lds + (bufoff) + ldsw + _i * 8192), 16, 0, 0); } while (0)
; #define PG8_LDA(dst, b, h) do { _Pragma("unroll") for (int m = 0; m < 4; ++m) _Pragma("unroll") for (int k = 0; k < 2; ++k) dst[m][k] = *(const LAS bf16x8*)(lds + PG8_SA(b, h) + aoff + m * 2048 + k * 1024); } while (0)
; #define PG8_LDB(dst, b, h) do { _Pragma("unroll") for (int n = 0; n < 2; ++n) _Pragma("unroll") for (int k = 0; k < 2; ++k) dst[n][k] = *(const LAS bf16x8*)(lds + PG8_SB(b, h) + boff + n * 2048 + k * 1024); } while (0)
; #define PG8_MMA(ai, bj, At, Bt) do { __builtin_amdgcn_s_setprio(1); _Pragma("unroll") for (int m = 0; m < 4; ++m) _Pragma("unroll") for (int n = 0; n < 2; ++n) _Pragma("unroll") for (int k = 0; k < 2; ++k) \
;         acc[ai][bj][m][n] = __builtin_amdgcn_mfma_f32_16x16x32_bf16(Bt[n][k], At[m][k], acc[ai][bj][m][n], 0, 0, 0); __builtin_amdgcn_s_setprio(0); } while (0)
; #define PG8_WAIT_V(n) asm volatile("s_waitcnt vmcnt(" #n ")" ::: "memory")
; #define PG8_WAIT_L(n) asm volatile("s_waitcnt lgkmcnt(" #n ")" ::: "memory")
; #define PG8_BAR __builtin_amdgcn_s_barrier()
; #define PG8_SCHED __builtin_amdgcn_sched_barrier(0)
; template <class Epi, bool ALIGN_EPI>
; __device__ __forceinline__ void gemm_phase(LAS unsigned char* lds, const Gemm g, const StaticOrder& S, const Epi& E) {
;     ...
;             PG8_WAIT_V(8); PG8_WAIT_L(0); PG8_BAR; PG8_MMA(1, 0, At, B0); PG8_MMA(1, 1, At, B1); PG8_BAR; PG8_SCHED;
;             PG8_LDB(B0, 1, 0); PG8_LDB(B1, 1, 1); PG8_SCHED; PG8_LDA(At, 1, 0); PG8_STAGE(PG8_SA(0, 1), a2 + hstepA, voffA);
;             PG8_WAIT_V(8); PG8_WAIT_L(0); PG8_BAR; PG8_MMA(0, 0, At, B0); PG8_MMA(0, 1, At, B1); PG8_BAR; PG8_SCHED;
	s_waitcnt lgkmcnt(0)
	v_mfma_f32_16x16x32_bf16 v[62:65], v[130:133], v[196:199], v[62:65]
	v_mfma_f32_16x16x32_bf16 v[62:65], v[134:137], v[200:203], v[62:65]
	v_mfma_f32_16x16x32_bf16 v[58:61], v[148:151], v[196:199], v[58:61]
	v_mfma_f32_16x16x32_bf16 v[58:61], v[156:159], v[200:203], v[58:61]
	v_mfma_f32_16x16x32_bf16 v[46:49], v[130:133], v[204:207], v[46:49]
	v_mfma_f32_16x16x32_bf16 v[46:49], v[134:137], v[208:211], v[46:49]
	v_mfma_f32_16x16x32_bf16 v[42:45], v[148:151], v[204:207], v[42:45]
	v_mfma_f32_16x16x32_bf16 v[42:45], v[156:159], v[208:211], v[42:45]
	v_mfma_f32_16x16x32_bf16 v[30:33], v[130:133], v[212:215], v[30:33]
	v_mfma_f32_16x16x32_bf16 v[30:33], v[134:137], v[216:219], v[30:33]
	v_mfma_f32_16x16x32_bf16 v[26:29], v[148:151], v[212:215], v[26:29]
	v_mfma_f32_16x16x32_bf16 v[26:29], v[156:159], v[216:219], v[26:29]
	v_mfma_f32_16x16x32_bf16 v[14:17], v[130:133], v[220:223], v[14:17]
	v_mfma_f32_16x16x32_bf16 v[14:17], v[134:137], v[224:227], v[14:17]
	v_mfma_f32_16x16x32_bf16 v[10:13], v[148:151], v[220:223], v[10:13]
	v_mfma_f32_16x16x32_bf16 v[10:13], v[156:159], v[224:227], v[10:13]
	v_mfma_f32_16x16x32_bf16 v[54:57], v[180:183], v[196:199], v[54:57]
	v_mfma_f32_16x16x32_bf16 v[54:57], v[184:187], v[200:203], v[54:57]
	v_mfma_f32_16x16x32_bf16 v[50:53], v[188:191], v[196:199], v[50:53]
	v_mfma_f32_16x16x32_bf16 v[50:53], v[192:195], v[200:203], v[50:53]
	v_mfma_f32_16x16x32_bf16 v[38:41], v[180:183], v[204:207], v[38:41]
	v_mfma_f32_16x16x32_bf16 v[38:41], v[184:187], v[208:211], v[38:41]
	v_mfma_f32_16x16x32_bf16 v[34:37], v[188:191], v[204:207], v[34:37]
	v_mfma_f32_16x16x32_bf16 v[34:37], v[192:195], v[208:211], v[34:37]
	v_mfma_f32_16x16x32_bf16 v[22:25], v[180:183], v[212:215], v[22:25]
	v_mfma_f32_16x16x32_bf16 v[22:25], v[184:187], v[216:219], v[22:25]
	v_mfma_f32_16x16x32_bf16 v[18:21], v[188:191], v[212:215], v[18:21]
	v_mfma_f32_16x16x32_bf16 v[18:21], v[192:195], v[216:219], v[18:21]
	v_mfma_f32_16x16x32_bf16 v[6:9], v[180:183], v[220:223], v[6:9]
	v_mfma_f32_16x16x32_bf16 v[6:9], v[184:187], v[224:227], v[6:9]
	v_mfma_f32_16x16x32_bf16 v[2:5], v[188:191], v[220:223], v[2:5]
	v_mfma_f32_16x16x32_bf16 v[2:5], v[192:195], v[224:227], v[2:5]
	s_barrier
	s_add_i32 s46, 0, 0x18000
	s_add_i32 s47, 0, 0x1c000
	v_add_u32_e32 v156, s46, v160
	v_add_u32_e32 v164, s47, v160
	ds_read_b128 v[130:133], v156
	ds_read_b128 v[134:137], v156 offset:1024
	ds_read_b128 v[148:151], v156 offset:2048
	ds_read_b128 v[156:159], v156 offset:3072
	ds_read_b128 v[180:183], v164
	ds_read_b128 v[184:187], v164 offset:1024
	ds_read_b128 v[188:191], v164 offset:2048
	ds_read_b128 v[192:195], v164 offset:3072
	s_add_u32 s8, s26, 0xb0000
	s_addc_u32 s9, s27, 0
	s_mov_b32 m0, s37
	v_lshl_add_u64 v[228:229], s[8:9], 0, v[138:139]
	ds_read_b128 v[196:199], v161 offset:32768
	ds_read_b128 v[200:203], v161 offset:33792
	ds_read_b128 v[204:207], v161 offset:34816
	ds_read_b128 v[208:211], v161 offset:35840
	ds_read_b128 v[212:215], v161 offset:36864
	ds_read_b128 v[216:219], v161 offset:37888
	ds_read_b128 v[220:223], v161 offset:38912
	ds_read_b128 v[224:227], v161 offset:39936
	global_load_lds_dwordx4 v[228:229], off
	v_lshl_add_u64 v[228:229], s[8:9], 0, v[140:141]
	s_mov_b32 m0, s38
	s_nop 0
	global_load_lds_dwordx4 v[228:229], off
	s_waitcnt vmcnt(8)
	s_waitcnt lgkmcnt(0)
	s_barrier
	s_waitcnt lgkmcnt(0)
	v_mfma_f32_16x16x32_bf16 v[126:129], v[130:133], v[196:199], v[126:129]
	v_mfma_f32_16x16x32_bf16 v[126:129], v[134:137], v[200:203], v[126:129]
	v_mfma_f32_16x16x32_bf16 v[122:125], v[148:151], v[196:199], v[122:125]
	v_mfma_f32_16x16x32_bf16 v[122:125], v[156:159], v[200:203], v[122:125]
	v_mfma_f32_16x16x32_bf16 v[110:113], v[130:133], v[204:207], v[110:113]
	v_mfma_f32_16x16x32_bf16 v[110:113], v[134:137], v[208:211], v[110:113]
	v_mfma_f32_16x16x32_bf16 v[106:109], v[148:151], v[204:207], v[106:109]
	v_mfma_f32_16x16x32_bf16 v[106:109], v[156:159], v[208:211], v[106:109]
	v_mfma_f32_16x16x32_bf16 v[94:97], v[130:133], v[212:215], v[94:97]
	v_mfma_f32_16x16x32_bf16 v[94:97], v[134:137], v[216:219], v[94:97]
	v_mfma_f32_16x16x32_bf16 v[90:93], v[148:151], v[212:215], v[90:93]
	v_mfma_f32_16x16x32_bf16 v[90:93], v[156:159], v[216:219], v[90:93]
	v_mfma_f32_16x16x32_bf16 v[78:81], v[130:133], v[220:223], v[78:81]
	v_mfma_f32_16x16x32_bf16 v[78:81], v[134:137], v[224:227], v[78:81]
	v_mfma_f32_16x16x32_bf16 v[74:77], v[148:151], v[220:223], v[74:77]
	v_mfma_f32_16x16x32_bf16 v[74:77], v[156:159], v[224:227], v[74:77]
	v_mfma_f32_16x16x32_bf16 v[118:121], v[180:183], v[196:199], v[118:121]
	v_mfma_f32_16x16x32_bf16 v[118:121], v[184:187], v[200:203], v[118:121]
	v_mfma_f32_16x16x32_bf16 v[114:117], v[188:191], v[196:199], v[114:117]
	v_mfma_f32_16x16x32_bf16 v[114:117], v[192:195], v[200:203], v[114:117]
	v_mfma_f32_16x16x32_bf16 v[102:105], v[180:183], v[204:207], v[102:105]
	v_mfma_f32_16x16x32_bf16 v[102:105], v[184:187], v[208:211], v[102:105]
	v_mfma_f32_16x16x32_bf16 v[98:101], v[188:191], v[204:207], v[98:101]
	v_mfma_f32_16x16x32_bf16 v[98:101], v[192:195], v[208:211], v[98:101]
	v_mfma_f32_16x16x32_bf16 v[86:89], v[180:183], v[212:215], v[86:89]
	v_mfma_f32_16x16x32_bf16 v[86:89], v[184:187], v[216:219], v[86:89]
	v_mfma_f32_16x16x32_bf16 v[82:85], v[188:191], v[212:215], v[82:85]
	v_mfma_f32_16x16x32_bf16 v[82:85], v[192:195], v[216:219], v[82:85]
	v_mfma_f32_16x16x32_bf16 v[70:73], v[180:183], v[220:223], v[70:73]
	v_mfma_f32_16x16x32_bf16 v[70:73], v[184:187], v[224:227], v[70:73]
	v_mfma_f32_16x16x32_bf16 v[66:69], v[188:191], v[220:223], v[66:69]
	v_mfma_f32_16x16x32_bf16 v[66:69], v[192:195], v[224:227], v[66:69]
	s_barrier
; #define PG8_STAGE(bufoff, gbase, voff) do { _Pragma("unroll") for (int _i = 0; _i < 2; ++_i) \
;         __builtin_amdgcn_global_load_lds((const unsigned*)((const char*)(gbase) + (voff)[_i]), (LAS unsigned*)(lds + (bufoff) + ldsw + _i * 8192), 16, 0, 0); } while (0)
; #define PG8_LDA(dst, b, h) do { _Pragma("unroll") for (int m = 0; m < 4; ++m) _Pragma("unroll") for (int k = 0; k < 2; ++k) dst[m][k] = *(const LAS bf16x8*)(lds + PG8_SA(b, h) + aoff + m * 2048 + k * 1024); } while (0)
; #define PG8_MMA(ai, bj, At, Bt) do { __builtin_amdgcn_s_setprio(1); _Pragma("unroll") for (int m = 0; m < 4; ++m) _Pragma("unroll") for (int n = 0; n < 2; ++n) _Pragma("unroll") for (int k = 0; k < 2; ++k) \
;         acc[ai][bj][m][n] = __builtin_amdgcn_mfma_f32_16x16x32_bf16(Bt[n][k], At[m][k], acc[ai][bj][m][n], 0, 0, 0); __builtin_amdgcn_s_setprio(0); } while (0)
; #define PG8_WAIT_V(n) asm volatile("s_waitcnt vmcnt(" #n ")" ::: "memory")
; #define PG8_WAIT_L(n) asm volatile("s_waitcnt lgkmcnt(" #n ")" ::: "memory")
; #define PG8_BAR __builtin_amdgcn_s_barrier()
; #define PG8_SCHED __builtin_amdgcn_sched_barrier(0)
; template <class Epi, bool ALIGN_EPI>
; __device__ __forceinline__ void gemm_phase(LAS unsigned char* lds, const Gemm g, const StaticOrder& S, const Epi& E) {
;     ...
;             PG8_LDA(At, 1, 1); PG8_STAGE(PG8_SB(1, 0), b3, voffB); PG8_STAGE(PG8_SB(1, 1), b3 + hstepB, voffB); PG8_STAGE(PG8_SA(1, 0), a3, voffA);
;             PG8_WAIT_V(8); PG8_WAIT_L(0); PG8_BAR; PG8_MMA(1, 0, At, B0); PG8_MMA(1, 1, At, B1); PG8_BAR; PG8_SCHED;
	s_add_i32 s8, s46, s30
	v_lshl_add_u64 v[152:153], v[152:153], 0, s[94:95]
	s_mov_b32 m0, s8
	ds_read_b128 v[196:199], v161 offset:49152
	ds_read_b128 v[200:203], v161 offset:50176
	ds_read_b128 v[204:207], v161 offset:51200
	ds_read_b128 v[208:211], v161 offset:52224
	ds_read_b128 v[212:215], v161 offset:53248
	ds_read_b128 v[216:219], v161 offset:54272
	ds_read_b128 v[220:223], v161 offset:55296
	ds_read_b128 v[224:227], v161 offset:56320
	global_load_lds_dwordx4 v[152:153], off
	s_add_i32 m0, s8, 0x2000
	s_add_u32 s8, s12, 0xb0080
	v_lshl_add_u64 v[152:153], v[162:163], 0, s[94:95]
	s_addc_u32 s9, s13, 0
	s_add_i32 s12, s47, s30
	global_load_lds_dwordx4 v[152:153], off
	v_lshl_add_u64 v[152:153], s[8:9], 0, v[0:1]
	s_mov_b32 m0, s12
	s_nop 0
	global_load_lds_dwordx4 v[152:153], off
	v_lshl_add_u64 v[152:153], s[8:9], 0, v[142:143]
	s_add_i32 m0, s12, 0x2000
	s_nop 0
	global_load_lds_dwordx4 v[152:153], off
	v_lshl_add_u64 v[152:153], v[170:171], 0, s[94:95]
	s_mov_b32 m0, s39
	s_nop 0
	global_load_lds_dwordx4 v[152:153], off
	v_lshl_add_u64 v[152:153], v[172:173], 0, s[94:95]
	s_mov_b32 m0, s40
	s_nop 0
	global_load_lds_dwordx4 v[152:153], off
	s_waitcnt vmcnt(8)
	s_waitcnt lgkmcnt(0)
	s_barrier
	s_waitcnt lgkmcnt(0)
	v_mfma_f32_16x16x32_bf16 v[62:65], v[130:133], v[196:199], v[62:65]
	v_mfma_f32_16x16x32_bf16 v[62:65], v[134:137], v[200:203], v[62:65]
	v_mfma_f32_16x16x32_bf16 v[58:61], v[148:151], v[196:199], v[58:61]
	v_mfma_f32_16x16x32_bf16 v[58:61], v[156:159], v[200:203], v[58:61]
	v_mfma_f32_16x16x32_bf16 v[46:49], v[130:133], v[204:207], v[46:49]
	v_mfma_f32_16x16x32_bf16 v[46:49], v[134:137], v[208:211], v[46:49]
	v_mfma_f32_16x16x32_bf16 v[42:45], v[148:151], v[204:207], v[42:45]
	v_mfma_f32_16x16x32_bf16 v[42:45], v[156:159], v[208:211], v[42:45]
	v_mfma_f32_16x16x32_bf16 v[30:33], v[130:133], v[212:215], v[30:33]
	v_mfma_f32_16x16x32_bf16 v[30:33], v[134:137], v[216:219], v[30:33]
	v_mfma_f32_16x16x32_bf16 v[26:29], v[148:151], v[212:215], v[26:29]
	v_mfma_f32_16x16x32_bf16 v[26:29], v[156:159], v[216:219], v[26:29]
	v_mfma_f32_16x16x32_bf16 v[14:17], v[130:133], v[220:223], v[14:17]
	v_mfma_f32_16x16x32_bf16 v[14:17], v[134:137], v[224:227], v[14:17]
	v_mfma_f32_16x16x32_bf16 v[10:13], v[148:151], v[220:223], v[10:13]
	v_mfma_f32_16x16x32_bf16 v[10:13], v[156:159], v[224:227], v[10:13]
	v_mfma_f32_16x16x32_bf16 v[54:57], v[180:183], v[196:199], v[54:57]
	v_mfma_f32_16x16x32_bf16 v[54:57], v[184:187], v[200:203], v[54:57]
	v_mfma_f32_16x16x32_bf16 v[50:53], v[188:191], v[196:199], v[50:53]
	v_mfma_f32_16x16x32_bf16 v[50:53], v[192:195], v[200:203], v[50:53]
	v_mfma_f32_16x16x32_bf16 v[38:41], v[180:183], v[204:207], v[38:41]
	v_mfma_f32_16x16x32_bf16 v[38:41], v[184:187], v[208:211], v[38:41]
	v_mfma_f32_16x16x32_bf16 v[34:37], v[188:191], v[204:207], v[34:37]
	v_mfma_f32_16x16x32_bf16 v[34:37], v[192:195], v[208:211], v[34:37]
	v_mfma_f32_16x16x32_bf16 v[22:25], v[180:183], v[212:215], v[22:25]
	v_mfma_f32_16x16x32_bf16 v[22:25], v[184:187], v[216:219], v[22:25]
	v_mfma_f32_16x16x32_bf16 v[18:21], v[188:191], v[212:215], v[18:21]
	v_mfma_f32_16x16x32_bf16 v[18:21], v[192:195], v[216:219], v[18:21]
	v_mfma_f32_16x16x32_bf16 v[6:9], v[180:183], v[220:223], v[6:9]
	v_mfma_f32_16x16x32_bf16 v[6:9], v[184:187], v[224:227], v[6:9]
	v_mfma_f32_16x16x32_bf16 v[2:5], v[188:191], v[220:223], v[2:5]
	v_mfma_f32_16x16x32_bf16 v[2:5], v[192:195], v[224:227], v[2:5]
	s_cmp_lg_u32 s45, 40
	s_cbranch_scc1 .Ltail_bar_2
	s_cmp_eq_u64 s[16:17], 0
	s_cbranch_scc1 .Ltail_skip_2

; #define PG8_STAGE(bufoff, gbase, voff) do { _Pragma("unroll") for (int _i = 0; _i < 2; ++_i) \
;         __builtin_amdgcn_global_load_lds((const unsigned*)((const char*)(gbase) + (voff)[_i]), (LAS unsigned*)(lds + (bufoff) + ldsw + _i * 8192), 16, 0, 0); } while (0)
; #define PG8_LDA(dst, b, h) do { _Pragma("unroll") for (int m = 0; m < 4; ++m) _Pragma("unroll") for (int k = 0; k < 2; ++k) dst[m][k] = *(const LAS bf16x8*)(lds + PG8_SA(b, h) + aoff + m * 2048 + k * 1024); } while (0)
; #define PG8_LDB(dst, b, h) do { _Pragma("unroll") for (int n = 0; n < 2; ++n) _Pragma("unroll") for (int k = 0; k < 2; ++k) dst[n][k] = *(const LAS bf16x8*)(lds + PG8_SB(b, h) + boff + n * 2048 + k * 1024); } while (0)
; #define PG8_MMA(ai, bj, At, Bt) do { __builtin_amdgcn_s_setprio(1); _Pragma("unroll") for (int m = 0; m < 4; ++m) _Pragma("unroll") for (int n = 0; n < 2; ++n) _Pragma("unroll") for (int k = 0; k < 2; ++k) \
;         acc[ai][bj][m][n] = __builtin_amdgcn_mfma_f32_16x16x32_bf16(Bt[n][k], At[m][k], acc[ai][bj][m][n], 0, 0, 0); __builtin_amdgcn_s_setprio(0); } while (0)
; #define PG8_WAIT_V(n) asm volatile("s_waitcnt vmcnt(" #n ")" ::: "memory")
; #define PG8_WAIT_L(n) asm volatile("s_waitcnt lgkmcnt(" #n ")" ::: "memory")
; #define PG8_BAR __builtin_amdgcn_s_barrier()
; #define PG8_SCHED __builtin_amdgcn_sched_barrier(0)
; template <class Epi, bool ALIGN_EPI>
; __device__ __forceinline__ void gemm_phase(LAS unsigned char* lds, const Gemm g, const StaticOrder& S, const Epi& E) {
;     ...
;             const bool last = (t == nt - 2);
;             const char* a1 = cA + (size_t)(t + 1) * kstep;
;             const char* a2 = last ? nA : cA + (size_t)(t + 2) * kstep; const char* b2 = last ? nB : cB + (size_t)(t + 2) * kstep;
;             const char* a3 = a2 + kstep; const char* b3 = b2 + kstep;
;             PG8_LDB(B0, 0, 0); PG8_LDB(B1, 0, 1); PG8_SCHED; PG8_LDA(At, 0, 0); PG8_STAGE(PG8_SA(1, 1), a1 + hstepA, voffA);
;             PG8_WAIT_V(8); PG8_WAIT_L(0); PG8_BAR; PG8_MMA(0, 0, At, B0); PG8_MMA(0, 1, At, B1); PG8_BAR; PG8_SCHED;
;             PG8_LDA(At, 0, 1); PG8_STAGE(PG8_SB(0, 0), b2, voffB); PG8_STAGE(PG8_SB(0, 1), b2 + hstepB, voffB); PG8_STAGE(PG8_SA(0, 0), a2, voffA);
;             PG8_WAIT_V(8); PG8_WAIT_L(0); PG8_BAR; PG8_MMA(1, 0, At, B0); PG8_MMA(1, 1, At, B1); PG8_BAR; PG8_SCHED;
.LBB0_849:
	s_add_u32 s18, s6, 0xfffc0080
	s_addc_u32 s19, s7, -1
	s_add_i32 s39, 0, 0x10000
	s_cmp_eq_u32 s38, 12
	s_cselect_b32 s21, s1, s19
	s_cselect_b32 s20, s34, s18
	v_add_u32_e32 v152, s39, v144
	s_cselect_b32 s19, s11, s37
	s_cselect_b32 s18, s35, s36
	s_add_i32 s42, 0, 0x14000
	ds_read_b128 v[140:143], v152
	ds_read_b128 v[148:151], v152 offset:1024
	ds_read_b128 v[156:159], v152 offset:2048
	ds_read_b128 v[180:183], v152 offset:3072
	v_add_u32_e32 v152, s42, v144
	ds_read_b128 v[184:187], v152
	ds_read_b128 v[188:191], v152 offset:1024
	ds_read_b128 v[192:195], v152 offset:2048
	ds_read_b128 v[196:199], v152 offset:3072
	v_lshl_add_u64 v[152:153], s[6:7], 0, v[136:137]
	s_add_i32 m0, s23, 0xc000
	ds_read_b128 v[200:203], v146
	ds_read_b128 v[204:207], v146 offset:1024
	ds_read_b128 v[208:211], v146 offset:2048
	ds_read_b128 v[212:215], v146 offset:3072
	ds_read_b128 v[216:219], v146 offset:4096
	ds_read_b128 v[220:223], v146 offset:5120
	ds_read_b128 v[224:227], v146 offset:6144
	ds_read_b128 v[228:231], v146 offset:7168
	global_load_lds_dwordx4 v[152:153], off
	v_lshl_add_u64 v[152:153], s[6:7], 0, v[138:139]
	s_add_i32 m0, s23, 0xe000
	s_nop 0
	global_load_lds_dwordx4 v[152:153], off
	s_waitcnt vmcnt(8)
	s_waitcnt lgkmcnt(0)
	s_barrier
	s_waitcnt lgkmcnt(0)
	v_mfma_f32_16x16x32_bf16 v[126:129], v[140:143], v[200:203], v[126:129]
	v_mfma_f32_16x16x32_bf16 v[126:129], v[148:151], v[204:207], v[126:129]
	v_mfma_f32_16x16x32_bf16 v[118:121], v[156:159], v[200:203], v[118:121]
	v_mfma_f32_16x16x32_bf16 v[118:121], v[180:183], v[204:207], v[118:121]
	v_mfma_f32_16x16x32_bf16 v[110:113], v[140:143], v[208:211], v[110:113]
	v_mfma_f32_16x16x32_bf16 v[110:113], v[148:151], v[212:215], v[110:113]
	v_mfma_f32_16x16x32_bf16 v[102:105], v[156:159], v[208:211], v[102:105]
	v_mfma_f32_16x16x32_bf16 v[102:105], v[180:183], v[212:215], v[102:105]
	v_mfma_f32_16x16x32_bf16 v[94:97], v[140:143], v[216:219], v[94:97]
	v_mfma_f32_16x16x32_bf16 v[94:97], v[148:151], v[220:223], v[94:97]
	v_mfma_f32_16x16x32_bf16 v[86:89], v[156:159], v[216:219], v[86:89]
	v_mfma_f32_16x16x32_bf16 v[86:89], v[180:183], v[220:223], v[86:89]
	v_mfma_f32_16x16x32_bf16 v[78:81], v[140:143], v[224:227], v[78:81]
	v_mfma_f32_16x16x32_bf16 v[78:81], v[148:151], v[228:231], v[78:81]
	v_mfma_f32_16x16x32_bf16 v[70:73], v[156:159], v[224:227], v[70:73]
	v_mfma_f32_16x16x32_bf16 v[70:73], v[180:183], v[228:231], v[70:73]
	v_mfma_f32_16x16x32_bf16 v[122:125], v[184:187], v[200:203], v[122:125]
	v_mfma_f32_16x16x32_bf16 v[122:125], v[188:191], v[204:207], v[122:125]
	v_mfma_f32_16x16x32_bf16 v[114:117], v[192:195], v[200:203], v[114:117]
	v_mfma_f32_16x16x32_bf16 v[114:117], v[196:199], v[204:207], v[114:117]
	v_mfma_f32_16x16x32_bf16 v[106:109], v[184:187], v[208:211], v[106:109]
	v_mfma_f32_16x16x32_bf16 v[106:109], v[188:191], v[212:215], v[106:109]
	v_mfma_f32_16x16x32_bf16 v[98:101], v[192:195], v[208:211], v[98:101]
	v_mfma_f32_16x16x32_bf16 v[98:101], v[196:199], v[212:215], v[98:101]
	v_mfma_f32_16x16x32_bf16 v[90:93], v[184:187], v[216:219], v[90:93]
	v_mfma_f32_16x16x32_bf16 v[90:93], v[188:191], v[220:223], v[90:93]
	v_mfma_f32_16x16x32_bf16 v[82:85], v[192:195], v[216:219], v[82:85]
	v_mfma_f32_16x16x32_bf16 v[82:85], v[196:199], v[220:223], v[82:85]
	v_mfma_f32_16x16x32_bf16 v[74:77], v[184:187], v[224:227], v[74:77]
	v_mfma_f32_16x16x32_bf16 v[74:77], v[188:191], v[228:231], v[74:77]
	v_mfma_f32_16x16x32_bf16 v[66:69], v[192:195], v[224:227], v[66:69]
	v_mfma_f32_16x16x32_bf16 v[66:69], v[196:199], v[228:231], v[66:69]
	s_barrier
	s_add_i32 s39, s39, s22
	v_lshl_add_u64 v[152:153], s[18:19], 0, v[0:1]
	s_mov_b32 m0, s39
	ds_read_b128 v[200:203], v146 offset:16384
	ds_read_b128 v[204:207], v146 offset:17408
	ds_read_b128 v[208:211], v146 offset:18432
	ds_read_b128 v[212:215], v146 offset:19456
	ds_read_b128 v[216:219], v146 offset:20480
	ds_read_b128 v[220:223], v146 offset:21504
	ds_read_b128 v[224:227], v146 offset:22528
	ds_read_b128 v[228:231], v146 offset:23552
	global_load_lds_dwordx4 v[152:153], off
	s_add_i32 m0, s39, 0x2000
	s_add_u32 s40, s18, 0x40000
	v_lshl_add_u64 v[160:161], s[18:19], 0, v[130:131]
	s_addc_u32 s41, s19, 0
	s_add_i32 s39, s42, s22
	global_load_lds_dwordx4 v[160:161], off
	v_lshl_add_u64 v[162:163], s[40:41], 0, v[0:1]
	s_mov_b32 m0, s39
	v_lshl_add_u64 v[170:171], s[20:21], 0, v[132:133]
	global_load_lds_dwordx4 v[162:163], off
	v_lshl_add_u64 v[162:163], s[40:41], 0, v[130:131]
	s_add_i32 m0, s39, 0x2000
	s_nop 0
	global_load_lds_dwordx4 v[162:163], off
	v_lshl_add_u64 v[162:163], s[20:21], 0, v[134:135]
	s_mov_b32 m0, s23
	s_nop 0
	global_load_lds_dwordx4 v[162:163], off
	s_mov_b32 m0, s24
	s_nop 0
	global_load_lds_dwordx4 v[170:171], off
	s_waitcnt vmcnt(8)
	s_waitcnt lgkmcnt(0)
	s_barrier
; #define PG8_STAGE(bufoff, gbase, voff) do { _Pragma("unroll") for (int _i = 0; _i < 2; ++_i) \
;         __builtin_amdgcn_global_load_lds((const unsigned*)((const char*)(gbase) + (voff)[_i]), (LAS unsigned*)(lds + (bufoff) + ldsw + _i * 8192), 16, 0, 0); } while (0)
; #define PG8_LDA(dst, b, h) do { _Pragma("unroll") for (int m = 0; m < 4; ++m) _Pragma("unroll") for (int k = 0; k < 2; ++k) dst[m][k] = *(const LAS bf16x8*)(lds + PG8_SA(b, h) + aoff + m * 2048 + k * 1024); } while (0)
; #define PG8_LDB(dst, b, h) do { _Pragma("unroll") for (int n = 0; n < 2; ++n) _Pragma("unroll") for (int k = 0; k < 2; ++k) dst[n][k] = *(const LAS bf16x8*)(lds + PG8_SB(b, h) + boff + n * 2048 + k * 1024); } while (0)
; #define PG8_MMA(ai, bj, At, Bt) do { __builtin_amdgcn_s_setprio(1); _Pragma("unroll") for (int m = 0; m < 4; ++m) _Pragma("unroll") for (int n = 0; n < 2; ++n) _Pragma("unroll") for (int k = 0; k < 2; ++k) \
;         acc[ai][bj][m][n] = __builtin_amdgcn_mfma_f32_16x16x32_bf16(Bt[n][k], At[m][k], acc[ai][bj][m][n], 0, 0, 0); __builtin_amdgcn_s_setprio(0); } while (0)
; #define PG8_WAIT_V(n) asm volatile("s_waitcnt vmcnt(" #n ")" ::: "memory")
; #define PG8_WAIT_L(n) asm volatile("s_waitcnt lgkmcnt(" #n ")" ::: "memory")
; #define PG8_BAR __builtin_amdgcn_s_barrier()
; #define PG8_SCHED __builtin_amdgcn_sched_barrier(0)
; template <class Epi, bool ALIGN_EPI>
; __device__ __forceinline__ void gemm_phase(LAS unsigned char* lds, const Gemm g, const StaticOrder& S, const Epi& E) {
;     ...
;             PG8_WAIT_V(8); PG8_WAIT_L(0); PG8_BAR; PG8_MMA(1, 0, At, B0); PG8_MMA(1, 1, At, B1); PG8_BAR; PG8_SCHED;
;             PG8_LDB(B0, 1, 0); PG8_LDB(B1, 1, 1); PG8_SCHED; PG8_LDA(At, 1, 0); PG8_STAGE(PG8_SA(0, 1), a2 + hstepA, voffA);
;             PG8_WAIT_V(8); PG8_WAIT_L(0); PG8_BAR; PG8_MMA(0, 0, At, B0); PG8_MMA(0, 1, At, B1); PG8_BAR; PG8_SCHED;
	s_waitcnt lgkmcnt(0)
	v_mfma_f32_16x16x32_bf16 v[62:65], v[140:143], v[200:203], v[62:65]
	v_mfma_f32_16x16x32_bf16 v[62:65], v[148:151], v[204:207], v[62:65]
	v_mfma_f32_16x16x32_bf16 v[54:57], v[156:159], v[200:203], v[54:57]
	v_mfma_f32_16x16x32_bf16 v[54:57], v[180:183], v[204:207], v[54:57]
	v_mfma_f32_16x16x32_bf16 v[46:49], v[140:143], v[208:211], v[46:49]
	v_mfma_f32_16x16x32_bf16 v[46:49], v[148:151], v[212:215], v[46:49]
	v_mfma_f32_16x16x32_bf16 v[38:41], v[156:159], v[208:211], v[38:41]
	v_mfma_f32_16x16x32_bf16 v[38:41], v[180:183], v[212:215], v[38:41]
	v_mfma_f32_16x16x32_bf16 v[30:33], v[140:143], v[216:219], v[30:33]
	v_mfma_f32_16x16x32_bf16 v[30:33], v[148:151], v[220:223], v[30:33]
	v_mfma_f32_16x16x32_bf16 v[22:25], v[156:159], v[216:219], v[22:25]
	v_mfma_f32_16x16x32_bf16 v[22:25], v[180:183], v[220:223], v[22:25]
	v_mfma_f32_16x16x32_bf16 v[14:17], v[140:143], v[224:227], v[14:17]
	v_mfma_f32_16x16x32_bf16 v[14:17], v[148:151], v[228:231], v[14:17]
	v_mfma_f32_16x16x32_bf16 v[6:9], v[156:159], v[224:227], v[6:9]
	v_mfma_f32_16x16x32_bf16 v[6:9], v[180:183], v[228:231], v[6:9]
	v_mfma_f32_16x16x32_bf16 v[58:61], v[184:187], v[200:203], v[58:61]
	v_mfma_f32_16x16x32_bf16 v[58:61], v[188:191], v[204:207], v[58:61]
	v_mfma_f32_16x16x32_bf16 v[50:53], v[192:195], v[200:203], v[50:53]
	v_mfma_f32_16x16x32_bf16 v[50:53], v[196:199], v[204:207], v[50:53]
	v_mfma_f32_16x16x32_bf16 v[42:45], v[184:187], v[208:211], v[42:45]
	v_mfma_f32_16x16x32_bf16 v[42:45], v[188:191], v[212:215], v[42:45]
	v_mfma_f32_16x16x32_bf16 v[34:37], v[192:195], v[208:211], v[34:37]
	v_mfma_f32_16x16x32_bf16 v[34:37], v[196:199], v[212:215], v[34:37]
	v_mfma_f32_16x16x32_bf16 v[26:29], v[184:187], v[216:219], v[26:29]
	v_mfma_f32_16x16x32_bf16 v[26:29], v[188:191], v[220:223], v[26:29]
	v_mfma_f32_16x16x32_bf16 v[18:21], v[192:195], v[216:219], v[18:21]
	v_mfma_f32_16x16x32_bf16 v[18:21], v[196:199], v[220:223], v[18:21]
	v_mfma_f32_16x16x32_bf16 v[10:13], v[184:187], v[224:227], v[10:13]
	v_mfma_f32_16x16x32_bf16 v[10:13], v[188:191], v[228:231], v[10:13]
	v_mfma_f32_16x16x32_bf16 v[2:5], v[192:195], v[224:227], v[2:5]
	v_mfma_f32_16x16x32_bf16 v[2:5], v[196:199], v[228:231], v[2:5]
	s_barrier
	s_add_i32 s39, 0, 0x18000
	v_add_u32_e32 v164, s39, v144
	s_add_i32 s40, 0, 0x1c000
	ds_read_b128 v[140:143], v164
	ds_read_b128 v[148:151], v164 offset:1024
	ds_read_b128 v[156:159], v164 offset:2048
	ds_read_b128 v[180:183], v164 offset:3072
	v_add_u32_e32 v164, s40, v144
	ds_read_b128 v[184:187], v164
	ds_read_b128 v[188:191], v164 offset:1024
	ds_read_b128 v[192:195], v164 offset:2048
	ds_read_b128 v[196:199], v164 offset:3072
	s_add_u32 s20, s20, 0x40000
	s_addc_u32 s21, s21, 0
	s_mov_b32 m0, s25
	v_lshl_add_u64 v[172:173], s[20:21], 0, v[134:135]
	ds_read_b128 v[200:203], v146 offset:32768
	ds_read_b128 v[204:207], v146 offset:33792
	ds_read_b128 v[208:211], v146 offset:34816
	ds_read_b128 v[212:215], v146 offset:35840
	ds_read_b128 v[216:219], v146 offset:36864
	ds_read_b128 v[220:223], v146 offset:37888
	ds_read_b128 v[224:227], v146 offset:38912
	ds_read_b128 v[228:231], v146 offset:39936
	global_load_lds_dwordx4 v[172:173], off
	v_lshl_add_u64 v[172:173], s[20:21], 0, v[132:133]
	s_mov_b32 m0, s26
	s_nop 0
	global_load_lds_dwordx4 v[172:173], off
	s_waitcnt vmcnt(8)
	s_waitcnt lgkmcnt(0)
	s_barrier
	s_waitcnt lgkmcnt(0)
	v_mfma_f32_16x16x32_bf16 v[126:129], v[140:143], v[200:203], v[126:129]
	v_mfma_f32_16x16x32_bf16 v[126:129], v[148:151], v[204:207], v[126:129]
	v_mfma_f32_16x16x32_bf16 v[118:121], v[156:159], v[200:203], v[118:121]
	v_mfma_f32_16x16x32_bf16 v[118:121], v[180:183], v[204:207], v[118:121]
	v_mfma_f32_16x16x32_bf16 v[110:113], v[140:143], v[208:211], v[110:113]
	v_mfma_f32_16x16x32_bf16 v[110:113], v[148:151], v[212:215], v[110:113]
	v_mfma_f32_16x16x32_bf16 v[102:105], v[156:159], v[208:211], v[102:105]
	v_mfma_f32_16x16x32_bf16 v[102:105], v[180:183], v[212:215], v[102:105]
	v_mfma_f32_16x16x32_bf16 v[94:97], v[140:143], v[216:219], v[94:97]
	v_mfma_f32_16x16x32_bf16 v[94:97], v[148:151], v[220:223], v[94:97]
	v_mfma_f32_16x16x32_bf16 v[86:89], v[156:159], v[216:219], v[86:89]
	v_mfma_f32_16x16x32_bf16 v[86:89], v[180:183], v[220:223], v[86:89]
	v_mfma_f32_16x16x32_bf16 v[78:81], v[140:143], v[224:227], v[78:81]
	v_mfma_f32_16x16x32_bf16 v[78:81], v[148:151], v[228:231], v[78:81]
	v_mfma_f32_16x16x32_bf16 v[70:73], v[156:159], v[224:227], v[70:73]
	v_mfma_f32_16x16x32_bf16 v[70:73], v[180:183], v[228:231], v[70:73]
	v_mfma_f32_16x16x32_bf16 v[122:125], v[184:187], v[200:203], v[122:125]
	v_mfma_f32_16x16x32_bf16 v[122:125], v[188:191], v[204:207], v[122:125]
	v_mfma_f32_16x16x32_bf16 v[114:117], v[192:195], v[200:203], v[114:117]
	v_mfma_f32_16x16x32_bf16 v[114:117], v[196:199], v[204:207], v[114:117]
	v_mfma_f32_16x16x32_bf16 v[106:109], v[184:187], v[208:211], v[106:109]
	v_mfma_f32_16x16x32_bf16 v[106:109], v[188:191], v[212:215], v[106:109]
	v_mfma_f32_16x16x32_bf16 v[98:101], v[192:195], v[208:211], v[98:101]
	v_mfma_f32_16x16x32_bf16 v[98:101], v[196:199], v[212:215], v[98:101]
	v_mfma_f32_16x16x32_bf16 v[90:93], v[184:187], v[216:219], v[90:93]
	v_mfma_f32_16x16x32_bf16 v[90:93], v[188:191], v[220:223], v[90:93]
	v_mfma_f32_16x16x32_bf16 v[82:85], v[192:195], v[216:219], v[82:85]
	v_mfma_f32_16x16x32_bf16 v[82:85], v[196:199], v[220:223], v[82:85]
	v_mfma_f32_16x16x32_bf16 v[74:77], v[184:187], v[224:227], v[74:77]
	v_mfma_f32_16x16x32_bf16 v[74:77], v[188:191], v[228:231], v[74:77]
	v_mfma_f32_16x16x32_bf16 v[66:69], v[192:195], v[224:227], v[66:69]
	v_mfma_f32_16x16x32_bf16 v[66:69], v[196:199], v[228:231], v[66:69]
	s_barrier
; #define PG8_STAGE(bufoff, gbase, voff) do { _Pragma("unroll") for (int _i = 0; _i < 2; ++_i) \
;         __builtin_amdgcn_global_load_lds((const unsigned*)((const char*)(gbase) + (voff)[_i]), (LAS unsigned*)(lds + (bufoff) + ldsw + _i * 8192), 16, 0, 0); } while (0)
; #define PG8_LDA(dst, b, h) do { _Pragma("unroll") for (int m = 0; m < 4; ++m) _Pragma("unroll") for (int k = 0; k < 2; ++k) dst[m][k] = *(const LAS bf16x8*)(lds + PG8_SA(b, h) + aoff + m * 2048 + k * 1024); } while (0)
; #define PG8_MMA(ai, bj, At, Bt) do { __builtin_amdgcn_s_setprio(1); _Pragma("unroll") for (int m = 0; m < 4; ++m) _Pragma("unroll") for (int n = 0; n < 2; ++n) _Pragma("unroll") for (int k = 0; k < 2; ++k) \
;         acc[ai][bj][m][n] = __builtin_amdgcn_mfma_f32_16x16x32_bf16(Bt[n][k], At[m][k], acc[ai][bj][m][n], 0, 0, 0); __builtin_amdgcn_s_setprio(0); } while (0)
; #define PG8_WAIT_V(n) asm volatile("s_waitcnt vmcnt(" #n ")" ::: "memory")
; #define PG8_WAIT_L(n) asm volatile("s_waitcnt lgkmcnt(" #n ")" ::: "memory")
; #define PG8_BAR __builtin_amdgcn_s_barrier()
; #define PG8_SCHED __builtin_amdgcn_sched_barrier(0)
; template <class Epi, bool ALIGN_EPI>
; __device__ __forceinline__ void gemm_phase(LAS unsigned char* lds, const Gemm g, const StaticOrder& S, const Epi& E) {
;     ...
;             PG8_LDA(At, 1, 1); PG8_STAGE(PG8_SB(1, 0), b3, voffB); PG8_STAGE(PG8_SB(1, 1), b3 + hstepB, voffB); PG8_STAGE(PG8_SA(1, 0), a3, voffA);
;             PG8_WAIT_V(8); PG8_WAIT_L(0); PG8_BAR; PG8_MMA(1, 0, At, B0); PG8_MMA(1, 1, At, B1); PG8_BAR; PG8_SCHED;
	s_add_i32 s20, s39, s22
	v_lshl_add_u64 v[152:153], v[152:153], 0, s[94:95]
	s_mov_b32 m0, s20
	ds_read_b128 v[200:203], v146 offset:49152
	ds_read_b128 v[204:207], v146 offset:50176
	ds_read_b128 v[208:211], v146 offset:51200
	ds_read_b128 v[212:215], v146 offset:52224
	ds_read_b128 v[216:219], v146 offset:53248
	ds_read_b128 v[220:223], v146 offset:54272
	ds_read_b128 v[224:227], v146 offset:55296
	ds_read_b128 v[228:231], v146 offset:56320
	global_load_lds_dwordx4 v[152:153], off
	s_add_i32 m0, s20, 0x2000
	s_add_u32 s18, s18, 0x40080
	v_lshl_add_u64 v[152:153], v[160:161], 0, s[94:95]
	s_addc_u32 s19, s19, 0
	s_add_i32 s20, s40, s22
	global_load_lds_dwordx4 v[152:153], off
	v_lshl_add_u64 v[152:153], s[18:19], 0, v[0:1]
	s_mov_b32 m0, s20
	s_nop 0
	global_load_lds_dwordx4 v[152:153], off
	v_lshl_add_u64 v[152:153], s[18:19], 0, v[130:131]
	s_add_i32 m0, s20, 0x2000
	s_nop 0
	global_load_lds_dwordx4 v[152:153], off
	v_lshl_add_u64 v[152:153], v[162:163], 0, s[94:95]
	s_mov_b32 m0, s27
	s_nop 0
	global_load_lds_dwordx4 v[152:153], off
	v_lshl_add_u64 v[152:153], v[170:171], 0, s[94:95]
	s_mov_b32 m0, s28
	s_nop 0
	global_load_lds_dwordx4 v[152:153], off
	s_waitcnt vmcnt(8)
	s_waitcnt lgkmcnt(0)
	s_barrier
	s_waitcnt lgkmcnt(0)
	v_mfma_f32_16x16x32_bf16 v[62:65], v[140:143], v[200:203], v[62:65]
	v_mfma_f32_16x16x32_bf16 v[62:65], v[148:151], v[204:207], v[62:65]
	v_mfma_f32_16x16x32_bf16 v[54:57], v[156:159], v[200:203], v[54:57]
	v_mfma_f32_16x16x32_bf16 v[54:57], v[180:183], v[204:207], v[54:57]
	v_mfma_f32_16x16x32_bf16 v[46:49], v[140:143], v[208:211], v[46:49]
	v_mfma_f32_16x16x32_bf16 v[46:49], v[148:151], v[212:215], v[46:49]
	v_mfma_f32_16x16x32_bf16 v[38:41], v[156:159], v[208:211], v[38:41]
	v_mfma_f32_16x16x32_bf16 v[38:41], v[180:183], v[212:215], v[38:41]
	v_mfma_f32_16x16x32_bf16 v[30:33], v[140:143], v[216:219], v[30:33]
	v_mfma_f32_16x16x32_bf16 v[30:33], v[148:151], v[220:223], v[30:33]
	v_mfma_f32_16x16x32_bf16 v[22:25], v[156:159], v[216:219], v[22:25]
	v_mfma_f32_16x16x32_bf16 v[22:25], v[180:183], v[220:223], v[22:25]
	v_mfma_f32_16x16x32_bf16 v[14:17], v[140:143], v[224:227], v[14:17]
	v_mfma_f32_16x16x32_bf16 v[14:17], v[148:151], v[228:231], v[14:17]
	v_mfma_f32_16x16x32_bf16 v[6:9], v[156:159], v[224:227], v[6:9]
	v_mfma_f32_16x16x32_bf16 v[6:9], v[180:183], v[228:231], v[6:9]
	v_mfma_f32_16x16x32_bf16 v[58:61], v[184:187], v[200:203], v[58:61]
	v_mfma_f32_16x16x32_bf16 v[58:61], v[188:191], v[204:207], v[58:61]
	v_mfma_f32_16x16x32_bf16 v[50:53], v[192:195], v[200:203], v[50:53]
	v_mfma_f32_16x16x32_bf16 v[50:53], v[196:199], v[204:207], v[50:53]
	v_mfma_f32_16x16x32_bf16 v[42:45], v[184:187], v[208:211], v[42:45]
	v_mfma_f32_16x16x32_bf16 v[42:45], v[188:191], v[212:215], v[42:45]
	v_mfma_f32_16x16x32_bf16 v[34:37], v[192:195], v[208:211], v[34:37]
	v_mfma_f32_16x16x32_bf16 v[34:37], v[196:199], v[212:215], v[34:37]
	v_mfma_f32_16x16x32_bf16 v[26:29], v[184:187], v[216:219], v[26:29]
	v_mfma_f32_16x16x32_bf16 v[26:29], v[188:191], v[220:223], v[26:29]
	v_mfma_f32_16x16x32_bf16 v[18:21], v[192:195], v[216:219], v[18:21]
	v_mfma_f32_16x16x32_bf16 v[18:21], v[196:199], v[220:223], v[18:21]
	v_mfma_f32_16x16x32_bf16 v[10:13], v[184:187], v[224:227], v[10:13]
	v_mfma_f32_16x16x32_bf16 v[10:13], v[188:191], v[228:231], v[10:13]
	v_mfma_f32_16x16x32_bf16 v[2:5], v[192:195], v[224:227], v[2:5]
	v_mfma_f32_16x16x32_bf16 v[2:5], v[196:199], v[228:231], v[2:5]
	s_cmp_lg_u32 s38, 12
	s_cbranch_scc1 .Ltail_bar_1
	s_cmp_eq_u64 s[8:9], 0
	s_cbranch_scc1 .Ltail_skip_1
